# nmajor_S
# baseline (speedup 1.0000x reference)
;     __device__ bool next(int i, Unit& u) const { if (!base.next(i >> 1, u)) return false; u.sub = i & 1; return true; }
; #define PG8_STAGE(bufoff, gbase, voff) do { _Pragma("unroll") for (int _i = 0; _i < 2; ++_i) \
;         __builtin_amdgcn_global_load_lds((const unsigned*)((const char*)(gbase) + (voff)[_i]), (PG8_LAS unsigned*)(lds + (bufoff) + ldsw + _i * 8192), 16, 0, 0); } while (0)
; #define PG8_LDA(dst, b, h) do { _Pragma("unroll") for (int m = 0; m < 4; ++m) _Pragma("unroll") for (int k = 0; k < 2; ++k) dst[m][k] = *(const PG8_LAS bf16x8*)(lds + PG8_SA(b, h) + aoff + m * 2048 + k * 1024); } while (0)
; #define PG8_LDB(dst, b, h) do { _Pragma("unroll") for (int n = 0; n < 2; ++n) _Pragma("unroll") for (int k = 0; k < 2; ++k) dst[n][k] = *(const PG8_LAS bf16x8*)(lds + PG8_SB(b, h) + boff + n * 2048 + k * 1024); } while (0)
; #define PG8_WAIT_V(n) asm volatile("s_waitcnt vmcnt(" #n ")" ::: "memory")
; template <class Epi, class Sched, bool ALIGN_EPI = false, bool SP2 = false, bool DUAL = false>
; __device__ __forceinline__ void gemm_phase(PG8_LAS unsigned char* lds, const Gemm g, const Sched& S, const Epi& E) {
;     ...
;         const bool has_next = S.next(ui + 1, nxt);
;         const char* nA = has_next ? (const char*)((DUAL && nxt.sub) ? g.A2 : g.A) + (size_t)nxt.pm * tstep : cA; const char* nB = has_next ? (const char*)((DUAL && nxt.sub) ? g.Bt2 : g.Bt) + (size_t)nxt.pn * tstep : cB;
;         for (int t = 0; t < nt; t += 2) {
;             const bool last = (t == nt - 2);
;             const char* a1 = cA + (size_t)(t + 1) * kstep;
;             const char* a2 = last ? nA : cA + (size_t)(t + 2) * kstep; const char* b2 = last ? nB : cB + (size_t)(t + 2) * kstep;
;             const char* a3 = a2 + kstep; const char* b3 = b2 + kstep;
;             if (last && has_next) S.a_ready(nxt);
;             if constexpr (SP2) {
;             PG8_LDB(B0, 0, 0); PG8_LDB(B1, 0, 1); PG8_SCHED; PG8_LDA(At, 0, 0); PG8_STAGE(PG8_SA(1, 1), a1 + hstep, voffA);
;             PG8_WAIT_V(8); PG8_WAIT_L(0); PG8_BAR; PG8_MMA(0, 0, At, B0); PG8_MMA(0, 1, At, B1); PG8_BAR; PG8_SCHED;
;             PG8_LDA(At, 0, 1); PG8_STAGE(PG8_SB(0, 0), b2, voffB); PG8_STAGE(PG8_SB(0, 1), b2 + hstep, voffB); PG8_STAGE(PG8_SA(0, 0), a2, voffA);
;             PG8_WAIT_V(8); PG8_WAIT_L(0); PG8_BAR; PG8_MMA(1, 0, At, B0); PG8_MMA(1, 1, At, B1); PG8_BAR; PG8_SCHED;
.LBB0_251:
	s_ashr_i32 s87, s86, 31
	s_lshl_b64 s[16:17], s[86:87], 20
	s_add_u32 s92, s58, s16
	s_addc_u32 s93, s59, s17
	s_and_b64 s[16:17], s[4:5], exec
	s_cselect_b32 s7, s93, s11
	s_cselect_b32 s9, s92, s10
	s_ashr_i32 s1, s0, 31
	s_lshl_b64 s[16:17], s[0:1], 20
	s_add_u32 s88, s90, s16
	s_addc_u32 s89, s91, s17
	s_and_b64 s[16:17], s[4:5], exec
	s_cselect_b32 s1, s89, s15
	s_cselect_b32 s45, s88, s14
	s_add_u32 s10, s10, 0x80080
	s_addc_u32 s11, s11, 0
	s_add_u32 s46, s14, 0x100
	s_addc_u32 s47, s15, 0
	s_mov_b32 s48, -2
	s_add_u32 s14, s10, 0xfff80080
	s_addc_u32 s15, s11, -1
	s_cmp_eq_u32 s48, 28
	s_cselect_b32 s17, s7, s15
	s_cselect_b32 s16, s9, s14
	s_cselect_b32 s15, s1, s47
	s_cselect_b32 s14, s45, s46
	s_waitcnt vmcnt(8)
	s_waitcnt lgkmcnt(0)
	s_setprio 1
	s_barrier
	v_mfma_f32_16x16x32_bf16 v[140:143], v[80:83], v[208:211], 0
	v_mfma_f32_16x16x32_bf16 v[140:143], v[84:87], v[212:215], v[140:143]
	v_mfma_f32_16x16x32_bf16 v[124:127], v[80:83], v[216:219], 0
	v_mfma_f32_16x16x32_bf16 v[124:127], v[84:87], v[220:223], v[124:127]
	v_mfma_f32_16x16x32_bf16 v[108:111], v[80:83], v[232:235], 0
	v_mfma_f32_16x16x32_bf16 v[108:111], v[84:87], v[236:239], v[108:111]
	v_mfma_f32_16x16x32_bf16 v[76:79], v[80:83], v[240:243], 0
	v_mfma_f32_16x16x32_bf16 v[76:79], v[84:87], v[244:247], v[76:79]
	v_mfma_f32_16x16x32_bf16 v[132:135], v[88:91], v[208:211], 0
	v_mfma_f32_16x16x32_bf16 v[132:135], v[92:95], v[212:215], v[132:135]
	v_mfma_f32_16x16x32_bf16 v[120:123], v[88:91], v[216:219], 0
	v_mfma_f32_16x16x32_bf16 v[120:123], v[92:95], v[220:223], v[120:123]
	v_mfma_f32_16x16x32_bf16 v[104:107], v[88:91], v[232:235], 0
	v_mfma_f32_16x16x32_bf16 v[104:107], v[92:95], v[236:239], v[104:107]
	v_mfma_f32_16x16x32_bf16 v[72:75], v[88:91], v[240:243], 0
	v_mfma_f32_16x16x32_bf16 v[72:75], v[92:95], v[244:247], v[72:75]
	s_setprio 0
	s_setprio 1
	v_mfma_f32_16x16x32_bf16 v[136:139], v[144:147], v[208:211], 0
	v_mfma_f32_16x16x32_bf16 v[136:139], v[148:151], v[212:215], v[136:139]
	v_mfma_f32_16x16x32_bf16 v[116:119], v[144:147], v[216:219], 0
	v_mfma_f32_16x16x32_bf16 v[116:119], v[148:151], v[220:223], v[116:119]
	v_mfma_f32_16x16x32_bf16 v[100:103], v[144:147], v[232:235], 0
	v_mfma_f32_16x16x32_bf16 v[100:103], v[148:151], v[236:239], v[100:103]
	v_mfma_f32_16x16x32_bf16 v[68:71], v[144:147], v[240:243], 0
	v_mfma_f32_16x16x32_bf16 v[68:71], v[148:151], v[244:247], v[68:71]
	v_mfma_f32_16x16x32_bf16 v[128:131], v[152:155], v[208:211], 0
	v_mfma_f32_16x16x32_bf16 v[128:131], v[156:159], v[212:215], v[128:131]
	v_mfma_f32_16x16x32_bf16 v[112:115], v[152:155], v[216:219], 0
	v_mfma_f32_16x16x32_bf16 v[112:115], v[156:159], v[220:223], v[112:115]
	v_mfma_f32_16x16x32_bf16 v[96:99], v[152:155], v[232:235], 0
	v_mfma_f32_16x16x32_bf16 v[96:99], v[156:159], v[236:239], v[96:99]
	v_mfma_f32_16x16x32_bf16 v[64:67], v[152:155], v[240:243], 0
	v_mfma_f32_16x16x32_bf16 v[64:67], v[156:159], v[244:247], v[64:67]
	s_barrier
	s_setprio 0
	s_add_i32 m0, s19, 0xc000
	s_nop 0
	global_load_lds_dwordx4 v186, s[10:11]
	s_add_i32 m0, s19, 0xe000
	s_nop 0
	global_load_lds_dwordx4 v188, s[10:11]
	s_add_i32 s49, s31, s18
	v_lshl_add_u64 v[192:193], s[14:15], 0, v[166:167]
	s_mov_b32 m0, s49
	ds_read_b128 v[208:211], v203 offset:16384
	ds_read_b128 v[212:215], v203 offset:17408
	ds_read_b128 v[216:219], v203 offset:18432
	ds_read_b128 v[220:223], v203 offset:19456
	ds_read_b128 v[232:235], v203 offset:20480
	ds_read_b128 v[236:239], v203 offset:21504
	ds_read_b128 v[240:243], v203 offset:22528
	ds_read_b128 v[244:247], v203 offset:23552
	global_load_lds_dwordx4 v[192:193], off
	s_add_i32 m0, s49, 0x2000
	s_add_u32 s50, s14, 0x80000
	v_lshl_add_u64 v[248:249], s[14:15], 0, v[170:171]
	s_addc_u32 s51, s15, 0
	s_add_i32 s49, s34, s18
	global_load_lds_dwordx4 v[248:249], off
	s_mov_b32 m0, s49
	v_lshl_add_u64 v[252:253], s[16:17], 0, v[168:169]
	global_load_lds_dwordx4 v166, s[50:51]
	s_add_i32 m0, s49, 0x2000
	s_nop 0
	global_load_lds_dwordx4 v170, s[50:51]
	v_lshl_add_u64 v[250:251], s[16:17], 0, v[164:165]
	s_mov_b32 m0, s19
	s_nop 0
	global_load_lds_dwordx4 v[250:251], off
	s_mov_b32 m0, s20
	s_nop 0
	global_load_lds_dwordx4 v[252:253], off
	s_waitcnt vmcnt(8)
	s_waitcnt lgkmcnt(0)
	s_setprio 1
	s_barrier
	v_mfma_f32_16x16x32_bf16 v[60:63], v[80:83], v[208:211], 0
	v_mfma_f32_16x16x32_bf16 v[60:63], v[84:87], v[212:215], v[60:63]
	v_mfma_f32_16x16x32_bf16 v[44:47], v[80:83], v[216:219], 0
	v_mfma_f32_16x16x32_bf16 v[44:47], v[84:87], v[220:223], v[44:47]
	v_mfma_f32_16x16x32_bf16 v[28:31], v[80:83], v[232:235], 0
	v_mfma_f32_16x16x32_bf16 v[28:31], v[84:87], v[236:239], v[28:31]
	v_mfma_f32_16x16x32_bf16 v[12:15], v[80:83], v[240:243], 0
	v_mfma_f32_16x16x32_bf16 v[12:15], v[84:87], v[244:247], v[12:15]
	v_mfma_f32_16x16x32_bf16 v[56:59], v[88:91], v[208:211], 0
	v_mfma_f32_16x16x32_bf16 v[56:59], v[92:95], v[212:215], v[56:59]
	v_mfma_f32_16x16x32_bf16 v[40:43], v[88:91], v[216:219], 0
	v_mfma_f32_16x16x32_bf16 v[40:43], v[92:95], v[220:223], v[40:43]
	v_mfma_f32_16x16x32_bf16 v[24:27], v[88:91], v[232:235], 0
	v_mfma_f32_16x16x32_bf16 v[24:27], v[92:95], v[236:239], v[24:27]
	v_mfma_f32_16x16x32_bf16 v[8:11], v[88:91], v[240:243], 0
	v_mfma_f32_16x16x32_bf16 v[8:11], v[92:95], v[244:247], v[8:11]
	s_setprio 0
	s_setprio 1
	v_mfma_f32_16x16x32_bf16 v[52:55], v[144:147], v[208:211], 0
	v_mfma_f32_16x16x32_bf16 v[52:55], v[148:151], v[212:215], v[52:55]
	v_mfma_f32_16x16x32_bf16 v[36:39], v[144:147], v[216:219], 0
	v_mfma_f32_16x16x32_bf16 v[36:39], v[148:151], v[220:223], v[36:39]
	v_mfma_f32_16x16x32_bf16 v[20:23], v[144:147], v[232:235], 0
	v_mfma_f32_16x16x32_bf16 v[20:23], v[148:151], v[236:239], v[20:23]
	v_mfma_f32_16x16x32_bf16 v[4:7], v[144:147], v[240:243], 0
	v_mfma_f32_16x16x32_bf16 v[4:7], v[148:151], v[244:247], v[4:7]
	v_mfma_f32_16x16x32_bf16 v[48:51], v[152:155], v[208:211], 0
	v_mfma_f32_16x16x32_bf16 v[48:51], v[156:159], v[212:215], v[48:51]
	v_mfma_f32_16x16x32_bf16 v[32:35], v[152:155], v[216:219], 0
	v_mfma_f32_16x16x32_bf16 v[32:35], v[156:159], v[220:223], v[32:35]
	v_mfma_f32_16x16x32_bf16 v[16:19], v[152:155], v[232:235], 0
	v_mfma_f32_16x16x32_bf16 v[16:19], v[156:159], v[236:239], v[16:19]
	v_mfma_f32_16x16x32_bf16 v[0:3], v[152:155], v[240:243], 0
	v_mfma_f32_16x16x32_bf16 v[0:3], v[156:159], v[244:247], v[0:3]
	s_barrier
; #define PG8_STAGE(bufoff, gbase, voff) do { _Pragma("unroll") for (int _i = 0; _i < 2; ++_i) \
;         __builtin_amdgcn_global_load_lds((const unsigned*)((const char*)(gbase) + (voff)[_i]), (PG8_LAS unsigned*)(lds + (bufoff) + ldsw + _i * 8192), 16, 0, 0); } while (0)
; #define PG8_LDA(dst, b, h) do { _Pragma("unroll") for (int m = 0; m < 4; ++m) _Pragma("unroll") for (int k = 0; k < 2; ++k) dst[m][k] = *(const PG8_LAS bf16x8*)(lds + PG8_SA(b, h) + aoff + m * 2048 + k * 1024); } while (0)
; #define PG8_LDB(dst, b, h) do { _Pragma("unroll") for (int n = 0; n < 2; ++n) _Pragma("unroll") for (int k = 0; k < 2; ++k) dst[n][k] = *(const PG8_LAS bf16x8*)(lds + PG8_SB(b, h) + boff + n * 2048 + k * 1024); } while (0)
; #define PG8_MMA(ai, bj, At, Bt) do { __builtin_amdgcn_s_setprio(1); _Pragma("unroll") for (int m = 0; m < 4; ++m) _Pragma("unroll") for (int n = 0; n < 2; ++n) _Pragma("unroll") for (int k = 0; k < 2; ++k) \
;         acc[ai][bj][m][n] = __builtin_amdgcn_mfma_f32_16x16x32_bf16(Bt[n][k], At[m][k], acc[ai][bj][m][n], 0, 0, 0); __builtin_amdgcn_s_setprio(0); } while (0)
; #define PG8_WAIT_V(n) asm volatile("s_waitcnt vmcnt(" #n ")" ::: "memory")
; #define PG8_WAIT_L(n) asm volatile("s_waitcnt lgkmcnt(" #n ")" ::: "memory")
; #define PG8_BAR __builtin_amdgcn_s_barrier()
; #define PG8_SCHED __builtin_amdgcn_sched_barrier(0)
; template <class Epi, class Sched, bool ALIGN_EPI = false, bool SP2 = false, bool DUAL = false>
; __device__ __forceinline__ void gemm_phase(PG8_LAS unsigned char* lds, const Gemm g, const Sched& S, const Epi& E) {
;     ...
;             PG8_LDB(B0, 1, 0); PG8_LDB(B1, 1, 1); PG8_SCHED; PG8_LDA(At, 1, 0); PG8_STAGE(PG8_SA(0, 1), a2 + hstep, voffA);
;             PG8_WAIT_V(8); PG8_WAIT_L(0); PG8_BAR; PG8_MMA(0, 0, At, B0); PG8_MMA(0, 1, At, B1); PG8_BAR; PG8_SCHED;
;             PG8_LDA(At, 1, 1); PG8_STAGE(PG8_SB(1, 0), b3, voffB); PG8_STAGE(PG8_SB(1, 1), b3 + hstep, voffB); PG8_STAGE(PG8_SA(1, 0), a3, voffA);
;             PG8_WAIT_V(8); PG8_WAIT_L(0); PG8_BAR; PG8_MMA(1, 0, At, B0); PG8_MMA(1, 1, At, B1); PG8_BAR; PG8_SCHED;
	s_setprio 0
	s_add_i32 s49, 0, 0x18000
	s_add_i32 s50, 0, 0x1c000
	v_add_u32_e32 v92, s49, v196
	v_add_u32_e32 v156, s50, v196
	ds_read_b128 v[80:83], v92
	ds_read_b128 v[84:87], v92 offset:1024
	ds_read_b128 v[88:91], v92 offset:2048
	ds_read_b128 v[92:95], v92 offset:3072
	ds_read_b128 v[144:147], v156
	ds_read_b128 v[148:151], v156 offset:1024
	ds_read_b128 v[152:155], v156 offset:2048
	ds_read_b128 v[156:159], v156 offset:3072
	s_add_u32 s16, s16, 0x80000
	s_addc_u32 s17, s17, 0
	s_mov_b32 m0, s21
	ds_read_b128 v[208:211], v203 offset:32768
	ds_read_b128 v[212:215], v203 offset:33792
	ds_read_b128 v[216:219], v203 offset:34816
	ds_read_b128 v[220:223], v203 offset:35840
	ds_read_b128 v[232:235], v203 offset:36864
	ds_read_b128 v[236:239], v203 offset:37888
	ds_read_b128 v[240:243], v203 offset:38912
	ds_read_b128 v[244:247], v203 offset:39936
	global_load_lds_dwordx4 v164, s[16:17]
	s_mov_b32 m0, s22
	s_nop 0
	global_load_lds_dwordx4 v168, s[16:17]
	s_waitcnt vmcnt(8)
	s_waitcnt lgkmcnt(0)
	s_setprio 1
	s_barrier
	v_mfma_f32_16x16x32_bf16 v[140:143], v[80:83], v[208:211], v[140:143]
	v_mfma_f32_16x16x32_bf16 v[140:143], v[84:87], v[212:215], v[140:143]
	v_mfma_f32_16x16x32_bf16 v[124:127], v[80:83], v[216:219], v[124:127]
	v_mfma_f32_16x16x32_bf16 v[124:127], v[84:87], v[220:223], v[124:127]
	v_mfma_f32_16x16x32_bf16 v[108:111], v[80:83], v[232:235], v[108:111]
	v_mfma_f32_16x16x32_bf16 v[108:111], v[84:87], v[236:239], v[108:111]
	v_mfma_f32_16x16x32_bf16 v[76:79], v[80:83], v[240:243], v[76:79]
	v_mfma_f32_16x16x32_bf16 v[76:79], v[84:87], v[244:247], v[76:79]
	v_mfma_f32_16x16x32_bf16 v[132:135], v[88:91], v[208:211], v[132:135]
	v_mfma_f32_16x16x32_bf16 v[132:135], v[92:95], v[212:215], v[132:135]
	v_mfma_f32_16x16x32_bf16 v[120:123], v[88:91], v[216:219], v[120:123]
	v_mfma_f32_16x16x32_bf16 v[120:123], v[92:95], v[220:223], v[120:123]
	v_mfma_f32_16x16x32_bf16 v[104:107], v[88:91], v[232:235], v[104:107]
	v_mfma_f32_16x16x32_bf16 v[104:107], v[92:95], v[236:239], v[104:107]
	v_mfma_f32_16x16x32_bf16 v[72:75], v[88:91], v[240:243], v[72:75]
	v_mfma_f32_16x16x32_bf16 v[72:75], v[92:95], v[244:247], v[72:75]
	s_setprio 0
	s_setprio 1
	v_mfma_f32_16x16x32_bf16 v[136:139], v[144:147], v[208:211], v[136:139]
	v_mfma_f32_16x16x32_bf16 v[136:139], v[148:151], v[212:215], v[136:139]
	v_mfma_f32_16x16x32_bf16 v[116:119], v[144:147], v[216:219], v[116:119]
	v_mfma_f32_16x16x32_bf16 v[116:119], v[148:151], v[220:223], v[116:119]
	v_mfma_f32_16x16x32_bf16 v[100:103], v[144:147], v[232:235], v[100:103]
	v_mfma_f32_16x16x32_bf16 v[100:103], v[148:151], v[236:239], v[100:103]
	v_mfma_f32_16x16x32_bf16 v[68:71], v[144:147], v[240:243], v[68:71]
	v_mfma_f32_16x16x32_bf16 v[68:71], v[148:151], v[244:247], v[68:71]
	v_mfma_f32_16x16x32_bf16 v[128:131], v[152:155], v[208:211], v[128:131]
	v_mfma_f32_16x16x32_bf16 v[128:131], v[156:159], v[212:215], v[128:131]
	v_mfma_f32_16x16x32_bf16 v[112:115], v[152:155], v[216:219], v[112:115]
	v_mfma_f32_16x16x32_bf16 v[112:115], v[156:159], v[220:223], v[112:115]
	v_mfma_f32_16x16x32_bf16 v[96:99], v[152:155], v[232:235], v[96:99]
	v_mfma_f32_16x16x32_bf16 v[96:99], v[156:159], v[236:239], v[96:99]
	v_mfma_f32_16x16x32_bf16 v[64:67], v[152:155], v[240:243], v[64:67]
	v_mfma_f32_16x16x32_bf16 v[64:67], v[156:159], v[244:247], v[64:67]
	s_barrier
	s_setprio 0
	s_add_i32 s16, s49, s18
	v_lshl_add_u64 v[192:193], v[192:193], 0, s[76:77]
	s_mov_b32 m0, s16
	ds_read_b128 v[208:211], v203 offset:49152
	ds_read_b128 v[212:215], v203 offset:50176
	ds_read_b128 v[216:219], v203 offset:51200
	ds_read_b128 v[220:223], v203 offset:52224
	ds_read_b128 v[232:235], v203 offset:53248
	ds_read_b128 v[236:239], v203 offset:54272
	ds_read_b128 v[240:243], v203 offset:55296
	ds_read_b128 v[244:247], v203 offset:56320
	global_load_lds_dwordx4 v[192:193], off
	s_add_i32 m0, s16, 0x2000
	s_add_u32 s14, s14, 0x80080
	v_lshl_add_u64 v[192:193], v[248:249], 0, s[76:77]
	s_addc_u32 s15, s15, 0
	s_add_i32 s16, s50, s18
	global_load_lds_dwordx4 v[192:193], off
	s_mov_b32 m0, s16
	s_nop 0
	global_load_lds_dwordx4 v166, s[14:15]
	s_add_i32 m0, s16, 0x2000
	s_nop 0
	global_load_lds_dwordx4 v170, s[14:15]
	v_lshl_add_u64 v[192:193], v[250:251], 0, s[76:77]
	s_mov_b32 m0, s27
	s_nop 0
	global_load_lds_dwordx4 v[192:193], off
	v_lshl_add_u64 v[192:193], v[252:253], 0, s[76:77]
	s_mov_b32 m0, s28
	s_nop 0
	global_load_lds_dwordx4 v[192:193], off
	s_waitcnt vmcnt(8)
	s_waitcnt lgkmcnt(0)
	s_setprio 1
	s_barrier
	v_mfma_f32_16x16x32_bf16 v[60:63], v[80:83], v[208:211], v[60:63]
	v_mfma_f32_16x16x32_bf16 v[60:63], v[84:87], v[212:215], v[60:63]
	v_mfma_f32_16x16x32_bf16 v[44:47], v[80:83], v[216:219], v[44:47]
	v_mfma_f32_16x16x32_bf16 v[44:47], v[84:87], v[220:223], v[44:47]
	v_mfma_f32_16x16x32_bf16 v[28:31], v[80:83], v[232:235], v[28:31]
	v_mfma_f32_16x16x32_bf16 v[28:31], v[84:87], v[236:239], v[28:31]
	v_mfma_f32_16x16x32_bf16 v[12:15], v[80:83], v[240:243], v[12:15]
	v_mfma_f32_16x16x32_bf16 v[12:15], v[84:87], v[244:247], v[12:15]
	v_mfma_f32_16x16x32_bf16 v[56:59], v[88:91], v[208:211], v[56:59]
	v_mfma_f32_16x16x32_bf16 v[56:59], v[92:95], v[212:215], v[56:59]
	v_mfma_f32_16x16x32_bf16 v[40:43], v[88:91], v[216:219], v[40:43]
	v_mfma_f32_16x16x32_bf16 v[40:43], v[92:95], v[220:223], v[40:43]
	v_mfma_f32_16x16x32_bf16 v[24:27], v[88:91], v[232:235], v[24:27]
	v_mfma_f32_16x16x32_bf16 v[24:27], v[92:95], v[236:239], v[24:27]
	v_mfma_f32_16x16x32_bf16 v[8:11], v[88:91], v[240:243], v[8:11]
	v_mfma_f32_16x16x32_bf16 v[8:11], v[92:95], v[244:247], v[8:11]
	s_setprio 0
	s_setprio 1
	v_mfma_f32_16x16x32_bf16 v[52:55], v[144:147], v[208:211], v[52:55]
	v_mfma_f32_16x16x32_bf16 v[52:55], v[148:151], v[212:215], v[52:55]
	v_mfma_f32_16x16x32_bf16 v[36:39], v[144:147], v[216:219], v[36:39]
	v_mfma_f32_16x16x32_bf16 v[36:39], v[148:151], v[220:223], v[36:39]
	v_mfma_f32_16x16x32_bf16 v[20:23], v[144:147], v[232:235], v[20:23]
	v_mfma_f32_16x16x32_bf16 v[20:23], v[148:151], v[236:239], v[20:23]
	v_mfma_f32_16x16x32_bf16 v[4:7], v[144:147], v[240:243], v[4:7]
	v_mfma_f32_16x16x32_bf16 v[4:7], v[148:151], v[244:247], v[4:7]
	v_mfma_f32_16x16x32_bf16 v[48:51], v[152:155], v[208:211], v[48:51]
	v_mfma_f32_16x16x32_bf16 v[48:51], v[156:159], v[212:215], v[48:51]
	v_mfma_f32_16x16x32_bf16 v[32:35], v[152:155], v[216:219], v[32:35]
	v_mfma_f32_16x16x32_bf16 v[32:35], v[156:159], v[220:223], v[32:35]
	v_mfma_f32_16x16x32_bf16 v[16:19], v[152:155], v[232:235], v[16:19]
	v_mfma_f32_16x16x32_bf16 v[16:19], v[156:159], v[236:239], v[16:19]
	v_mfma_f32_16x16x32_bf16 v[0:3], v[152:155], v[240:243], v[0:3]
	v_mfma_f32_16x16x32_bf16 v[0:3], v[156:159], v[244:247], v[0:3]
	s_barrier
	s_setprio 0
	s_add_i32 s48, s48, 2
	s_add_u32 s10, s10, 0x100
	s_addc_u32 s11, s11, 0
	s_add_u32 s46, s46, 0x100
	s_addc_u32 s47, s47, 0
; #define PG8_STAGE(bufoff, gbase, voff) do { _Pragma("unroll") for (int _i = 0; _i < 2; ++_i) \
;         __builtin_amdgcn_global_load_lds((const unsigned*)((const char*)(gbase) + (voff)[_i]), (PG8_LAS unsigned*)(lds + (bufoff) + ldsw + _i * 8192), 16, 0, 0); } while (0)
; #define PG8_LDA(dst, b, h) do { _Pragma("unroll") for (int m = 0; m < 4; ++m) _Pragma("unroll") for (int k = 0; k < 2; ++k) dst[m][k] = *(const PG8_LAS bf16x8*)(lds + PG8_SA(b, h) + aoff + m * 2048 + k * 1024); } while (0)
; #define PG8_LDB(dst, b, h) do { _Pragma("unroll") for (int n = 0; n < 2; ++n) _Pragma("unroll") for (int k = 0; k < 2; ++k) dst[n][k] = *(const PG8_LAS bf16x8*)(lds + PG8_SB(b, h) + boff + n * 2048 + k * 1024); } while (0)
; #define PG8_MMA(ai, bj, At, Bt) do { __builtin_amdgcn_s_setprio(1); _Pragma("unroll") for (int m = 0; m < 4; ++m) _Pragma("unroll") for (int n = 0; n < 2; ++n) _Pragma("unroll") for (int k = 0; k < 2; ++k) \
;         acc[ai][bj][m][n] = __builtin_amdgcn_mfma_f32_16x16x32_bf16(Bt[n][k], At[m][k], acc[ai][bj][m][n], 0, 0, 0); __builtin_amdgcn_s_setprio(0); } while (0)
; #define PG8_WAIT_V(n) asm volatile("s_waitcnt vmcnt(" #n ")" ::: "memory")
; #define PG8_WAIT_L(n) asm volatile("s_waitcnt lgkmcnt(" #n ")" ::: "memory")
; #define PG8_BAR __builtin_amdgcn_s_barrier()
; #define PG8_SCHED __builtin_amdgcn_sched_barrier(0)
; template <class Epi, class Sched, bool ALIGN_EPI = false, bool SP2 = false, bool DUAL = false>
; __device__ __forceinline__ void gemm_phase(PG8_LAS unsigned char* lds, const Gemm g, const Sched& S, const Epi& E) {
;     ...
;             const char* a2 = last ? nA : cA + (size_t)(t + 2) * kstep; const char* b2 = last ? nB : cB + (size_t)(t + 2) * kstep;
;             const char* a3 = a2 + kstep; const char* b3 = b2 + kstep;
;             if (last && has_next) S.a_ready(nxt);
;             if constexpr (SP2) {
;             PG8_LDB(B0, 0, 0); PG8_LDB(B1, 0, 1); PG8_SCHED; PG8_LDA(At, 0, 0); PG8_STAGE(PG8_SA(1, 1), a1 + hstep, voffA);
;             PG8_WAIT_V(8); PG8_WAIT_L(0); PG8_BAR; PG8_MMA(0, 0, At, B0); PG8_MMA(0, 1, At, B1); PG8_BAR; PG8_SCHED;
;             PG8_LDA(At, 0, 1); PG8_STAGE(PG8_SB(0, 0), b2, voffB); PG8_STAGE(PG8_SB(0, 1), b2 + hstep, voffB); PG8_STAGE(PG8_SA(0, 0), a2, voffA);
;             PG8_WAIT_V(8); PG8_WAIT_L(0); PG8_BAR; PG8_MMA(1, 0, At, B0); PG8_MMA(1, 1, At, B1); PG8_BAR; PG8_SCHED;
.LBB0_252:
	ds_read_b128 v[80:83], v199
	ds_read_b128 v[84:87], v199 offset:1024
	ds_read_b128 v[88:91], v199 offset:2048
	ds_read_b128 v[92:95], v199 offset:3072
	ds_read_b128 v[144:147], v202
	ds_read_b128 v[148:151], v202 offset:1024
	ds_read_b128 v[152:155], v202 offset:2048
	ds_read_b128 v[156:159], v202 offset:3072
	s_add_u32 s14, s10, 0xfff80080
	s_addc_u32 s15, s11, -1
	s_cmp_eq_u32 s48, 28
	s_cselect_b32 s17, s7, s15
	s_cselect_b32 s16, s9, s14
	s_cselect_b32 s15, s1, s47
	s_cselect_b32 s14, s45, s46
	s_add_i32 m0, s19, 0xc000
	ds_read_b128 v[208:211], v203
	ds_read_b128 v[212:215], v203 offset:1024
	ds_read_b128 v[216:219], v203 offset:2048
	ds_read_b128 v[220:223], v203 offset:3072
	ds_read_b128 v[232:235], v203 offset:4096
	ds_read_b128 v[236:239], v203 offset:5120
	ds_read_b128 v[240:243], v203 offset:6144
	ds_read_b128 v[244:247], v203 offset:7168
	global_load_lds_dwordx4 v186, s[10:11]
	s_add_i32 m0, s19, 0xe000
	s_nop 0
	global_load_lds_dwordx4 v188, s[10:11]
	s_waitcnt vmcnt(8)
	s_waitcnt lgkmcnt(0)
	s_setprio 1
	s_barrier
	v_mfma_f32_16x16x32_bf16 v[140:143], v[80:83], v[208:211], v[140:143]
	v_mfma_f32_16x16x32_bf16 v[140:143], v[84:87], v[212:215], v[140:143]
	v_mfma_f32_16x16x32_bf16 v[124:127], v[80:83], v[216:219], v[124:127]
	v_mfma_f32_16x16x32_bf16 v[124:127], v[84:87], v[220:223], v[124:127]
	v_mfma_f32_16x16x32_bf16 v[108:111], v[80:83], v[232:235], v[108:111]
	v_mfma_f32_16x16x32_bf16 v[108:111], v[84:87], v[236:239], v[108:111]
	v_mfma_f32_16x16x32_bf16 v[76:79], v[80:83], v[240:243], v[76:79]
	v_mfma_f32_16x16x32_bf16 v[76:79], v[84:87], v[244:247], v[76:79]
	v_mfma_f32_16x16x32_bf16 v[132:135], v[88:91], v[208:211], v[132:135]
	v_mfma_f32_16x16x32_bf16 v[132:135], v[92:95], v[212:215], v[132:135]
	v_mfma_f32_16x16x32_bf16 v[120:123], v[88:91], v[216:219], v[120:123]
	v_mfma_f32_16x16x32_bf16 v[120:123], v[92:95], v[220:223], v[120:123]
	v_mfma_f32_16x16x32_bf16 v[104:107], v[88:91], v[232:235], v[104:107]
	v_mfma_f32_16x16x32_bf16 v[104:107], v[92:95], v[236:239], v[104:107]
	v_mfma_f32_16x16x32_bf16 v[72:75], v[88:91], v[240:243], v[72:75]
	v_mfma_f32_16x16x32_bf16 v[72:75], v[92:95], v[244:247], v[72:75]
	s_setprio 0
	s_setprio 1
	v_mfma_f32_16x16x32_bf16 v[136:139], v[144:147], v[208:211], v[136:139]
	v_mfma_f32_16x16x32_bf16 v[136:139], v[148:151], v[212:215], v[136:139]
	v_mfma_f32_16x16x32_bf16 v[116:119], v[144:147], v[216:219], v[116:119]
	v_mfma_f32_16x16x32_bf16 v[116:119], v[148:151], v[220:223], v[116:119]
	v_mfma_f32_16x16x32_bf16 v[100:103], v[144:147], v[232:235], v[100:103]
	v_mfma_f32_16x16x32_bf16 v[100:103], v[148:151], v[236:239], v[100:103]
	v_mfma_f32_16x16x32_bf16 v[68:71], v[144:147], v[240:243], v[68:71]
	v_mfma_f32_16x16x32_bf16 v[68:71], v[148:151], v[244:247], v[68:71]
	v_mfma_f32_16x16x32_bf16 v[128:131], v[152:155], v[208:211], v[128:131]
	v_mfma_f32_16x16x32_bf16 v[128:131], v[156:159], v[212:215], v[128:131]
	v_mfma_f32_16x16x32_bf16 v[112:115], v[152:155], v[216:219], v[112:115]
	v_mfma_f32_16x16x32_bf16 v[112:115], v[156:159], v[220:223], v[112:115]
	v_mfma_f32_16x16x32_bf16 v[96:99], v[152:155], v[232:235], v[96:99]
	v_mfma_f32_16x16x32_bf16 v[96:99], v[156:159], v[236:239], v[96:99]
	v_mfma_f32_16x16x32_bf16 v[64:67], v[152:155], v[240:243], v[64:67]
	v_mfma_f32_16x16x32_bf16 v[64:67], v[156:159], v[244:247], v[64:67]
	s_barrier
	s_setprio 0
	s_add_i32 s49, s31, s18
	v_lshl_add_u64 v[192:193], s[14:15], 0, v[166:167]
	s_mov_b32 m0, s49
	ds_read_b128 v[208:211], v203 offset:16384
	ds_read_b128 v[212:215], v203 offset:17408
	ds_read_b128 v[216:219], v203 offset:18432
	ds_read_b128 v[220:223], v203 offset:19456
	ds_read_b128 v[232:235], v203 offset:20480
	ds_read_b128 v[236:239], v203 offset:21504
	ds_read_b128 v[240:243], v203 offset:22528
	ds_read_b128 v[244:247], v203 offset:23552
	global_load_lds_dwordx4 v[192:193], off
	s_add_i32 m0, s49, 0x2000
	s_add_u32 s50, s14, 0x80000
	v_lshl_add_u64 v[248:249], s[14:15], 0, v[170:171]
	s_addc_u32 s51, s15, 0
	s_add_i32 s49, s34, s18
	global_load_lds_dwordx4 v[248:249], off
	s_mov_b32 m0, s49
	v_lshl_add_u64 v[252:253], s[16:17], 0, v[168:169]
	global_load_lds_dwordx4 v166, s[50:51]
	s_add_i32 m0, s49, 0x2000
	s_nop 0
	global_load_lds_dwordx4 v170, s[50:51]
	v_lshl_add_u64 v[250:251], s[16:17], 0, v[164:165]
	s_mov_b32 m0, s19
	s_nop 0
	global_load_lds_dwordx4 v[250:251], off
	s_mov_b32 m0, s20
	s_nop 0
	global_load_lds_dwordx4 v[252:253], off
	s_waitcnt vmcnt(8)
	s_waitcnt lgkmcnt(0)
	s_setprio 1
	s_barrier
	v_mfma_f32_16x16x32_bf16 v[60:63], v[80:83], v[208:211], v[60:63]
	v_mfma_f32_16x16x32_bf16 v[60:63], v[84:87], v[212:215], v[60:63]
	v_mfma_f32_16x16x32_bf16 v[44:47], v[80:83], v[216:219], v[44:47]
	v_mfma_f32_16x16x32_bf16 v[44:47], v[84:87], v[220:223], v[44:47]
	v_mfma_f32_16x16x32_bf16 v[28:31], v[80:83], v[232:235], v[28:31]
	v_mfma_f32_16x16x32_bf16 v[28:31], v[84:87], v[236:239], v[28:31]
	v_mfma_f32_16x16x32_bf16 v[12:15], v[80:83], v[240:243], v[12:15]
	v_mfma_f32_16x16x32_bf16 v[12:15], v[84:87], v[244:247], v[12:15]
	v_mfma_f32_16x16x32_bf16 v[56:59], v[88:91], v[208:211], v[56:59]
	v_mfma_f32_16x16x32_bf16 v[56:59], v[92:95], v[212:215], v[56:59]
	v_mfma_f32_16x16x32_bf16 v[40:43], v[88:91], v[216:219], v[40:43]
	v_mfma_f32_16x16x32_bf16 v[40:43], v[92:95], v[220:223], v[40:43]
	v_mfma_f32_16x16x32_bf16 v[24:27], v[88:91], v[232:235], v[24:27]
	v_mfma_f32_16x16x32_bf16 v[24:27], v[92:95], v[236:239], v[24:27]
	v_mfma_f32_16x16x32_bf16 v[8:11], v[88:91], v[240:243], v[8:11]
	v_mfma_f32_16x16x32_bf16 v[8:11], v[92:95], v[244:247], v[8:11]
	s_setprio 0
	s_setprio 1
	v_mfma_f32_16x16x32_bf16 v[52:55], v[144:147], v[208:211], v[52:55]
	v_mfma_f32_16x16x32_bf16 v[52:55], v[148:151], v[212:215], v[52:55]
	v_mfma_f32_16x16x32_bf16 v[36:39], v[144:147], v[216:219], v[36:39]
	v_mfma_f32_16x16x32_bf16 v[36:39], v[148:151], v[220:223], v[36:39]
	v_mfma_f32_16x16x32_bf16 v[20:23], v[144:147], v[232:235], v[20:23]
	v_mfma_f32_16x16x32_bf16 v[20:23], v[148:151], v[236:239], v[20:23]
	v_mfma_f32_16x16x32_bf16 v[4:7], v[144:147], v[240:243], v[4:7]
	v_mfma_f32_16x16x32_bf16 v[4:7], v[148:151], v[244:247], v[4:7]
	v_mfma_f32_16x16x32_bf16 v[48:51], v[152:155], v[208:211], v[48:51]
	v_mfma_f32_16x16x32_bf16 v[48:51], v[156:159], v[212:215], v[48:51]
	v_mfma_f32_16x16x32_bf16 v[32:35], v[152:155], v[216:219], v[32:35]
	v_mfma_f32_16x16x32_bf16 v[32:35], v[156:159], v[220:223], v[32:35]
	v_mfma_f32_16x16x32_bf16 v[16:19], v[152:155], v[232:235], v[16:19]
	v_mfma_f32_16x16x32_bf16 v[16:19], v[156:159], v[236:239], v[16:19]
	v_mfma_f32_16x16x32_bf16 v[0:3], v[152:155], v[240:243], v[0:3]
	v_mfma_f32_16x16x32_bf16 v[0:3], v[156:159], v[244:247], v[0:3]
	s_barrier
; #define PG8_STAGE(bufoff, gbase, voff) do { _Pragma("unroll") for (int _i = 0; _i < 2; ++_i) \
;         __builtin_amdgcn_global_load_lds((const unsigned*)((const char*)(gbase) + (voff)[_i]), (PG8_LAS unsigned*)(lds + (bufoff) + ldsw + _i * 8192), 16, 0, 0); } while (0)
; #define PG8_LDA(dst, b, h) do { _Pragma("unroll") for (int m = 0; m < 4; ++m) _Pragma("unroll") for (int k = 0; k < 2; ++k) dst[m][k] = *(const PG8_LAS bf16x8*)(lds + PG8_SA(b, h) + aoff + m * 2048 + k * 1024); } while (0)
; #define PG8_LDB(dst, b, h) do { _Pragma("unroll") for (int n = 0; n < 2; ++n) _Pragma("unroll") for (int k = 0; k < 2; ++k) dst[n][k] = *(const PG8_LAS bf16x8*)(lds + PG8_SB(b, h) + boff + n * 2048 + k * 1024); } while (0)
; #define PG8_MMA(ai, bj, At, Bt) do { __builtin_amdgcn_s_setprio(1); _Pragma("unroll") for (int m = 0; m < 4; ++m) _Pragma("unroll") for (int n = 0; n < 2; ++n) _Pragma("unroll") for (int k = 0; k < 2; ++k) \
;         acc[ai][bj][m][n] = __builtin_amdgcn_mfma_f32_16x16x32_bf16(Bt[n][k], At[m][k], acc[ai][bj][m][n], 0, 0, 0); __builtin_amdgcn_s_setprio(0); } while (0)
; #define PG8_WAIT_V(n) asm volatile("s_waitcnt vmcnt(" #n ")" ::: "memory")
; #define PG8_WAIT_L(n) asm volatile("s_waitcnt lgkmcnt(" #n ")" ::: "memory")
; #define PG8_BAR __builtin_amdgcn_s_barrier()
; #define PG8_SCHED __builtin_amdgcn_sched_barrier(0)
; template <class Epi, class Sched, bool ALIGN_EPI = false, bool SP2 = false, bool DUAL = false>
; __device__ __forceinline__ void gemm_phase(PG8_LAS unsigned char* lds, const Gemm g, const Sched& S, const Epi& E) {
;     ...
;             PG8_LDB(B0, 1, 0); PG8_LDB(B1, 1, 1); PG8_SCHED; PG8_LDA(At, 1, 0); PG8_STAGE(PG8_SA(0, 1), a2 + hstep, voffA);
;             PG8_WAIT_V(8); PG8_WAIT_L(0); PG8_BAR; PG8_MMA(0, 0, At, B0); PG8_MMA(0, 1, At, B1); PG8_BAR; PG8_SCHED;
;             PG8_LDA(At, 1, 1); PG8_STAGE(PG8_SB(1, 0), b3, voffB); PG8_STAGE(PG8_SB(1, 1), b3 + hstep, voffB); PG8_STAGE(PG8_SA(1, 0), a3, voffA);
;             PG8_WAIT_V(8); PG8_WAIT_L(0); PG8_BAR; PG8_MMA(1, 0, At, B0); PG8_MMA(1, 1, At, B1); PG8_BAR; PG8_SCHED;
	s_setprio 0
	s_add_i32 s49, 0, 0x18000
	s_add_i32 s50, 0, 0x1c000
	v_add_u32_e32 v92, s49, v196
	v_add_u32_e32 v156, s50, v196
	ds_read_b128 v[80:83], v92
	ds_read_b128 v[84:87], v92 offset:1024
	ds_read_b128 v[88:91], v92 offset:2048
	ds_read_b128 v[92:95], v92 offset:3072
	ds_read_b128 v[144:147], v156
	ds_read_b128 v[148:151], v156 offset:1024
	ds_read_b128 v[152:155], v156 offset:2048
	ds_read_b128 v[156:159], v156 offset:3072
	s_add_u32 s16, s16, 0x80000
	s_addc_u32 s17, s17, 0
	s_mov_b32 m0, s21
	ds_read_b128 v[208:211], v203 offset:32768
	ds_read_b128 v[212:215], v203 offset:33792
	ds_read_b128 v[216:219], v203 offset:34816
	ds_read_b128 v[220:223], v203 offset:35840
	ds_read_b128 v[232:235], v203 offset:36864
	ds_read_b128 v[236:239], v203 offset:37888
	ds_read_b128 v[240:243], v203 offset:38912
	ds_read_b128 v[244:247], v203 offset:39936
	global_load_lds_dwordx4 v164, s[16:17]
	s_mov_b32 m0, s22
	s_nop 0
	global_load_lds_dwordx4 v168, s[16:17]
	s_waitcnt vmcnt(8)
	s_waitcnt lgkmcnt(0)
	s_setprio 1
	s_barrier
	v_mfma_f32_16x16x32_bf16 v[140:143], v[80:83], v[208:211], v[140:143]
	v_mfma_f32_16x16x32_bf16 v[140:143], v[84:87], v[212:215], v[140:143]
	v_mfma_f32_16x16x32_bf16 v[124:127], v[80:83], v[216:219], v[124:127]
	v_mfma_f32_16x16x32_bf16 v[124:127], v[84:87], v[220:223], v[124:127]
	v_mfma_f32_16x16x32_bf16 v[108:111], v[80:83], v[232:235], v[108:111]
	v_mfma_f32_16x16x32_bf16 v[108:111], v[84:87], v[236:239], v[108:111]
	v_mfma_f32_16x16x32_bf16 v[76:79], v[80:83], v[240:243], v[76:79]
	v_mfma_f32_16x16x32_bf16 v[76:79], v[84:87], v[244:247], v[76:79]
	v_mfma_f32_16x16x32_bf16 v[132:135], v[88:91], v[208:211], v[132:135]
	v_mfma_f32_16x16x32_bf16 v[132:135], v[92:95], v[212:215], v[132:135]
	v_mfma_f32_16x16x32_bf16 v[120:123], v[88:91], v[216:219], v[120:123]
	v_mfma_f32_16x16x32_bf16 v[120:123], v[92:95], v[220:223], v[120:123]
	v_mfma_f32_16x16x32_bf16 v[104:107], v[88:91], v[232:235], v[104:107]
	v_mfma_f32_16x16x32_bf16 v[104:107], v[92:95], v[236:239], v[104:107]
	v_mfma_f32_16x16x32_bf16 v[72:75], v[88:91], v[240:243], v[72:75]
	v_mfma_f32_16x16x32_bf16 v[72:75], v[92:95], v[244:247], v[72:75]
	s_setprio 0
	s_setprio 1
	v_mfma_f32_16x16x32_bf16 v[136:139], v[144:147], v[208:211], v[136:139]
	v_mfma_f32_16x16x32_bf16 v[136:139], v[148:151], v[212:215], v[136:139]
	v_mfma_f32_16x16x32_bf16 v[116:119], v[144:147], v[216:219], v[116:119]
	v_mfma_f32_16x16x32_bf16 v[116:119], v[148:151], v[220:223], v[116:119]
	v_mfma_f32_16x16x32_bf16 v[100:103], v[144:147], v[232:235], v[100:103]
	v_mfma_f32_16x16x32_bf16 v[100:103], v[148:151], v[236:239], v[100:103]
	v_mfma_f32_16x16x32_bf16 v[68:71], v[144:147], v[240:243], v[68:71]
	v_mfma_f32_16x16x32_bf16 v[68:71], v[148:151], v[244:247], v[68:71]
	v_mfma_f32_16x16x32_bf16 v[128:131], v[152:155], v[208:211], v[128:131]
	v_mfma_f32_16x16x32_bf16 v[128:131], v[156:159], v[212:215], v[128:131]
	v_mfma_f32_16x16x32_bf16 v[112:115], v[152:155], v[216:219], v[112:115]
	v_mfma_f32_16x16x32_bf16 v[112:115], v[156:159], v[220:223], v[112:115]
	v_mfma_f32_16x16x32_bf16 v[96:99], v[152:155], v[232:235], v[96:99]
	v_mfma_f32_16x16x32_bf16 v[96:99], v[156:159], v[236:239], v[96:99]
	v_mfma_f32_16x16x32_bf16 v[64:67], v[152:155], v[240:243], v[64:67]
	v_mfma_f32_16x16x32_bf16 v[64:67], v[156:159], v[244:247], v[64:67]
	s_barrier
	s_setprio 0
	s_add_i32 s16, s49, s18
	v_lshl_add_u64 v[192:193], v[192:193], 0, s[76:77]
	s_mov_b32 m0, s16
	ds_read_b128 v[208:211], v203 offset:49152
	ds_read_b128 v[212:215], v203 offset:50176
	ds_read_b128 v[216:219], v203 offset:51200
	ds_read_b128 v[220:223], v203 offset:52224
	ds_read_b128 v[232:235], v203 offset:53248
	ds_read_b128 v[236:239], v203 offset:54272
	ds_read_b128 v[240:243], v203 offset:55296
	ds_read_b128 v[244:247], v203 offset:56320
	global_load_lds_dwordx4 v[192:193], off
	s_add_i32 m0, s16, 0x2000
	s_add_u32 s14, s14, 0x80080
	v_lshl_add_u64 v[192:193], v[248:249], 0, s[76:77]
	s_addc_u32 s15, s15, 0
	s_add_i32 s16, s50, s18
	global_load_lds_dwordx4 v[192:193], off
	s_mov_b32 m0, s16
	s_nop 0
	global_load_lds_dwordx4 v166, s[14:15]
	s_add_i32 m0, s16, 0x2000
	s_nop 0
	global_load_lds_dwordx4 v170, s[14:15]
	v_lshl_add_u64 v[192:193], v[250:251], 0, s[76:77]
	s_mov_b32 m0, s27
	s_nop 0
	global_load_lds_dwordx4 v[192:193], off
	v_lshl_add_u64 v[192:193], v[252:253], 0, s[76:77]
	s_mov_b32 m0, s28
	s_nop 0
	global_load_lds_dwordx4 v[192:193], off
	s_waitcnt vmcnt(8)
	s_waitcnt lgkmcnt(0)
	s_setprio 1
	s_barrier
	v_mfma_f32_16x16x32_bf16 v[60:63], v[80:83], v[208:211], v[60:63]
	v_mfma_f32_16x16x32_bf16 v[60:63], v[84:87], v[212:215], v[60:63]
	v_mfma_f32_16x16x32_bf16 v[44:47], v[80:83], v[216:219], v[44:47]
	v_mfma_f32_16x16x32_bf16 v[44:47], v[84:87], v[220:223], v[44:47]
	v_mfma_f32_16x16x32_bf16 v[28:31], v[80:83], v[232:235], v[28:31]
	v_mfma_f32_16x16x32_bf16 v[28:31], v[84:87], v[236:239], v[28:31]
	v_mfma_f32_16x16x32_bf16 v[12:15], v[80:83], v[240:243], v[12:15]
	v_mfma_f32_16x16x32_bf16 v[12:15], v[84:87], v[244:247], v[12:15]
	v_mfma_f32_16x16x32_bf16 v[56:59], v[88:91], v[208:211], v[56:59]
	v_mfma_f32_16x16x32_bf16 v[56:59], v[92:95], v[212:215], v[56:59]
	v_mfma_f32_16x16x32_bf16 v[40:43], v[88:91], v[216:219], v[40:43]
	v_mfma_f32_16x16x32_bf16 v[40:43], v[92:95], v[220:223], v[40:43]
	v_mfma_f32_16x16x32_bf16 v[24:27], v[88:91], v[232:235], v[24:27]
	v_mfma_f32_16x16x32_bf16 v[24:27], v[92:95], v[236:239], v[24:27]
	v_mfma_f32_16x16x32_bf16 v[8:11], v[88:91], v[240:243], v[8:11]
	v_mfma_f32_16x16x32_bf16 v[8:11], v[92:95], v[244:247], v[8:11]
	s_setprio 0
	s_setprio 1
	v_mfma_f32_16x16x32_bf16 v[52:55], v[144:147], v[208:211], v[52:55]
	v_mfma_f32_16x16x32_bf16 v[52:55], v[148:151], v[212:215], v[52:55]
	v_mfma_f32_16x16x32_bf16 v[36:39], v[144:147], v[216:219], v[36:39]
	v_mfma_f32_16x16x32_bf16 v[36:39], v[148:151], v[220:223], v[36:39]
	v_mfma_f32_16x16x32_bf16 v[20:23], v[144:147], v[232:235], v[20:23]
	v_mfma_f32_16x16x32_bf16 v[20:23], v[148:151], v[236:239], v[20:23]
	v_mfma_f32_16x16x32_bf16 v[4:7], v[144:147], v[240:243], v[4:7]
	v_mfma_f32_16x16x32_bf16 v[4:7], v[148:151], v[244:247], v[4:7]
	v_mfma_f32_16x16x32_bf16 v[48:51], v[152:155], v[208:211], v[48:51]
	v_mfma_f32_16x16x32_bf16 v[48:51], v[156:159], v[212:215], v[48:51]
	v_mfma_f32_16x16x32_bf16 v[32:35], v[152:155], v[216:219], v[32:35]
	v_mfma_f32_16x16x32_bf16 v[32:35], v[156:159], v[220:223], v[32:35]
	v_mfma_f32_16x16x32_bf16 v[16:19], v[152:155], v[232:235], v[16:19]
	v_mfma_f32_16x16x32_bf16 v[16:19], v[156:159], v[236:239], v[16:19]
	v_mfma_f32_16x16x32_bf16 v[0:3], v[152:155], v[240:243], v[0:3]
	v_mfma_f32_16x16x32_bf16 v[0:3], v[156:159], v[244:247], v[0:3]
	s_barrier
	s_setprio 0
	s_add_i32 s48, s48, 2
	s_add_u32 s10, s10, 0x100
	s_addc_u32 s11, s11, 0
	s_add_u32 s46, s46, 0x100
	s_addc_u32 s47, s47, 0
	s_cmp_gt_u32 s48, 29
	s_cbranch_scc0 .LBB0_252
	s_and_b64 vcc, exec, s[38:39]
	s_cbranch_vccz .LBB0_255
	s_barrier

; #define PG8_STAGE(bufoff, gbase, voff) do { _Pragma("unroll") for (int _i = 0; _i < 2; ++_i) \
;         __builtin_amdgcn_global_load_lds((const unsigned*)((const char*)(gbase) + (voff)[_i]), (PG8_LAS unsigned*)(lds + (bufoff) + ldsw + _i * 8192), 16, 0, 0); } while (0)
; #define PG8_LDA(dst, b, h) do { _Pragma("unroll") for (int m = 0; m < 4; ++m) _Pragma("unroll") for (int k = 0; k < 2; ++k) dst[m][k] = *(const PG8_LAS bf16x8*)(lds + PG8_SA(b, h) + aoff + m * 2048 + k * 1024); } while (0)
; #define PG8_LDB(dst, b, h) do { _Pragma("unroll") for (int n = 0; n < 2; ++n) _Pragma("unroll") for (int k = 0; k < 2; ++k) dst[n][k] = *(const PG8_LAS bf16x8*)(lds + PG8_SB(b, h) + boff + n * 2048 + k * 1024); } while (0)
; #define PG8_MMA(ai, bj, At, Bt) do { __builtin_amdgcn_s_setprio(1); _Pragma("unroll") for (int m = 0; m < 4; ++m) _Pragma("unroll") for (int n = 0; n < 2; ++n) _Pragma("unroll") for (int k = 0; k < 2; ++k) \
;         acc[ai][bj][m][n] = __builtin_amdgcn_mfma_f32_16x16x32_bf16(Bt[n][k], At[m][k], acc[ai][bj][m][n], 0, 0, 0); __builtin_amdgcn_s_setprio(0); } while (0)
; #define PG8_WAIT_V(n) asm volatile("s_waitcnt vmcnt(" #n ")" ::: "memory")
; #define PG8_WAIT_L(n) asm volatile("s_waitcnt lgkmcnt(" #n ")" ::: "memory")
; #define PG8_BAR __builtin_amdgcn_s_barrier()
; #define PG8_SCHED __builtin_amdgcn_sched_barrier(0)
; template <class Epi, class Sched, bool ALIGN_EPI = false, bool SP2 = false, bool DUAL = false>
; __device__ __forceinline__ void gemm_phase(PG8_LAS unsigned char* lds, const Gemm g, const Sched& S, const Epi& E) {
;     ...
;             const char* a2 = last ? nA : cA + (size_t)(t + 2) * kstep; const char* b2 = last ? nB : cB + (size_t)(t + 2) * kstep;
;             const char* a3 = a2 + kstep; const char* b3 = b2 + kstep;
;             if (last && has_next) S.a_ready(nxt);
;             if constexpr (SP2) {
;             PG8_LDB(B0, 0, 0); PG8_LDB(B1, 0, 1); PG8_SCHED; PG8_LDA(At, 0, 0); PG8_STAGE(PG8_SA(1, 1), a1 + hstep, voffA);
;             PG8_WAIT_V(8); PG8_WAIT_L(0); PG8_BAR; PG8_MMA(0, 0, At, B0); PG8_MMA(0, 1, At, B1); PG8_BAR; PG8_SCHED;
;             PG8_LDA(At, 0, 1); PG8_STAGE(PG8_SB(0, 0), b2, voffB); PG8_STAGE(PG8_SB(0, 1), b2 + hstep, voffB); PG8_STAGE(PG8_SA(0, 0), a2, voffA);
;             PG8_WAIT_V(8); PG8_WAIT_L(0); PG8_BAR; PG8_MMA(1, 0, At, B0); PG8_MMA(1, 1, At, B1); PG8_BAR; PG8_SCHED;
.LBB0_805:
	v_add_u32_e32 v1, s44, v235
	ds_read_b128 v[132:135], v1
	ds_read_b128 v[136:139], v1 offset:1024
	ds_read_b128 v[140:143], v1 offset:2048
	ds_read_b128 v[144:147], v1 offset:3072
	v_add_u32_e32 v1, s45, v235
	ds_read_b128 v[148:151], v1
	ds_read_b128 v[152:155], v1 offset:1024
	ds_read_b128 v[156:159], v1 offset:2048
	ds_read_b128 v[160:163], v1 offset:3072
	s_add_u32 s16, s14, 0xfff80080
	s_addc_u32 s17, s15, -1
	s_cmp_eq_u32 s75, 28
	s_cselect_b32 s19, s50, s17
	s_cselect_b32 s18, s51, s16
	s_cselect_b32 s17, s65, s73
	s_cselect_b32 s16, s67, s72
	s_add_i32 m0, s28, 0xc000
	ds_read_b128 v[164:167], v237
	ds_read_b128 v[168:171], v237 offset:1024
	ds_read_b128 v[172:175], v237 offset:2048
	ds_read_b128 v[176:179], v237 offset:3072
	ds_read_b128 v[180:183], v237 offset:4096
	ds_read_b128 v[202:205], v237 offset:5120
	ds_read_b128 v[206:209], v237 offset:6144
	ds_read_b128 v[210:213], v237 offset:7168
	global_load_lds_dwordx4 v192, s[14:15]
	s_add_i32 m0, s28, 0xe000
	s_nop 0
	global_load_lds_dwordx4 v194, s[14:15]
	s_waitcnt vmcnt(8)
	s_waitcnt lgkmcnt(0)
	s_setprio 1
	s_barrier
	v_mfma_f32_16x16x32_bf16 v[128:131], v[132:135], v[164:167], v[128:131]
	v_mfma_f32_16x16x32_bf16 v[128:131], v[136:139], v[168:171], v[128:131]
	v_mfma_f32_16x16x32_bf16 v[120:123], v[132:135], v[172:175], v[120:123]
	v_mfma_f32_16x16x32_bf16 v[120:123], v[136:139], v[176:179], v[120:123]
	v_mfma_f32_16x16x32_bf16 v[112:115], v[132:135], v[180:183], v[112:115]
	v_mfma_f32_16x16x32_bf16 v[112:115], v[136:139], v[202:205], v[112:115]
	v_mfma_f32_16x16x32_bf16 v[104:107], v[132:135], v[206:209], v[104:107]
	v_mfma_f32_16x16x32_bf16 v[104:107], v[136:139], v[210:213], v[104:107]
	v_mfma_f32_16x16x32_bf16 v[124:127], v[140:143], v[164:167], v[124:127]
	v_mfma_f32_16x16x32_bf16 v[124:127], v[144:147], v[168:171], v[124:127]
	v_mfma_f32_16x16x32_bf16 v[116:119], v[140:143], v[172:175], v[116:119]
	v_mfma_f32_16x16x32_bf16 v[116:119], v[144:147], v[176:179], v[116:119]
	v_mfma_f32_16x16x32_bf16 v[108:111], v[140:143], v[180:183], v[108:111]
	v_mfma_f32_16x16x32_bf16 v[108:111], v[144:147], v[202:205], v[108:111]
	v_mfma_f32_16x16x32_bf16 v[100:103], v[140:143], v[206:209], v[100:103]
	v_mfma_f32_16x16x32_bf16 v[100:103], v[144:147], v[210:213], v[100:103]
	s_setprio 0
	s_setprio 1
	v_mfma_f32_16x16x32_bf16 v[96:99], v[148:151], v[164:167], v[96:99]
	v_mfma_f32_16x16x32_bf16 v[96:99], v[152:155], v[168:171], v[96:99]
	v_mfma_f32_16x16x32_bf16 v[88:91], v[148:151], v[172:175], v[88:91]
	v_mfma_f32_16x16x32_bf16 v[88:91], v[152:155], v[176:179], v[88:91]
	v_mfma_f32_16x16x32_bf16 v[80:83], v[148:151], v[180:183], v[80:83]
	v_mfma_f32_16x16x32_bf16 v[80:83], v[152:155], v[202:205], v[80:83]
	v_mfma_f32_16x16x32_bf16 v[72:75], v[148:151], v[206:209], v[72:75]
	v_mfma_f32_16x16x32_bf16 v[72:75], v[152:155], v[210:213], v[72:75]
	v_mfma_f32_16x16x32_bf16 v[92:95], v[156:159], v[164:167], v[92:95]
	v_mfma_f32_16x16x32_bf16 v[92:95], v[160:163], v[168:171], v[92:95]
	v_mfma_f32_16x16x32_bf16 v[84:87], v[156:159], v[172:175], v[84:87]
	v_mfma_f32_16x16x32_bf16 v[84:87], v[160:163], v[176:179], v[84:87]
	v_mfma_f32_16x16x32_bf16 v[76:79], v[156:159], v[180:183], v[76:79]
	v_mfma_f32_16x16x32_bf16 v[76:79], v[160:163], v[202:205], v[76:79]
	v_mfma_f32_16x16x32_bf16 v[68:71], v[156:159], v[206:209], v[68:71]
	v_mfma_f32_16x16x32_bf16 v[68:71], v[160:163], v[210:213], v[68:71]
	s_barrier
	s_setprio 0
	s_add_i32 s76, s44, s27
	v_lshl_add_u64 v[214:215], s[16:17], 0, v[186:187]
	s_mov_b32 m0, s76
	ds_read_b128 v[164:167], v237 offset:16384
	ds_read_b128 v[168:171], v237 offset:17408
	ds_read_b128 v[172:175], v237 offset:18432
	ds_read_b128 v[176:179], v237 offset:19456
	ds_read_b128 v[180:183], v237 offset:20480
	ds_read_b128 v[202:205], v237 offset:21504
	ds_read_b128 v[206:209], v237 offset:22528
	ds_read_b128 v[210:213], v237 offset:23552
	global_load_lds_dwordx4 v[214:215], off
	s_add_i32 m0, s76, 0x2000
	s_add_u32 s76, s16, 0x80000
	v_lshl_add_u64 v[216:217], s[16:17], 0, v[190:191]
	s_addc_u32 s77, s17, 0
	s_add_i32 s78, s45, s27
	global_load_lds_dwordx4 v[216:217], off
	s_mov_b32 m0, s78
	v_lshl_add_u64 v[218:219], s[18:19], 0, v[184:185]
	global_load_lds_dwordx4 v186, s[76:77]
	v_lshl_add_u64 v[2:3], s[76:77], 0, v[190:191]
	s_add_i32 m0, s78, 0x2000
	v_lshl_add_u64 v[220:221], s[18:19], 0, v[188:189]
	global_load_lds_dwordx4 v[2:3], off
	s_mov_b32 m0, s28
	s_nop 0
	global_load_lds_dwordx4 v[218:219], off
	s_mov_b32 m0, s29
	s_nop 0
	global_load_lds_dwordx4 v[220:221], off
	s_waitcnt vmcnt(8)
	s_waitcnt lgkmcnt(0)
	s_setprio 1
	s_barrier
; #define PG8_STAGE(bufoff, gbase, voff) do { _Pragma("unroll") for (int _i = 0; _i < 2; ++_i) \
;         __builtin_amdgcn_global_load_lds((const unsigned*)((const char*)(gbase) + (voff)[_i]), (PG8_LAS unsigned*)(lds + (bufoff) + ldsw + _i * 8192), 16, 0, 0); } while (0)
; #define PG8_LDA(dst, b, h) do { _Pragma("unroll") for (int m = 0; m < 4; ++m) _Pragma("unroll") for (int k = 0; k < 2; ++k) dst[m][k] = *(const PG8_LAS bf16x8*)(lds + PG8_SA(b, h) + aoff + m * 2048 + k * 1024); } while (0)
; #define PG8_LDB(dst, b, h) do { _Pragma("unroll") for (int n = 0; n < 2; ++n) _Pragma("unroll") for (int k = 0; k < 2; ++k) dst[n][k] = *(const PG8_LAS bf16x8*)(lds + PG8_SB(b, h) + boff + n * 2048 + k * 1024); } while (0)
; #define PG8_MMA(ai, bj, At, Bt) do { __builtin_amdgcn_s_setprio(1); _Pragma("unroll") for (int m = 0; m < 4; ++m) _Pragma("unroll") for (int n = 0; n < 2; ++n) _Pragma("unroll") for (int k = 0; k < 2; ++k) \
;         acc[ai][bj][m][n] = __builtin_amdgcn_mfma_f32_16x16x32_bf16(Bt[n][k], At[m][k], acc[ai][bj][m][n], 0, 0, 0); __builtin_amdgcn_s_setprio(0); } while (0)
; #define PG8_WAIT_V(n) asm volatile("s_waitcnt vmcnt(" #n ")" ::: "memory")
; #define PG8_WAIT_L(n) asm volatile("s_waitcnt lgkmcnt(" #n ")" ::: "memory")
; #define PG8_BAR __builtin_amdgcn_s_barrier()
; #define PG8_SCHED __builtin_amdgcn_sched_barrier(0)
; template <class Epi, class Sched, bool ALIGN_EPI = false, bool SP2 = false, bool DUAL = false>
; __device__ __forceinline__ void gemm_phase(PG8_LAS unsigned char* lds, const Gemm g, const Sched& S, const Epi& E) {
;     ...
;             PG8_WAIT_V(8); PG8_WAIT_L(0); PG8_BAR; PG8_MMA(1, 0, At, B0); PG8_MMA(1, 1, At, B1); PG8_BAR; PG8_SCHED;
;             PG8_LDB(B0, 1, 0); PG8_LDB(B1, 1, 1); PG8_SCHED; PG8_LDA(At, 1, 0); PG8_STAGE(PG8_SA(0, 1), a2 + hstep, voffA);
;             PG8_WAIT_V(8); PG8_WAIT_L(0); PG8_BAR; PG8_MMA(0, 0, At, B0); PG8_MMA(0, 1, At, B1); PG8_BAR; PG8_SCHED;
	v_mfma_f32_16x16x32_bf16 v[64:67], v[132:135], v[164:167], v[64:67]
	v_mfma_f32_16x16x32_bf16 v[64:67], v[136:139], v[168:171], v[64:67]
	v_mfma_f32_16x16x32_bf16 v[56:59], v[132:135], v[172:175], v[56:59]
	v_mfma_f32_16x16x32_bf16 v[56:59], v[136:139], v[176:179], v[56:59]
	v_mfma_f32_16x16x32_bf16 v[48:51], v[132:135], v[180:183], v[48:51]
	v_mfma_f32_16x16x32_bf16 v[48:51], v[136:139], v[202:205], v[48:51]
	v_mfma_f32_16x16x32_bf16 v[40:43], v[132:135], v[206:209], v[40:43]
	v_mfma_f32_16x16x32_bf16 v[40:43], v[136:139], v[210:213], v[40:43]
	v_mfma_f32_16x16x32_bf16 v[60:63], v[140:143], v[164:167], v[60:63]
	v_mfma_f32_16x16x32_bf16 v[60:63], v[144:147], v[168:171], v[60:63]
	v_mfma_f32_16x16x32_bf16 v[52:55], v[140:143], v[172:175], v[52:55]
	v_mfma_f32_16x16x32_bf16 v[52:55], v[144:147], v[176:179], v[52:55]
	v_mfma_f32_16x16x32_bf16 v[44:47], v[140:143], v[180:183], v[44:47]
	v_mfma_f32_16x16x32_bf16 v[44:47], v[144:147], v[202:205], v[44:47]
	v_mfma_f32_16x16x32_bf16 v[36:39], v[140:143], v[206:209], v[36:39]
	v_mfma_f32_16x16x32_bf16 v[36:39], v[144:147], v[210:213], v[36:39]
	s_setprio 0
	s_setprio 1
	v_mfma_f32_16x16x32_bf16 v[32:35], v[148:151], v[164:167], v[32:35]
	v_mfma_f32_16x16x32_bf16 v[32:35], v[152:155], v[168:171], v[32:35]
	v_mfma_f32_16x16x32_bf16 v[24:27], v[148:151], v[172:175], v[24:27]
	v_mfma_f32_16x16x32_bf16 v[24:27], v[152:155], v[176:179], v[24:27]
	v_mfma_f32_16x16x32_bf16 v[16:19], v[148:151], v[180:183], v[16:19]
	v_mfma_f32_16x16x32_bf16 v[16:19], v[152:155], v[202:205], v[16:19]
	v_mfma_f32_16x16x32_bf16 v[8:11], v[148:151], v[206:209], v[8:11]
	v_mfma_f32_16x16x32_bf16 v[8:11], v[152:155], v[210:213], v[8:11]
	v_mfma_f32_16x16x32_bf16 v[28:31], v[156:159], v[164:167], v[28:31]
	v_mfma_f32_16x16x32_bf16 v[28:31], v[160:163], v[168:171], v[28:31]
	v_mfma_f32_16x16x32_bf16 v[20:23], v[156:159], v[172:175], v[20:23]
	v_mfma_f32_16x16x32_bf16 v[20:23], v[160:163], v[176:179], v[20:23]
	v_mfma_f32_16x16x32_bf16 v[12:15], v[156:159], v[180:183], v[12:15]
	v_mfma_f32_16x16x32_bf16 v[12:15], v[160:163], v[202:205], v[12:15]
	v_mfma_f32_16x16x32_bf16 v[2:5], v[156:159], v[206:209], v[4:7]
	v_mfma_f32_16x16x32_bf16 v[2:5], v[160:163], v[210:213], v[2:5]
	s_barrier
	s_setprio 0
	s_add_i32 s76, 0, 0x18000
	v_add_u32_e32 v1, s76, v235
	s_add_i32 s77, 0, 0x1c000
	ds_read_b128 v[132:135], v1
	ds_read_b128 v[136:139], v1 offset:1024
	ds_read_b128 v[140:143], v1 offset:2048
	ds_read_b128 v[144:147], v1 offset:3072
	v_add_u32_e32 v1, s77, v235
	ds_read_b128 v[148:151], v1
	ds_read_b128 v[152:155], v1 offset:1024
	ds_read_b128 v[156:159], v1 offset:2048
	ds_read_b128 v[160:163], v1 offset:3072
	s_add_u32 s18, s18, 0x80000
	s_addc_u32 s19, s19, 0
	s_mov_b32 m0, s34
	ds_read_b128 v[164:167], v237 offset:32768
	ds_read_b128 v[168:171], v237 offset:33792
	ds_read_b128 v[172:175], v237 offset:34816
	ds_read_b128 v[176:179], v237 offset:35840
	ds_read_b128 v[180:183], v237 offset:36864
	ds_read_b128 v[202:205], v237 offset:37888
	ds_read_b128 v[206:209], v237 offset:38912
	ds_read_b128 v[210:213], v237 offset:39936
	global_load_lds_dwordx4 v184, s[18:19]
	s_mov_b32 m0, s35
	s_nop 0
	global_load_lds_dwordx4 v188, s[18:19]
	s_waitcnt vmcnt(8)
	s_waitcnt lgkmcnt(0)
	s_setprio 1
	s_barrier
	v_mfma_f32_16x16x32_bf16 v[128:131], v[132:135], v[164:167], v[128:131]
	v_mfma_f32_16x16x32_bf16 v[128:131], v[136:139], v[168:171], v[128:131]
	v_mfma_f32_16x16x32_bf16 v[120:123], v[132:135], v[172:175], v[120:123]
	v_mfma_f32_16x16x32_bf16 v[120:123], v[136:139], v[176:179], v[120:123]
	v_mfma_f32_16x16x32_bf16 v[112:115], v[132:135], v[180:183], v[112:115]
	v_mfma_f32_16x16x32_bf16 v[112:115], v[136:139], v[202:205], v[112:115]
	v_mfma_f32_16x16x32_bf16 v[104:107], v[132:135], v[206:209], v[104:107]
	v_mfma_f32_16x16x32_bf16 v[104:107], v[136:139], v[210:213], v[104:107]
	v_mfma_f32_16x16x32_bf16 v[124:127], v[140:143], v[164:167], v[124:127]
	v_mfma_f32_16x16x32_bf16 v[124:127], v[144:147], v[168:171], v[124:127]
	v_mfma_f32_16x16x32_bf16 v[116:119], v[140:143], v[172:175], v[116:119]
	v_mfma_f32_16x16x32_bf16 v[116:119], v[144:147], v[176:179], v[116:119]
	v_mfma_f32_16x16x32_bf16 v[108:111], v[140:143], v[180:183], v[108:111]
	v_mfma_f32_16x16x32_bf16 v[108:111], v[144:147], v[202:205], v[108:111]
	v_mfma_f32_16x16x32_bf16 v[100:103], v[140:143], v[206:209], v[100:103]
	v_mfma_f32_16x16x32_bf16 v[100:103], v[144:147], v[210:213], v[100:103]
	s_setprio 0
	s_setprio 1
	v_mfma_f32_16x16x32_bf16 v[96:99], v[148:151], v[164:167], v[96:99]
	v_mfma_f32_16x16x32_bf16 v[96:99], v[152:155], v[168:171], v[96:99]
	v_mfma_f32_16x16x32_bf16 v[88:91], v[148:151], v[172:175], v[88:91]
	v_mfma_f32_16x16x32_bf16 v[88:91], v[152:155], v[176:179], v[88:91]
	v_mfma_f32_16x16x32_bf16 v[80:83], v[148:151], v[180:183], v[80:83]
	v_mfma_f32_16x16x32_bf16 v[80:83], v[152:155], v[202:205], v[80:83]
	v_mfma_f32_16x16x32_bf16 v[72:75], v[148:151], v[206:209], v[72:75]
	v_mfma_f32_16x16x32_bf16 v[72:75], v[152:155], v[210:213], v[72:75]
	v_mfma_f32_16x16x32_bf16 v[92:95], v[156:159], v[164:167], v[92:95]
	v_mfma_f32_16x16x32_bf16 v[92:95], v[160:163], v[168:171], v[92:95]
	v_mfma_f32_16x16x32_bf16 v[84:87], v[156:159], v[172:175], v[84:87]
	v_mfma_f32_16x16x32_bf16 v[84:87], v[160:163], v[176:179], v[84:87]
	v_mfma_f32_16x16x32_bf16 v[76:79], v[156:159], v[180:183], v[76:79]
	v_mfma_f32_16x16x32_bf16 v[76:79], v[160:163], v[202:205], v[76:79]
	v_mfma_f32_16x16x32_bf16 v[68:71], v[156:159], v[206:209], v[68:71]
	v_mfma_f32_16x16x32_bf16 v[68:71], v[160:163], v[210:213], v[68:71]
	s_barrier
; #define PG8_STAGE(bufoff, gbase, voff) do { _Pragma("unroll") for (int _i = 0; _i < 2; ++_i) \
;         __builtin_amdgcn_global_load_lds((const unsigned*)((const char*)(gbase) + (voff)[_i]), (PG8_LAS unsigned*)(lds + (bufoff) + ldsw + _i * 8192), 16, 0, 0); } while (0)
; #define PG8_LDA(dst, b, h) do { _Pragma("unroll") for (int m = 0; m < 4; ++m) _Pragma("unroll") for (int k = 0; k < 2; ++k) dst[m][k] = *(const PG8_LAS bf16x8*)(lds + PG8_SA(b, h) + aoff + m * 2048 + k * 1024); } while (0)
; #define PG8_MMA(ai, bj, At, Bt) do { __builtin_amdgcn_s_setprio(1); _Pragma("unroll") for (int m = 0; m < 4; ++m) _Pragma("unroll") for (int n = 0; n < 2; ++n) _Pragma("unroll") for (int k = 0; k < 2; ++k) \
;         acc[ai][bj][m][n] = __builtin_amdgcn_mfma_f32_16x16x32_bf16(Bt[n][k], At[m][k], acc[ai][bj][m][n], 0, 0, 0); __builtin_amdgcn_s_setprio(0); } while (0)
; #define PG8_WAIT_V(n) asm volatile("s_waitcnt vmcnt(" #n ")" ::: "memory")
; #define PG8_WAIT_L(n) asm volatile("s_waitcnt lgkmcnt(" #n ")" ::: "memory")
; #define PG8_BAR __builtin_amdgcn_s_barrier()
; #define PG8_SCHED __builtin_amdgcn_sched_barrier(0)
; template <class Epi, class Sched, bool ALIGN_EPI = false, bool SP2 = false, bool DUAL = false>
; __device__ __forceinline__ void gemm_phase(PG8_LAS unsigned char* lds, const Gemm g, const Sched& S, const Epi& E) {
;     ...
;             PG8_WAIT_V(8); PG8_WAIT_L(0); PG8_BAR; PG8_MMA(0, 0, At, B0); PG8_MMA(0, 1, At, B1); PG8_BAR; PG8_SCHED;
;             PG8_LDA(At, 1, 1); PG8_STAGE(PG8_SB(1, 0), b3, voffB); PG8_STAGE(PG8_SB(1, 1), b3 + hstep, voffB); PG8_STAGE(PG8_SA(1, 0), a3, voffA);
;             PG8_WAIT_V(8); PG8_WAIT_L(0); PG8_BAR; PG8_MMA(1, 0, At, B0); PG8_MMA(1, 1, At, B1); PG8_BAR; PG8_SCHED;
	s_setprio 0
	s_add_i32 s18, s76, s27
	v_lshl_add_u64 v[6:7], v[214:215], 0, s[36:37]
	s_mov_b32 m0, s18
	ds_read_b128 v[164:167], v237 offset:49152
	ds_read_b128 v[168:171], v237 offset:50176
	ds_read_b128 v[172:175], v237 offset:51200
	ds_read_b128 v[176:179], v237 offset:52224
	ds_read_b128 v[180:183], v237 offset:53248
	ds_read_b128 v[202:205], v237 offset:54272
	ds_read_b128 v[206:209], v237 offset:55296
	ds_read_b128 v[210:213], v237 offset:56320
	global_load_lds_dwordx4 v[6:7], off
	s_add_i32 m0, s18, 0x2000
	s_add_u32 s16, s16, 0x80080
	v_lshl_add_u64 v[6:7], v[216:217], 0, s[36:37]
	s_addc_u32 s17, s17, 0
	s_add_i32 s18, s77, s27
	global_load_lds_dwordx4 v[6:7], off
	s_mov_b32 m0, s18
	s_nop 0
	global_load_lds_dwordx4 v186, s[16:17]
	s_add_i32 m0, s18, 0x2000
	s_nop 0
	global_load_lds_dwordx4 v190, s[16:17]
	v_lshl_add_u64 v[6:7], v[218:219], 0, s[36:37]
	s_mov_b32 m0, s42
	s_nop 0
	global_load_lds_dwordx4 v[6:7], off
	v_lshl_add_u64 v[6:7], v[220:221], 0, s[36:37]
	s_mov_b32 m0, s43
	s_nop 0
	global_load_lds_dwordx4 v[6:7], off
	s_waitcnt vmcnt(8)
	s_waitcnt lgkmcnt(0)
	s_setprio 1
	s_barrier
	v_mfma_f32_16x16x32_bf16 v[64:67], v[132:135], v[164:167], v[64:67]
	v_mfma_f32_16x16x32_bf16 v[64:67], v[136:139], v[168:171], v[64:67]
	v_mfma_f32_16x16x32_bf16 v[56:59], v[132:135], v[172:175], v[56:59]
	v_mfma_f32_16x16x32_bf16 v[56:59], v[136:139], v[176:179], v[56:59]
	v_mfma_f32_16x16x32_bf16 v[48:51], v[132:135], v[180:183], v[48:51]
	v_mfma_f32_16x16x32_bf16 v[48:51], v[136:139], v[202:205], v[48:51]
	v_mfma_f32_16x16x32_bf16 v[40:43], v[132:135], v[206:209], v[40:43]
	v_mfma_f32_16x16x32_bf16 v[40:43], v[136:139], v[210:213], v[40:43]
	v_mfma_f32_16x16x32_bf16 v[60:63], v[140:143], v[164:167], v[60:63]
	v_mfma_f32_16x16x32_bf16 v[60:63], v[144:147], v[168:171], v[60:63]
	v_mfma_f32_16x16x32_bf16 v[52:55], v[140:143], v[172:175], v[52:55]
	v_mfma_f32_16x16x32_bf16 v[52:55], v[144:147], v[176:179], v[52:55]
	v_mfma_f32_16x16x32_bf16 v[44:47], v[140:143], v[180:183], v[44:47]
	v_mfma_f32_16x16x32_bf16 v[44:47], v[144:147], v[202:205], v[44:47]
	v_mfma_f32_16x16x32_bf16 v[36:39], v[140:143], v[206:209], v[36:39]
	v_mfma_f32_16x16x32_bf16 v[36:39], v[144:147], v[210:213], v[36:39]
	s_setprio 0
	s_setprio 1
	v_mfma_f32_16x16x32_bf16 v[32:35], v[148:151], v[164:167], v[32:35]
	v_mfma_f32_16x16x32_bf16 v[28:31], v[156:159], v[164:167], v[28:31]
	v_mfma_f32_16x16x32_bf16 v[24:27], v[148:151], v[172:175], v[24:27]
	v_mfma_f32_16x16x32_bf16 v[20:23], v[156:159], v[172:175], v[20:23]
	v_mfma_f32_16x16x32_bf16 v[16:19], v[148:151], v[180:183], v[16:19]
	v_mfma_f32_16x16x32_bf16 v[12:15], v[156:159], v[180:183], v[12:15]
	v_mfma_f32_16x16x32_bf16 v[6:9], v[148:151], v[206:209], v[8:11]
	v_mfma_f32_16x16x32_bf16 v[2:5], v[156:159], v[206:209], v[2:5]
	v_mfma_f32_16x16x32_bf16 v[32:35], v[152:155], v[168:171], v[32:35]
	v_mfma_f32_16x16x32_bf16 v[28:31], v[160:163], v[168:171], v[28:31]
	v_mfma_f32_16x16x32_bf16 v[24:27], v[152:155], v[176:179], v[24:27]
	v_mfma_f32_16x16x32_bf16 v[20:23], v[160:163], v[176:179], v[20:23]
	v_mfma_f32_16x16x32_bf16 v[16:19], v[152:155], v[202:205], v[16:19]
	v_mfma_f32_16x16x32_bf16 v[12:15], v[160:163], v[202:205], v[12:15]
	v_mfma_f32_16x16x32_bf16 v[8:11], v[152:155], v[210:213], v[6:9]
	v_mfma_f32_16x16x32_bf16 v[4:7], v[160:163], v[210:213], v[2:5]
	s_barrier
	s_setprio 0
	s_add_i32 s75, s75, 2
	s_add_u32 s14, s14, 0x100
	s_addc_u32 s15, s15, 0
	s_add_u32 s72, s72, 0x100
	s_addc_u32 s73, s73, 0
	s_cmp_gt_u32 s75, 29
	s_cbranch_scc0 .LBB0_805
	s_and_b64 vcc, exec, s[38:39]
	s_cbranch_vccz .LBB0_808
	s_barrier

;     __device__ bool next(int i, Unit& u) const { if (!base.next(i >> 1, u)) return false; u.sub = i & 1; return true; }
; #define PG8_STAGE(bufoff, gbase, voff) do { _Pragma("unroll") for (int _i = 0; _i < 2; ++_i) \
;         __builtin_amdgcn_global_load_lds((const unsigned*)((const char*)(gbase) + (voff)[_i]), (PG8_LAS unsigned*)(lds + (bufoff) + ldsw + _i * 8192), 16, 0, 0); } while (0)
; #define PG8_LDA(dst, b, h) do { _Pragma("unroll") for (int m = 0; m < 4; ++m) _Pragma("unroll") for (int k = 0; k < 2; ++k) dst[m][k] = *(const PG8_LAS bf16x8*)(lds + PG8_SA(b, h) + aoff + m * 2048 + k * 1024); } while (0)
; #define PG8_LDB(dst, b, h) do { _Pragma("unroll") for (int n = 0; n < 2; ++n) _Pragma("unroll") for (int k = 0; k < 2; ++k) dst[n][k] = *(const PG8_LAS bf16x8*)(lds + PG8_SB(b, h) + boff + n * 2048 + k * 1024); } while (0)
; #define PG8_WAIT_V(n) asm volatile("s_waitcnt vmcnt(" #n ")" ::: "memory")
; template <class Epi, class Sched, bool ALIGN_EPI = false, bool SP2 = false, bool DUAL = false>
; __device__ __forceinline__ void gemm_phase(PG8_LAS unsigned char* lds, const Gemm g, const Sched& S, const Epi& E) {
;     ...
;         const bool has_next = S.next(ui + 1, nxt);
;         const char* nA = has_next ? (const char*)((DUAL && nxt.sub) ? g.A2 : g.A) + (size_t)nxt.pm * tstep : cA; const char* nB = has_next ? (const char*)((DUAL && nxt.sub) ? g.Bt2 : g.Bt) + (size_t)nxt.pn * tstep : cB;
;         for (int t = 0; t < nt; t += 2) {
;             const bool last = (t == nt - 2);
;             const char* a1 = cA + (size_t)(t + 1) * kstep;
;             const char* a2 = last ? nA : cA + (size_t)(t + 2) * kstep; const char* b2 = last ? nB : cB + (size_t)(t + 2) * kstep;
;             const char* a3 = a2 + kstep; const char* b3 = b2 + kstep;
;             if (last && has_next) S.a_ready(nxt);
;             if constexpr (SP2) {
;             PG8_LDB(B0, 0, 0); PG8_LDB(B1, 0, 1); PG8_SCHED; PG8_LDA(At, 0, 0); PG8_STAGE(PG8_SA(1, 1), a1 + hstep, voffA);
;             PG8_WAIT_V(8); PG8_WAIT_L(0); PG8_BAR; PG8_MMA(0, 0, At, B0); PG8_MMA(0, 1, At, B1); PG8_BAR; PG8_SCHED;
;             PG8_LDA(At, 0, 1); PG8_STAGE(PG8_SB(0, 0), b2, voffB); PG8_STAGE(PG8_SB(0, 1), b2 + hstep, voffB); PG8_STAGE(PG8_SA(0, 0), a2, voffA);
;             PG8_WAIT_V(8); PG8_WAIT_L(0); PG8_BAR; PG8_MMA(1, 0, At, B0); PG8_MMA(1, 1, At, B1); PG8_BAR; PG8_SCHED;
.LBB0_895:
	s_ashr_i32 s61, s60, 31
	s_lshl_b64 s[18:19], s[60:61], 20
	s_add_u32 s62, s10, s18
	s_addc_u32 s63, s11, s19
	s_and_b64 s[18:19], s[6:7], exec
	s_cselect_b32 s18, s63, s17
	s_cselect_b32 s19, s62, s16
	s_ashr_i32 s41, s40, 31
	s_lshl_b64 s[64:65], s[40:41], 20
	s_add_u32 s64, s12, s64
	s_addc_u32 s65, s13, s65
	s_and_b64 s[68:69], s[6:7], exec
	s_cselect_b32 s41, s65, s15
	s_cselect_b32 s61, s64, s14
	s_add_u32 s68, s16, 0x80080
	s_addc_u32 s69, s17, 0
	s_add_u32 s67, s14, 0x100
	s_addc_u32 s70, s15, 0
	s_mov_b32 s71, -2
	s_waitcnt lgkmcnt(0)
	s_add_u32 s14, s68, 0xfff80080
	s_addc_u32 s15, s69, -1
	s_cmp_eq_u32 s71, 28
	s_cselect_b32 s17, s18, s15
	s_cselect_b32 s16, s19, s14
	s_cselect_b32 s15, s41, s70
	s_cselect_b32 s14, s61, s67
	s_waitcnt vmcnt(8)
	s_waitcnt lgkmcnt(0)
	s_setprio 1
	s_barrier
	v_mfma_f32_16x16x32_bf16 v[124:127], v[128:131], v[160:163], 0
	v_mfma_f32_16x16x32_bf16 v[124:127], v[132:135], v[164:167], v[124:127]
	v_mfma_f32_16x16x32_bf16 v[108:111], v[128:131], v[168:171], 0
	v_mfma_f32_16x16x32_bf16 v[108:111], v[132:135], v[172:175], v[108:111]
	v_mfma_f32_16x16x32_bf16 v[92:95], v[128:131], v[196:199], 0
	v_mfma_f32_16x16x32_bf16 v[92:95], v[132:135], v[202:205], v[92:95]
	v_mfma_f32_16x16x32_bf16 v[76:79], v[128:131], v[206:209], 0
	v_mfma_f32_16x16x32_bf16 v[76:79], v[132:135], v[232:235], v[76:79]
	v_mfma_f32_16x16x32_bf16 v[120:123], v[136:139], v[160:163], 0
	v_mfma_f32_16x16x32_bf16 v[120:123], v[140:143], v[164:167], v[120:123]
	v_mfma_f32_16x16x32_bf16 v[104:107], v[136:139], v[168:171], 0
	v_mfma_f32_16x16x32_bf16 v[104:107], v[140:143], v[172:175], v[104:107]
	v_mfma_f32_16x16x32_bf16 v[88:91], v[136:139], v[196:199], 0
	v_mfma_f32_16x16x32_bf16 v[88:91], v[140:143], v[202:205], v[88:91]
	v_mfma_f32_16x16x32_bf16 v[72:75], v[136:139], v[206:209], 0
	v_mfma_f32_16x16x32_bf16 v[72:75], v[140:143], v[232:235], v[72:75]
	s_setprio 0
	s_setprio 1
	v_mfma_f32_16x16x32_bf16 v[116:119], v[144:147], v[160:163], 0
	v_mfma_f32_16x16x32_bf16 v[116:119], v[148:151], v[164:167], v[116:119]
	v_mfma_f32_16x16x32_bf16 v[100:103], v[144:147], v[168:171], 0
	v_mfma_f32_16x16x32_bf16 v[100:103], v[148:151], v[172:175], v[100:103]
	v_mfma_f32_16x16x32_bf16 v[84:87], v[144:147], v[196:199], 0
	v_mfma_f32_16x16x32_bf16 v[84:87], v[148:151], v[202:205], v[84:87]
	v_mfma_f32_16x16x32_bf16 v[68:71], v[144:147], v[206:209], 0
	v_mfma_f32_16x16x32_bf16 v[68:71], v[148:151], v[232:235], v[68:71]
	v_mfma_f32_16x16x32_bf16 v[112:115], v[152:155], v[160:163], 0
	v_mfma_f32_16x16x32_bf16 v[112:115], v[156:159], v[164:167], v[112:115]
	v_mfma_f32_16x16x32_bf16 v[96:99], v[152:155], v[168:171], 0
	v_mfma_f32_16x16x32_bf16 v[96:99], v[156:159], v[172:175], v[96:99]
	v_mfma_f32_16x16x32_bf16 v[80:83], v[152:155], v[196:199], 0
	v_mfma_f32_16x16x32_bf16 v[80:83], v[156:159], v[202:205], v[80:83]
	v_mfma_f32_16x16x32_bf16 v[64:67], v[152:155], v[206:209], 0
	v_mfma_f32_16x16x32_bf16 v[64:67], v[156:159], v[232:235], v[64:67]
	s_barrier
	s_setprio 0
	s_add_i32 m0, s27, 0xc000
	s_nop 0
	global_load_lds_dwordx4 v188, s[68:69]
	s_add_i32 m0, s27, 0xe000
	s_nop 0
	global_load_lds_dwordx4 v190, s[68:69]
	s_add_i32 s72, s48, s26
	v_lshl_add_u64 v[222:223], s[14:15], 0, v[182:183]
	s_mov_b32 m0, s72
	ds_read_b128 v[160:163], v220 offset:16384
	ds_read_b128 v[164:167], v220 offset:17408
	ds_read_b128 v[168:171], v220 offset:18432
	ds_read_b128 v[172:175], v220 offset:19456
	ds_read_b128 v[196:199], v220 offset:20480
	ds_read_b128 v[202:205], v220 offset:21504
	ds_read_b128 v[206:209], v220 offset:22528
	ds_read_b128 v[232:235], v220 offset:23552
	global_load_lds_dwordx4 v[222:223], off
	s_add_i32 m0, s72, 0x2000
	s_add_u32 s72, s14, 0x80000
	v_lshl_add_u64 v[228:229], s[14:15], 0, v[186:187]
	s_addc_u32 s73, s15, 0
	s_add_i32 s74, s49, s26
	global_load_lds_dwordx4 v[228:229], off
	s_mov_b32 m0, s74
	v_lshl_add_u64 v[238:239], s[16:17], 0, v[184:185]
	global_load_lds_dwordx4 v182, s[72:73]
	s_add_i32 m0, s74, 0x2000
	s_nop 0
	global_load_lds_dwordx4 v186, s[72:73]
	v_lshl_add_u64 v[236:237], s[16:17], 0, v[180:181]
	s_mov_b32 m0, s27
	s_nop 0
	global_load_lds_dwordx4 v[236:237], off
	s_mov_b32 m0, s28
	s_nop 0
	global_load_lds_dwordx4 v[238:239], off
	s_waitcnt vmcnt(8)
	s_waitcnt lgkmcnt(0)
	s_setprio 1
	s_barrier
	v_mfma_f32_16x16x32_bf16 v[60:63], v[128:131], v[160:163], 0
	v_mfma_f32_16x16x32_bf16 v[60:63], v[132:135], v[164:167], v[60:63]
	v_mfma_f32_16x16x32_bf16 v[44:47], v[128:131], v[168:171], 0
	v_mfma_f32_16x16x32_bf16 v[44:47], v[132:135], v[172:175], v[44:47]
	v_mfma_f32_16x16x32_bf16 v[28:31], v[128:131], v[196:199], 0
	v_mfma_f32_16x16x32_bf16 v[28:31], v[132:135], v[202:205], v[28:31]
	v_mfma_f32_16x16x32_bf16 v[12:15], v[128:131], v[206:209], 0
	v_mfma_f32_16x16x32_bf16 v[12:15], v[132:135], v[232:235], v[12:15]
	v_mfma_f32_16x16x32_bf16 v[56:59], v[136:139], v[160:163], 0
	v_mfma_f32_16x16x32_bf16 v[56:59], v[140:143], v[164:167], v[56:59]
	v_mfma_f32_16x16x32_bf16 v[40:43], v[136:139], v[168:171], 0
	v_mfma_f32_16x16x32_bf16 v[40:43], v[140:143], v[172:175], v[40:43]
	v_mfma_f32_16x16x32_bf16 v[24:27], v[136:139], v[196:199], 0
	v_mfma_f32_16x16x32_bf16 v[24:27], v[140:143], v[202:205], v[24:27]
	v_mfma_f32_16x16x32_bf16 v[8:11], v[136:139], v[206:209], 0
	v_mfma_f32_16x16x32_bf16 v[8:11], v[140:143], v[232:235], v[8:11]
	s_setprio 0
	s_setprio 1
	v_mfma_f32_16x16x32_bf16 v[52:55], v[144:147], v[160:163], 0
	v_mfma_f32_16x16x32_bf16 v[52:55], v[148:151], v[164:167], v[52:55]
	v_mfma_f32_16x16x32_bf16 v[36:39], v[144:147], v[168:171], 0
	v_mfma_f32_16x16x32_bf16 v[36:39], v[148:151], v[172:175], v[36:39]
	v_mfma_f32_16x16x32_bf16 v[20:23], v[144:147], v[196:199], 0
	v_mfma_f32_16x16x32_bf16 v[20:23], v[148:151], v[202:205], v[20:23]
	v_mfma_f32_16x16x32_bf16 v[4:7], v[144:147], v[206:209], 0
	v_mfma_f32_16x16x32_bf16 v[4:7], v[148:151], v[232:235], v[4:7]
	v_mfma_f32_16x16x32_bf16 v[48:51], v[152:155], v[160:163], 0
	v_mfma_f32_16x16x32_bf16 v[48:51], v[156:159], v[164:167], v[48:51]
	v_mfma_f32_16x16x32_bf16 v[32:35], v[152:155], v[168:171], 0
	v_mfma_f32_16x16x32_bf16 v[32:35], v[156:159], v[172:175], v[32:35]
	v_mfma_f32_16x16x32_bf16 v[16:19], v[152:155], v[196:199], 0
	v_mfma_f32_16x16x32_bf16 v[16:19], v[156:159], v[202:205], v[16:19]
	v_mfma_f32_16x16x32_bf16 v[0:3], v[152:155], v[206:209], 0
	v_mfma_f32_16x16x32_bf16 v[0:3], v[156:159], v[232:235], v[0:3]
	s_barrier
; #define PG8_STAGE(bufoff, gbase, voff) do { _Pragma("unroll") for (int _i = 0; _i < 2; ++_i) \
;         __builtin_amdgcn_global_load_lds((const unsigned*)((const char*)(gbase) + (voff)[_i]), (PG8_LAS unsigned*)(lds + (bufoff) + ldsw + _i * 8192), 16, 0, 0); } while (0)
; #define PG8_LDA(dst, b, h) do { _Pragma("unroll") for (int m = 0; m < 4; ++m) _Pragma("unroll") for (int k = 0; k < 2; ++k) dst[m][k] = *(const PG8_LAS bf16x8*)(lds + PG8_SA(b, h) + aoff + m * 2048 + k * 1024); } while (0)
; #define PG8_LDB(dst, b, h) do { _Pragma("unroll") for (int n = 0; n < 2; ++n) _Pragma("unroll") for (int k = 0; k < 2; ++k) dst[n][k] = *(const PG8_LAS bf16x8*)(lds + PG8_SB(b, h) + boff + n * 2048 + k * 1024); } while (0)
; #define PG8_MMA(ai, bj, At, Bt) do { __builtin_amdgcn_s_setprio(1); _Pragma("unroll") for (int m = 0; m < 4; ++m) _Pragma("unroll") for (int n = 0; n < 2; ++n) _Pragma("unroll") for (int k = 0; k < 2; ++k) \
;         acc[ai][bj][m][n] = __builtin_amdgcn_mfma_f32_16x16x32_bf16(Bt[n][k], At[m][k], acc[ai][bj][m][n], 0, 0, 0); __builtin_amdgcn_s_setprio(0); } while (0)
; #define PG8_WAIT_V(n) asm volatile("s_waitcnt vmcnt(" #n ")" ::: "memory")
; #define PG8_WAIT_L(n) asm volatile("s_waitcnt lgkmcnt(" #n ")" ::: "memory")
; #define PG8_BAR __builtin_amdgcn_s_barrier()
; #define PG8_SCHED __builtin_amdgcn_sched_barrier(0)
; template <class Epi, class Sched, bool ALIGN_EPI = false, bool SP2 = false, bool DUAL = false>
; __device__ __forceinline__ void gemm_phase(PG8_LAS unsigned char* lds, const Gemm g, const Sched& S, const Epi& E) {
;     ...
;             PG8_LDB(B0, 1, 0); PG8_LDB(B1, 1, 1); PG8_SCHED; PG8_LDA(At, 1, 0); PG8_STAGE(PG8_SA(0, 1), a2 + hstep, voffA);
;             PG8_WAIT_V(8); PG8_WAIT_L(0); PG8_BAR; PG8_MMA(0, 0, At, B0); PG8_MMA(0, 1, At, B1); PG8_BAR; PG8_SCHED;
;             PG8_LDA(At, 1, 1); PG8_STAGE(PG8_SB(1, 0), b3, voffB); PG8_STAGE(PG8_SB(1, 1), b3 + hstep, voffB); PG8_STAGE(PG8_SA(1, 0), a3, voffA);
;             PG8_WAIT_V(8); PG8_WAIT_L(0); PG8_BAR; PG8_MMA(1, 0, At, B0); PG8_MMA(1, 1, At, B1); PG8_BAR; PG8_SCHED;
	s_setprio 0
	s_add_i32 s72, 0, 0x18000
	s_add_i32 s73, 0, 0x1c000
	v_add_u32_e32 v140, s72, v216
	v_add_u32_e32 v156, s73, v216
	ds_read_b128 v[128:131], v140
	ds_read_b128 v[132:135], v140 offset:1024
	ds_read_b128 v[136:139], v140 offset:2048
	ds_read_b128 v[140:143], v140 offset:3072
	ds_read_b128 v[144:147], v156
	ds_read_b128 v[148:151], v156 offset:1024
	ds_read_b128 v[152:155], v156 offset:2048
	ds_read_b128 v[156:159], v156 offset:3072
	s_add_u32 s16, s16, 0x80000
	s_addc_u32 s17, s17, 0
	s_mov_b32 m0, s29
	ds_read_b128 v[160:163], v220 offset:32768
	ds_read_b128 v[164:167], v220 offset:33792
	ds_read_b128 v[168:171], v220 offset:34816
	ds_read_b128 v[172:175], v220 offset:35840
	ds_read_b128 v[196:199], v220 offset:36864
	ds_read_b128 v[202:205], v220 offset:37888
	ds_read_b128 v[206:209], v220 offset:38912
	ds_read_b128 v[232:235], v220 offset:39936
	global_load_lds_dwordx4 v180, s[16:17]
	s_mov_b32 m0, s34
	s_nop 0
	global_load_lds_dwordx4 v184, s[16:17]
	s_waitcnt vmcnt(8)
	s_waitcnt lgkmcnt(0)
	s_setprio 1
	s_barrier
	v_mfma_f32_16x16x32_bf16 v[124:127], v[128:131], v[160:163], v[124:127]
	v_mfma_f32_16x16x32_bf16 v[124:127], v[132:135], v[164:167], v[124:127]
	v_mfma_f32_16x16x32_bf16 v[108:111], v[128:131], v[168:171], v[108:111]
	v_mfma_f32_16x16x32_bf16 v[108:111], v[132:135], v[172:175], v[108:111]
	v_mfma_f32_16x16x32_bf16 v[92:95], v[128:131], v[196:199], v[92:95]
	v_mfma_f32_16x16x32_bf16 v[92:95], v[132:135], v[202:205], v[92:95]
	v_mfma_f32_16x16x32_bf16 v[76:79], v[128:131], v[206:209], v[76:79]
	v_mfma_f32_16x16x32_bf16 v[76:79], v[132:135], v[232:235], v[76:79]
	v_mfma_f32_16x16x32_bf16 v[120:123], v[136:139], v[160:163], v[120:123]
	v_mfma_f32_16x16x32_bf16 v[120:123], v[140:143], v[164:167], v[120:123]
	v_mfma_f32_16x16x32_bf16 v[104:107], v[136:139], v[168:171], v[104:107]
	v_mfma_f32_16x16x32_bf16 v[104:107], v[140:143], v[172:175], v[104:107]
	v_mfma_f32_16x16x32_bf16 v[88:91], v[136:139], v[196:199], v[88:91]
	v_mfma_f32_16x16x32_bf16 v[88:91], v[140:143], v[202:205], v[88:91]
	v_mfma_f32_16x16x32_bf16 v[72:75], v[136:139], v[206:209], v[72:75]
	v_mfma_f32_16x16x32_bf16 v[72:75], v[140:143], v[232:235], v[72:75]
	s_setprio 0
	s_setprio 1
	v_mfma_f32_16x16x32_bf16 v[116:119], v[144:147], v[160:163], v[116:119]
	v_mfma_f32_16x16x32_bf16 v[116:119], v[148:151], v[164:167], v[116:119]
	v_mfma_f32_16x16x32_bf16 v[100:103], v[144:147], v[168:171], v[100:103]
	v_mfma_f32_16x16x32_bf16 v[100:103], v[148:151], v[172:175], v[100:103]
	v_mfma_f32_16x16x32_bf16 v[84:87], v[144:147], v[196:199], v[84:87]
	v_mfma_f32_16x16x32_bf16 v[84:87], v[148:151], v[202:205], v[84:87]
	v_mfma_f32_16x16x32_bf16 v[68:71], v[144:147], v[206:209], v[68:71]
	v_mfma_f32_16x16x32_bf16 v[68:71], v[148:151], v[232:235], v[68:71]
	v_mfma_f32_16x16x32_bf16 v[112:115], v[152:155], v[160:163], v[112:115]
	v_mfma_f32_16x16x32_bf16 v[112:115], v[156:159], v[164:167], v[112:115]
	v_mfma_f32_16x16x32_bf16 v[96:99], v[152:155], v[168:171], v[96:99]
	v_mfma_f32_16x16x32_bf16 v[96:99], v[156:159], v[172:175], v[96:99]
	v_mfma_f32_16x16x32_bf16 v[80:83], v[152:155], v[196:199], v[80:83]
	v_mfma_f32_16x16x32_bf16 v[80:83], v[156:159], v[202:205], v[80:83]
	v_mfma_f32_16x16x32_bf16 v[64:67], v[152:155], v[206:209], v[64:67]
	v_mfma_f32_16x16x32_bf16 v[64:67], v[156:159], v[232:235], v[64:67]
	s_barrier
	s_setprio 0
	s_add_i32 s16, s72, s26
	v_lshl_add_u64 v[222:223], v[222:223], 0, s[36:37]
	s_mov_b32 m0, s16
	ds_read_b128 v[160:163], v220 offset:49152
	ds_read_b128 v[164:167], v220 offset:50176
	ds_read_b128 v[168:171], v220 offset:51200
	ds_read_b128 v[172:175], v220 offset:52224
	ds_read_b128 v[196:199], v220 offset:53248
	ds_read_b128 v[202:205], v220 offset:54272
	ds_read_b128 v[206:209], v220 offset:55296
	ds_read_b128 v[232:235], v220 offset:56320
	global_load_lds_dwordx4 v[222:223], off
	s_add_i32 m0, s16, 0x2000
	s_add_u32 s14, s14, 0x80080
	v_lshl_add_u64 v[222:223], v[228:229], 0, s[36:37]
	s_addc_u32 s15, s15, 0
	s_add_i32 s16, s73, s26
	global_load_lds_dwordx4 v[222:223], off
	s_mov_b32 m0, s16
	s_nop 0
	global_load_lds_dwordx4 v182, s[14:15]
	s_add_i32 m0, s16, 0x2000
	s_nop 0
	global_load_lds_dwordx4 v186, s[14:15]
	v_lshl_add_u64 v[222:223], v[236:237], 0, s[36:37]
	s_mov_b32 m0, s44
	s_nop 0
	global_load_lds_dwordx4 v[222:223], off
	v_lshl_add_u64 v[222:223], v[238:239], 0, s[36:37]
	s_mov_b32 m0, s45
	s_nop 0
	global_load_lds_dwordx4 v[222:223], off
	s_waitcnt vmcnt(8)
	s_waitcnt lgkmcnt(0)
	s_setprio 1
	s_barrier
	v_mfma_f32_16x16x32_bf16 v[60:63], v[128:131], v[160:163], v[60:63]
	v_mfma_f32_16x16x32_bf16 v[60:63], v[132:135], v[164:167], v[60:63]
	v_mfma_f32_16x16x32_bf16 v[44:47], v[128:131], v[168:171], v[44:47]
	v_mfma_f32_16x16x32_bf16 v[44:47], v[132:135], v[172:175], v[44:47]
	v_mfma_f32_16x16x32_bf16 v[28:31], v[128:131], v[196:199], v[28:31]
	v_mfma_f32_16x16x32_bf16 v[28:31], v[132:135], v[202:205], v[28:31]
	v_mfma_f32_16x16x32_bf16 v[12:15], v[128:131], v[206:209], v[12:15]
	v_mfma_f32_16x16x32_bf16 v[12:15], v[132:135], v[232:235], v[12:15]
	v_mfma_f32_16x16x32_bf16 v[56:59], v[136:139], v[160:163], v[56:59]
	v_mfma_f32_16x16x32_bf16 v[56:59], v[140:143], v[164:167], v[56:59]
	v_mfma_f32_16x16x32_bf16 v[40:43], v[136:139], v[168:171], v[40:43]
	v_mfma_f32_16x16x32_bf16 v[40:43], v[140:143], v[172:175], v[40:43]
	v_mfma_f32_16x16x32_bf16 v[24:27], v[136:139], v[196:199], v[24:27]
	v_mfma_f32_16x16x32_bf16 v[24:27], v[140:143], v[202:205], v[24:27]
	v_mfma_f32_16x16x32_bf16 v[8:11], v[136:139], v[206:209], v[8:11]
	v_mfma_f32_16x16x32_bf16 v[8:11], v[140:143], v[232:235], v[8:11]
	s_setprio 0
	s_setprio 1
	v_mfma_f32_16x16x32_bf16 v[52:55], v[144:147], v[160:163], v[52:55]
	v_mfma_f32_16x16x32_bf16 v[52:55], v[148:151], v[164:167], v[52:55]
	v_mfma_f32_16x16x32_bf16 v[36:39], v[144:147], v[168:171], v[36:39]
	v_mfma_f32_16x16x32_bf16 v[36:39], v[148:151], v[172:175], v[36:39]
	v_mfma_f32_16x16x32_bf16 v[20:23], v[144:147], v[196:199], v[20:23]
	v_mfma_f32_16x16x32_bf16 v[20:23], v[148:151], v[202:205], v[20:23]
	v_mfma_f32_16x16x32_bf16 v[4:7], v[144:147], v[206:209], v[4:7]
	v_mfma_f32_16x16x32_bf16 v[4:7], v[148:151], v[232:235], v[4:7]
	v_mfma_f32_16x16x32_bf16 v[48:51], v[152:155], v[160:163], v[48:51]
	v_mfma_f32_16x16x32_bf16 v[48:51], v[156:159], v[164:167], v[48:51]
	v_mfma_f32_16x16x32_bf16 v[32:35], v[152:155], v[168:171], v[32:35]
	v_mfma_f32_16x16x32_bf16 v[32:35], v[156:159], v[172:175], v[32:35]
	v_mfma_f32_16x16x32_bf16 v[16:19], v[152:155], v[196:199], v[16:19]
	v_mfma_f32_16x16x32_bf16 v[16:19], v[156:159], v[202:205], v[16:19]
	v_mfma_f32_16x16x32_bf16 v[0:3], v[152:155], v[206:209], v[0:3]
	v_mfma_f32_16x16x32_bf16 v[0:3], v[156:159], v[232:235], v[0:3]
	s_barrier
	s_setprio 0
	s_add_i32 s71, s71, 2
	s_add_u32 s68, s68, 0x100
	s_addc_u32 s69, s69, 0
	s_add_u32 s67, s67, 0x100
	s_addc_u32 s70, s70, 0
; #define PG8_STAGE(bufoff, gbase, voff) do { _Pragma("unroll") for (int _i = 0; _i < 2; ++_i) \
;         __builtin_amdgcn_global_load_lds((const unsigned*)((const char*)(gbase) + (voff)[_i]), (PG8_LAS unsigned*)(lds + (bufoff) + ldsw + _i * 8192), 16, 0, 0); } while (0)
; #define PG8_LDA(dst, b, h) do { _Pragma("unroll") for (int m = 0; m < 4; ++m) _Pragma("unroll") for (int k = 0; k < 2; ++k) dst[m][k] = *(const PG8_LAS bf16x8*)(lds + PG8_SA(b, h) + aoff + m * 2048 + k * 1024); } while (0)
; #define PG8_LDB(dst, b, h) do { _Pragma("unroll") for (int n = 0; n < 2; ++n) _Pragma("unroll") for (int k = 0; k < 2; ++k) dst[n][k] = *(const PG8_LAS bf16x8*)(lds + PG8_SB(b, h) + boff + n * 2048 + k * 1024); } while (0)
; #define PG8_MMA(ai, bj, At, Bt) do { __builtin_amdgcn_s_setprio(1); _Pragma("unroll") for (int m = 0; m < 4; ++m) _Pragma("unroll") for (int n = 0; n < 2; ++n) _Pragma("unroll") for (int k = 0; k < 2; ++k) \
;         acc[ai][bj][m][n] = __builtin_amdgcn_mfma_f32_16x16x32_bf16(Bt[n][k], At[m][k], acc[ai][bj][m][n], 0, 0, 0); __builtin_amdgcn_s_setprio(0); } while (0)
; #define PG8_WAIT_V(n) asm volatile("s_waitcnt vmcnt(" #n ")" ::: "memory")
; #define PG8_WAIT_L(n) asm volatile("s_waitcnt lgkmcnt(" #n ")" ::: "memory")
; #define PG8_BAR __builtin_amdgcn_s_barrier()
; #define PG8_SCHED __builtin_amdgcn_sched_barrier(0)
; template <class Epi, class Sched, bool ALIGN_EPI = false, bool SP2 = false, bool DUAL = false>
; __device__ __forceinline__ void gemm_phase(PG8_LAS unsigned char* lds, const Gemm g, const Sched& S, const Epi& E) {
;     ...
;             const char* a2 = last ? nA : cA + (size_t)(t + 2) * kstep; const char* b2 = last ? nB : cB + (size_t)(t + 2) * kstep;
;             const char* a3 = a2 + kstep; const char* b3 = b2 + kstep;
;             if (last && has_next) S.a_ready(nxt);
;             if constexpr (SP2) {
;             PG8_LDB(B0, 0, 0); PG8_LDB(B1, 0, 1); PG8_SCHED; PG8_LDA(At, 0, 0); PG8_STAGE(PG8_SA(1, 1), a1 + hstep, voffA);
;             PG8_WAIT_V(8); PG8_WAIT_L(0); PG8_BAR; PG8_MMA(0, 0, At, B0); PG8_MMA(0, 1, At, B1); PG8_BAR; PG8_SCHED;
;             PG8_LDA(At, 0, 1); PG8_STAGE(PG8_SB(0, 0), b2, voffB); PG8_STAGE(PG8_SB(0, 1), b2 + hstep, voffB); PG8_STAGE(PG8_SA(0, 0), a2, voffA);
;             PG8_WAIT_V(8); PG8_WAIT_L(0); PG8_BAR; PG8_MMA(1, 0, At, B0); PG8_MMA(1, 1, At, B1); PG8_BAR; PG8_SCHED;
.LBB0_896:
	ds_read_b128 v[128:131], v218
	ds_read_b128 v[132:135], v218 offset:1024
	ds_read_b128 v[136:139], v218 offset:2048
	ds_read_b128 v[140:143], v218 offset:3072
	ds_read_b128 v[144:147], v219
	ds_read_b128 v[148:151], v219 offset:1024
	ds_read_b128 v[152:155], v219 offset:2048
	ds_read_b128 v[156:159], v219 offset:3072
	s_add_u32 s14, s68, 0xfff80080
	s_addc_u32 s15, s69, -1
	s_cmp_eq_u32 s71, 28
	s_cselect_b32 s17, s18, s15
	s_cselect_b32 s16, s19, s14
	s_cselect_b32 s15, s41, s70
	s_cselect_b32 s14, s61, s67
	s_add_i32 m0, s27, 0xc000
	ds_read_b128 v[160:163], v220
	ds_read_b128 v[164:167], v220 offset:1024
	ds_read_b128 v[168:171], v220 offset:2048
	ds_read_b128 v[172:175], v220 offset:3072
	ds_read_b128 v[196:199], v220 offset:4096
	ds_read_b128 v[202:205], v220 offset:5120
	ds_read_b128 v[206:209], v220 offset:6144
	ds_read_b128 v[232:235], v220 offset:7168
	global_load_lds_dwordx4 v188, s[68:69]
	s_add_i32 m0, s27, 0xe000
	s_nop 0
	global_load_lds_dwordx4 v190, s[68:69]
	s_waitcnt vmcnt(8)
	s_waitcnt lgkmcnt(0)
	s_setprio 1
	s_barrier
	v_mfma_f32_16x16x32_bf16 v[124:127], v[128:131], v[160:163], v[124:127]
	v_mfma_f32_16x16x32_bf16 v[124:127], v[132:135], v[164:167], v[124:127]
	v_mfma_f32_16x16x32_bf16 v[108:111], v[128:131], v[168:171], v[108:111]
	v_mfma_f32_16x16x32_bf16 v[108:111], v[132:135], v[172:175], v[108:111]
	v_mfma_f32_16x16x32_bf16 v[92:95], v[128:131], v[196:199], v[92:95]
	v_mfma_f32_16x16x32_bf16 v[92:95], v[132:135], v[202:205], v[92:95]
	v_mfma_f32_16x16x32_bf16 v[76:79], v[128:131], v[206:209], v[76:79]
	v_mfma_f32_16x16x32_bf16 v[76:79], v[132:135], v[232:235], v[76:79]
	v_mfma_f32_16x16x32_bf16 v[120:123], v[136:139], v[160:163], v[120:123]
	v_mfma_f32_16x16x32_bf16 v[120:123], v[140:143], v[164:167], v[120:123]
	v_mfma_f32_16x16x32_bf16 v[104:107], v[136:139], v[168:171], v[104:107]
	v_mfma_f32_16x16x32_bf16 v[104:107], v[140:143], v[172:175], v[104:107]
	v_mfma_f32_16x16x32_bf16 v[88:91], v[136:139], v[196:199], v[88:91]
	v_mfma_f32_16x16x32_bf16 v[88:91], v[140:143], v[202:205], v[88:91]
	v_mfma_f32_16x16x32_bf16 v[72:75], v[136:139], v[206:209], v[72:75]
	v_mfma_f32_16x16x32_bf16 v[72:75], v[140:143], v[232:235], v[72:75]
	s_setprio 0
	s_setprio 1
	v_mfma_f32_16x16x32_bf16 v[116:119], v[144:147], v[160:163], v[116:119]
	v_mfma_f32_16x16x32_bf16 v[116:119], v[148:151], v[164:167], v[116:119]
	v_mfma_f32_16x16x32_bf16 v[100:103], v[144:147], v[168:171], v[100:103]
	v_mfma_f32_16x16x32_bf16 v[100:103], v[148:151], v[172:175], v[100:103]
	v_mfma_f32_16x16x32_bf16 v[84:87], v[144:147], v[196:199], v[84:87]
	v_mfma_f32_16x16x32_bf16 v[84:87], v[148:151], v[202:205], v[84:87]
	v_mfma_f32_16x16x32_bf16 v[68:71], v[144:147], v[206:209], v[68:71]
	v_mfma_f32_16x16x32_bf16 v[68:71], v[148:151], v[232:235], v[68:71]
	v_mfma_f32_16x16x32_bf16 v[112:115], v[152:155], v[160:163], v[112:115]
	v_mfma_f32_16x16x32_bf16 v[112:115], v[156:159], v[164:167], v[112:115]
	v_mfma_f32_16x16x32_bf16 v[96:99], v[152:155], v[168:171], v[96:99]
	v_mfma_f32_16x16x32_bf16 v[96:99], v[156:159], v[172:175], v[96:99]
	v_mfma_f32_16x16x32_bf16 v[80:83], v[152:155], v[196:199], v[80:83]
	v_mfma_f32_16x16x32_bf16 v[80:83], v[156:159], v[202:205], v[80:83]
	v_mfma_f32_16x16x32_bf16 v[64:67], v[152:155], v[206:209], v[64:67]
	v_mfma_f32_16x16x32_bf16 v[64:67], v[156:159], v[232:235], v[64:67]
	s_barrier
	s_setprio 0
	s_add_i32 s72, s48, s26
	v_lshl_add_u64 v[222:223], s[14:15], 0, v[182:183]
	s_mov_b32 m0, s72
	ds_read_b128 v[160:163], v220 offset:16384
	ds_read_b128 v[164:167], v220 offset:17408
	ds_read_b128 v[168:171], v220 offset:18432
	ds_read_b128 v[172:175], v220 offset:19456
	ds_read_b128 v[196:199], v220 offset:20480
	ds_read_b128 v[202:205], v220 offset:21504
	ds_read_b128 v[206:209], v220 offset:22528
	ds_read_b128 v[232:235], v220 offset:23552
	global_load_lds_dwordx4 v[222:223], off
	s_add_i32 m0, s72, 0x2000
	s_add_u32 s72, s14, 0x80000
	v_lshl_add_u64 v[228:229], s[14:15], 0, v[186:187]
	s_addc_u32 s73, s15, 0
	s_add_i32 s74, s49, s26
	global_load_lds_dwordx4 v[228:229], off
	s_mov_b32 m0, s74
	v_lshl_add_u64 v[238:239], s[16:17], 0, v[184:185]
	global_load_lds_dwordx4 v182, s[72:73]
	s_add_i32 m0, s74, 0x2000
	s_nop 0
	global_load_lds_dwordx4 v186, s[72:73]
	v_lshl_add_u64 v[236:237], s[16:17], 0, v[180:181]
	s_mov_b32 m0, s27
	s_nop 0
	global_load_lds_dwordx4 v[236:237], off
	s_mov_b32 m0, s28
	s_nop 0
	global_load_lds_dwordx4 v[238:239], off
	s_waitcnt vmcnt(8)
	s_waitcnt lgkmcnt(0)
	s_setprio 1
	s_barrier
	v_mfma_f32_16x16x32_bf16 v[60:63], v[128:131], v[160:163], v[60:63]
	v_mfma_f32_16x16x32_bf16 v[60:63], v[132:135], v[164:167], v[60:63]
	v_mfma_f32_16x16x32_bf16 v[44:47], v[128:131], v[168:171], v[44:47]
	v_mfma_f32_16x16x32_bf16 v[44:47], v[132:135], v[172:175], v[44:47]
	v_mfma_f32_16x16x32_bf16 v[28:31], v[128:131], v[196:199], v[28:31]
	v_mfma_f32_16x16x32_bf16 v[28:31], v[132:135], v[202:205], v[28:31]
	v_mfma_f32_16x16x32_bf16 v[12:15], v[128:131], v[206:209], v[12:15]
	v_mfma_f32_16x16x32_bf16 v[12:15], v[132:135], v[232:235], v[12:15]
	v_mfma_f32_16x16x32_bf16 v[56:59], v[136:139], v[160:163], v[56:59]
	v_mfma_f32_16x16x32_bf16 v[56:59], v[140:143], v[164:167], v[56:59]
	v_mfma_f32_16x16x32_bf16 v[40:43], v[136:139], v[168:171], v[40:43]
	v_mfma_f32_16x16x32_bf16 v[40:43], v[140:143], v[172:175], v[40:43]
	v_mfma_f32_16x16x32_bf16 v[24:27], v[136:139], v[196:199], v[24:27]
	v_mfma_f32_16x16x32_bf16 v[24:27], v[140:143], v[202:205], v[24:27]
	v_mfma_f32_16x16x32_bf16 v[8:11], v[136:139], v[206:209], v[8:11]
	v_mfma_f32_16x16x32_bf16 v[8:11], v[140:143], v[232:235], v[8:11]
	s_setprio 0
	s_setprio 1
	v_mfma_f32_16x16x32_bf16 v[52:55], v[144:147], v[160:163], v[52:55]
	v_mfma_f32_16x16x32_bf16 v[52:55], v[148:151], v[164:167], v[52:55]
	v_mfma_f32_16x16x32_bf16 v[36:39], v[144:147], v[168:171], v[36:39]
	v_mfma_f32_16x16x32_bf16 v[36:39], v[148:151], v[172:175], v[36:39]
	v_mfma_f32_16x16x32_bf16 v[20:23], v[144:147], v[196:199], v[20:23]
	v_mfma_f32_16x16x32_bf16 v[20:23], v[148:151], v[202:205], v[20:23]
	v_mfma_f32_16x16x32_bf16 v[4:7], v[144:147], v[206:209], v[4:7]
	v_mfma_f32_16x16x32_bf16 v[4:7], v[148:151], v[232:235], v[4:7]
	v_mfma_f32_16x16x32_bf16 v[48:51], v[152:155], v[160:163], v[48:51]
	v_mfma_f32_16x16x32_bf16 v[48:51], v[156:159], v[164:167], v[48:51]
	v_mfma_f32_16x16x32_bf16 v[32:35], v[152:155], v[168:171], v[32:35]
	v_mfma_f32_16x16x32_bf16 v[32:35], v[156:159], v[172:175], v[32:35]
	v_mfma_f32_16x16x32_bf16 v[16:19], v[152:155], v[196:199], v[16:19]
	v_mfma_f32_16x16x32_bf16 v[16:19], v[156:159], v[202:205], v[16:19]
	v_mfma_f32_16x16x32_bf16 v[0:3], v[152:155], v[206:209], v[0:3]
	v_mfma_f32_16x16x32_bf16 v[0:3], v[156:159], v[232:235], v[0:3]
	s_barrier
; #define PG8_STAGE(bufoff, gbase, voff) do { _Pragma("unroll") for (int _i = 0; _i < 2; ++_i) \
;         __builtin_amdgcn_global_load_lds((const unsigned*)((const char*)(gbase) + (voff)[_i]), (PG8_LAS unsigned*)(lds + (bufoff) + ldsw + _i * 8192), 16, 0, 0); } while (0)
; #define PG8_LDA(dst, b, h) do { _Pragma("unroll") for (int m = 0; m < 4; ++m) _Pragma("unroll") for (int k = 0; k < 2; ++k) dst[m][k] = *(const PG8_LAS bf16x8*)(lds + PG8_SA(b, h) + aoff + m * 2048 + k * 1024); } while (0)
; #define PG8_LDB(dst, b, h) do { _Pragma("unroll") for (int n = 0; n < 2; ++n) _Pragma("unroll") for (int k = 0; k < 2; ++k) dst[n][k] = *(const PG8_LAS bf16x8*)(lds + PG8_SB(b, h) + boff + n * 2048 + k * 1024); } while (0)
; #define PG8_MMA(ai, bj, At, Bt) do { __builtin_amdgcn_s_setprio(1); _Pragma("unroll") for (int m = 0; m < 4; ++m) _Pragma("unroll") for (int n = 0; n < 2; ++n) _Pragma("unroll") for (int k = 0; k < 2; ++k) \
;         acc[ai][bj][m][n] = __builtin_amdgcn_mfma_f32_16x16x32_bf16(Bt[n][k], At[m][k], acc[ai][bj][m][n], 0, 0, 0); __builtin_amdgcn_s_setprio(0); } while (0)
; #define PG8_WAIT_V(n) asm volatile("s_waitcnt vmcnt(" #n ")" ::: "memory")
; #define PG8_WAIT_L(n) asm volatile("s_waitcnt lgkmcnt(" #n ")" ::: "memory")
; #define PG8_BAR __builtin_amdgcn_s_barrier()
; #define PG8_SCHED __builtin_amdgcn_sched_barrier(0)
; template <class Epi, class Sched, bool ALIGN_EPI = false, bool SP2 = false, bool DUAL = false>
; __device__ __forceinline__ void gemm_phase(PG8_LAS unsigned char* lds, const Gemm g, const Sched& S, const Epi& E) {
;     ...
;             PG8_LDB(B0, 1, 0); PG8_LDB(B1, 1, 1); PG8_SCHED; PG8_LDA(At, 1, 0); PG8_STAGE(PG8_SA(0, 1), a2 + hstep, voffA);
;             PG8_WAIT_V(8); PG8_WAIT_L(0); PG8_BAR; PG8_MMA(0, 0, At, B0); PG8_MMA(0, 1, At, B1); PG8_BAR; PG8_SCHED;
;             PG8_LDA(At, 1, 1); PG8_STAGE(PG8_SB(1, 0), b3, voffB); PG8_STAGE(PG8_SB(1, 1), b3 + hstep, voffB); PG8_STAGE(PG8_SA(1, 0), a3, voffA);
;             PG8_WAIT_V(8); PG8_WAIT_L(0); PG8_BAR; PG8_MMA(1, 0, At, B0); PG8_MMA(1, 1, At, B1); PG8_BAR; PG8_SCHED;
	s_setprio 0
	s_add_i32 s72, 0, 0x18000
	s_add_i32 s73, 0, 0x1c000
	v_add_u32_e32 v140, s72, v216
	v_add_u32_e32 v156, s73, v216
	ds_read_b128 v[128:131], v140
	ds_read_b128 v[132:135], v140 offset:1024
	ds_read_b128 v[136:139], v140 offset:2048
	ds_read_b128 v[140:143], v140 offset:3072
	ds_read_b128 v[144:147], v156
	ds_read_b128 v[148:151], v156 offset:1024
	ds_read_b128 v[152:155], v156 offset:2048
	ds_read_b128 v[156:159], v156 offset:3072
	s_add_u32 s16, s16, 0x80000
	s_addc_u32 s17, s17, 0
	s_mov_b32 m0, s29
	ds_read_b128 v[160:163], v220 offset:32768
	ds_read_b128 v[164:167], v220 offset:33792
	ds_read_b128 v[168:171], v220 offset:34816
	ds_read_b128 v[172:175], v220 offset:35840
	ds_read_b128 v[196:199], v220 offset:36864
	ds_read_b128 v[202:205], v220 offset:37888
	ds_read_b128 v[206:209], v220 offset:38912
	ds_read_b128 v[232:235], v220 offset:39936
	global_load_lds_dwordx4 v180, s[16:17]
	s_mov_b32 m0, s34
	s_nop 0
	global_load_lds_dwordx4 v184, s[16:17]
	s_waitcnt vmcnt(8)
	s_waitcnt lgkmcnt(0)
	s_setprio 1
	s_barrier
	v_mfma_f32_16x16x32_bf16 v[124:127], v[128:131], v[160:163], v[124:127]
	v_mfma_f32_16x16x32_bf16 v[124:127], v[132:135], v[164:167], v[124:127]
	v_mfma_f32_16x16x32_bf16 v[108:111], v[128:131], v[168:171], v[108:111]
	v_mfma_f32_16x16x32_bf16 v[108:111], v[132:135], v[172:175], v[108:111]
	v_mfma_f32_16x16x32_bf16 v[92:95], v[128:131], v[196:199], v[92:95]
	v_mfma_f32_16x16x32_bf16 v[92:95], v[132:135], v[202:205], v[92:95]
	v_mfma_f32_16x16x32_bf16 v[76:79], v[128:131], v[206:209], v[76:79]
	v_mfma_f32_16x16x32_bf16 v[76:79], v[132:135], v[232:235], v[76:79]
	v_mfma_f32_16x16x32_bf16 v[120:123], v[136:139], v[160:163], v[120:123]
	v_mfma_f32_16x16x32_bf16 v[120:123], v[140:143], v[164:167], v[120:123]
	v_mfma_f32_16x16x32_bf16 v[104:107], v[136:139], v[168:171], v[104:107]
	v_mfma_f32_16x16x32_bf16 v[104:107], v[140:143], v[172:175], v[104:107]
	v_mfma_f32_16x16x32_bf16 v[88:91], v[136:139], v[196:199], v[88:91]
	v_mfma_f32_16x16x32_bf16 v[88:91], v[140:143], v[202:205], v[88:91]
	v_mfma_f32_16x16x32_bf16 v[72:75], v[136:139], v[206:209], v[72:75]
	v_mfma_f32_16x16x32_bf16 v[72:75], v[140:143], v[232:235], v[72:75]
	s_setprio 0
	s_setprio 1
	v_mfma_f32_16x16x32_bf16 v[116:119], v[144:147], v[160:163], v[116:119]
	v_mfma_f32_16x16x32_bf16 v[116:119], v[148:151], v[164:167], v[116:119]
	v_mfma_f32_16x16x32_bf16 v[100:103], v[144:147], v[168:171], v[100:103]
	v_mfma_f32_16x16x32_bf16 v[100:103], v[148:151], v[172:175], v[100:103]
	v_mfma_f32_16x16x32_bf16 v[84:87], v[144:147], v[196:199], v[84:87]
	v_mfma_f32_16x16x32_bf16 v[84:87], v[148:151], v[202:205], v[84:87]
	v_mfma_f32_16x16x32_bf16 v[68:71], v[144:147], v[206:209], v[68:71]
	v_mfma_f32_16x16x32_bf16 v[68:71], v[148:151], v[232:235], v[68:71]
	v_mfma_f32_16x16x32_bf16 v[112:115], v[152:155], v[160:163], v[112:115]
	v_mfma_f32_16x16x32_bf16 v[112:115], v[156:159], v[164:167], v[112:115]
	v_mfma_f32_16x16x32_bf16 v[96:99], v[152:155], v[168:171], v[96:99]
	v_mfma_f32_16x16x32_bf16 v[96:99], v[156:159], v[172:175], v[96:99]
	v_mfma_f32_16x16x32_bf16 v[80:83], v[152:155], v[196:199], v[80:83]
	v_mfma_f32_16x16x32_bf16 v[80:83], v[156:159], v[202:205], v[80:83]
	v_mfma_f32_16x16x32_bf16 v[64:67], v[152:155], v[206:209], v[64:67]
	v_mfma_f32_16x16x32_bf16 v[64:67], v[156:159], v[232:235], v[64:67]
	s_barrier
	s_setprio 0
	s_add_i32 s16, s72, s26
	v_lshl_add_u64 v[222:223], v[222:223], 0, s[36:37]
	s_mov_b32 m0, s16
	ds_read_b128 v[160:163], v220 offset:49152
	ds_read_b128 v[164:167], v220 offset:50176
	ds_read_b128 v[168:171], v220 offset:51200
	ds_read_b128 v[172:175], v220 offset:52224
	ds_read_b128 v[196:199], v220 offset:53248
	ds_read_b128 v[202:205], v220 offset:54272
	ds_read_b128 v[206:209], v220 offset:55296
	ds_read_b128 v[232:235], v220 offset:56320
	global_load_lds_dwordx4 v[222:223], off
	s_add_i32 m0, s16, 0x2000
	s_add_u32 s14, s14, 0x80080
	v_lshl_add_u64 v[222:223], v[228:229], 0, s[36:37]
	s_addc_u32 s15, s15, 0
	s_add_i32 s16, s73, s26
	global_load_lds_dwordx4 v[222:223], off
	s_mov_b32 m0, s16
	s_nop 0
	global_load_lds_dwordx4 v182, s[14:15]
	s_add_i32 m0, s16, 0x2000
	s_nop 0
	global_load_lds_dwordx4 v186, s[14:15]
	v_lshl_add_u64 v[222:223], v[236:237], 0, s[36:37]
	s_mov_b32 m0, s44
	s_nop 0
	global_load_lds_dwordx4 v[222:223], off
	v_lshl_add_u64 v[222:223], v[238:239], 0, s[36:37]
	s_mov_b32 m0, s45
	s_nop 0
	global_load_lds_dwordx4 v[222:223], off
	s_waitcnt vmcnt(8)
	s_waitcnt lgkmcnt(0)
	s_setprio 1
	s_barrier
	v_mfma_f32_16x16x32_bf16 v[60:63], v[128:131], v[160:163], v[60:63]
	v_mfma_f32_16x16x32_bf16 v[60:63], v[132:135], v[164:167], v[60:63]
	v_mfma_f32_16x16x32_bf16 v[44:47], v[128:131], v[168:171], v[44:47]
	v_mfma_f32_16x16x32_bf16 v[44:47], v[132:135], v[172:175], v[44:47]
	v_mfma_f32_16x16x32_bf16 v[28:31], v[128:131], v[196:199], v[28:31]
	v_mfma_f32_16x16x32_bf16 v[28:31], v[132:135], v[202:205], v[28:31]
	v_mfma_f32_16x16x32_bf16 v[12:15], v[128:131], v[206:209], v[12:15]
	v_mfma_f32_16x16x32_bf16 v[12:15], v[132:135], v[232:235], v[12:15]
	v_mfma_f32_16x16x32_bf16 v[56:59], v[136:139], v[160:163], v[56:59]
	v_mfma_f32_16x16x32_bf16 v[56:59], v[140:143], v[164:167], v[56:59]
	v_mfma_f32_16x16x32_bf16 v[40:43], v[136:139], v[168:171], v[40:43]
	v_mfma_f32_16x16x32_bf16 v[40:43], v[140:143], v[172:175], v[40:43]
	v_mfma_f32_16x16x32_bf16 v[24:27], v[136:139], v[196:199], v[24:27]
	v_mfma_f32_16x16x32_bf16 v[24:27], v[140:143], v[202:205], v[24:27]
	v_mfma_f32_16x16x32_bf16 v[8:11], v[136:139], v[206:209], v[8:11]
	v_mfma_f32_16x16x32_bf16 v[8:11], v[140:143], v[232:235], v[8:11]
	s_setprio 0
	s_setprio 1
	v_mfma_f32_16x16x32_bf16 v[52:55], v[144:147], v[160:163], v[52:55]
	v_mfma_f32_16x16x32_bf16 v[52:55], v[148:151], v[164:167], v[52:55]
	v_mfma_f32_16x16x32_bf16 v[36:39], v[144:147], v[168:171], v[36:39]
	v_mfma_f32_16x16x32_bf16 v[36:39], v[148:151], v[172:175], v[36:39]
	v_mfma_f32_16x16x32_bf16 v[20:23], v[144:147], v[196:199], v[20:23]
	v_mfma_f32_16x16x32_bf16 v[20:23], v[148:151], v[202:205], v[20:23]
	v_mfma_f32_16x16x32_bf16 v[4:7], v[144:147], v[206:209], v[4:7]
	v_mfma_f32_16x16x32_bf16 v[4:7], v[148:151], v[232:235], v[4:7]
	v_mfma_f32_16x16x32_bf16 v[48:51], v[152:155], v[160:163], v[48:51]
	v_mfma_f32_16x16x32_bf16 v[48:51], v[156:159], v[164:167], v[48:51]
	v_mfma_f32_16x16x32_bf16 v[32:35], v[152:155], v[168:171], v[32:35]
	v_mfma_f32_16x16x32_bf16 v[32:35], v[156:159], v[172:175], v[32:35]
	v_mfma_f32_16x16x32_bf16 v[16:19], v[152:155], v[196:199], v[16:19]
	v_mfma_f32_16x16x32_bf16 v[16:19], v[156:159], v[202:205], v[16:19]
	v_mfma_f32_16x16x32_bf16 v[0:3], v[152:155], v[206:209], v[0:3]
	v_mfma_f32_16x16x32_bf16 v[0:3], v[156:159], v[232:235], v[0:3]
	s_barrier
	s_setprio 0
	s_add_i32 s71, s71, 2
	s_add_u32 s68, s68, 0x100
	s_addc_u32 s69, s69, 0
	s_add_u32 s67, s67, 0x100
	s_addc_u32 s70, s70, 0
	s_cmp_gt_u32 s71, 29
	s_cbranch_scc0 .LBB0_896
	s_and_b64 vcc, exec, s[38:39]
	s_cbranch_vccz .LBB0_899
	s_barrier

;     __device__ bool next(int i, Unit& u) const { if (!base.next(i >> 1, u)) return false; u.sub = i & 1; return true; }
; #define PG8_STAGE(bufoff, gbase, voff) do { _Pragma("unroll") for (int _i = 0; _i < 2; ++_i) \
;         __builtin_amdgcn_global_load_lds((const unsigned*)((const char*)(gbase) + (voff)[_i]), (PG8_LAS unsigned*)(lds + (bufoff) + ldsw + _i * 8192), 16, 0, 0); } while (0)
; #define PG8_LDA(dst, b, h) do { _Pragma("unroll") for (int m = 0; m < 4; ++m) _Pragma("unroll") for (int k = 0; k < 2; ++k) dst[m][k] = *(const PG8_LAS bf16x8*)(lds + PG8_SA(b, h) + aoff + m * 2048 + k * 1024); } while (0)
; #define PG8_LDB(dst, b, h) do { _Pragma("unroll") for (int n = 0; n < 2; ++n) _Pragma("unroll") for (int k = 0; k < 2; ++k) dst[n][k] = *(const PG8_LAS bf16x8*)(lds + PG8_SB(b, h) + boff + n * 2048 + k * 1024); } while (0)
; #define PG8_WAIT_V(n) asm volatile("s_waitcnt vmcnt(" #n ")" ::: "memory")
; template <class Epi, class Sched, bool ALIGN_EPI = false, bool SP2 = false, bool DUAL = false>
; __device__ __forceinline__ void gemm_phase(PG8_LAS unsigned char* lds, const Gemm g, const Sched& S, const Epi& E) {
;     ...
;         const bool has_next = S.next(ui + 1, nxt);
;         const char* nA = has_next ? (const char*)((DUAL && nxt.sub) ? g.A2 : g.A) + (size_t)nxt.pm * tstep : cA; const char* nB = has_next ? (const char*)((DUAL && nxt.sub) ? g.Bt2 : g.Bt) + (size_t)nxt.pn * tstep : cB;
;         for (int t = 0; t < nt; t += 2) {
;             const bool last = (t == nt - 2);
;             const char* a1 = cA + (size_t)(t + 1) * kstep;
;             const char* a2 = last ? nA : cA + (size_t)(t + 2) * kstep; const char* b2 = last ? nB : cB + (size_t)(t + 2) * kstep;
;             const char* a3 = a2 + kstep; const char* b3 = b2 + kstep;
;             if (last && has_next) S.a_ready(nxt);
;             if constexpr (SP2) {
;             PG8_LDB(B0, 0, 0); PG8_LDB(B1, 0, 1); PG8_SCHED; PG8_LDA(At, 0, 0); PG8_STAGE(PG8_SA(1, 1), a1 + hstep, voffA);
;             PG8_WAIT_V(8); PG8_WAIT_L(0); PG8_BAR; PG8_MMA(0, 0, At, B0); PG8_MMA(0, 1, At, B1); PG8_BAR; PG8_SCHED;
;             PG8_LDA(At, 0, 1); PG8_STAGE(PG8_SB(0, 0), b2, voffB); PG8_STAGE(PG8_SB(0, 1), b2 + hstep, voffB); PG8_STAGE(PG8_SA(0, 0), a2, voffA);
;             PG8_WAIT_V(8); PG8_WAIT_L(0); PG8_BAR; PG8_MMA(1, 0, At, B0); PG8_MMA(1, 1, At, B1); PG8_BAR; PG8_SCHED;
.LBB0_991:
	s_ashr_i32 s25, s24, 31
	s_lshl_b64 s[28:29], s[24:25], 20
	s_add_u32 s30, s19, s28
	s_addc_u32 s31, s21, s29
	s_and_b64 s[28:29], s[4:5], exec
	s_cselect_b32 s25, s31, s27
	s_cselect_b32 s28, s30, s26
	s_ashr_i32 s23, s22, 31
	s_lshl_b64 s[36:37], s[22:23], 20
	s_add_u32 s36, s8, s36
	s_addc_u32 s37, s9, s37
	s_and_b64 s[40:41], s[4:5], exec
	s_cselect_b32 s23, s37, s15
	s_cselect_b32 s29, s36, s14
	s_add_u32 s40, s26, 0x80080
	s_addc_u32 s41, s27, 0
	s_add_u32 s63, s14, 0x100
	s_addc_u32 s64, s15, 0
	s_mov_b32 s65, -2
	s_add_u32 s14, s40, 0xfff80080
	s_addc_u32 s15, s41, -1
	s_cmp_eq_u32 s65, 28
	s_cselect_b32 s27, s25, s15
	s_cselect_b32 s26, s28, s14
	s_cselect_b32 s15, s23, s64
	s_cselect_b32 s14, s29, s63
	s_waitcnt vmcnt(8)
	s_waitcnt lgkmcnt(0)
	s_setprio 1
	s_barrier
	v_mfma_f32_16x16x32_bf16 v[124:127], v[128:131], v[160:163], 0
	v_mfma_f32_16x16x32_bf16 v[124:127], v[132:135], v[164:167], v[124:127]
	v_mfma_f32_16x16x32_bf16 v[108:111], v[128:131], v[188:191], 0
	v_mfma_f32_16x16x32_bf16 v[108:111], v[132:135], v[192:195], v[108:111]
	v_mfma_f32_16x16x32_bf16 v[92:95], v[128:131], v[196:199], 0
	v_mfma_f32_16x16x32_bf16 v[92:95], v[132:135], v[202:205], v[92:95]
	v_mfma_f32_16x16x32_bf16 v[76:79], v[128:131], v[206:209], 0
	v_mfma_f32_16x16x32_bf16 v[76:79], v[132:135], v[220:223], v[76:79]
	v_mfma_f32_16x16x32_bf16 v[120:123], v[136:139], v[160:163], 0
	v_mfma_f32_16x16x32_bf16 v[120:123], v[140:143], v[164:167], v[120:123]
	v_mfma_f32_16x16x32_bf16 v[104:107], v[136:139], v[188:191], 0
	v_mfma_f32_16x16x32_bf16 v[104:107], v[140:143], v[192:195], v[104:107]
	v_mfma_f32_16x16x32_bf16 v[88:91], v[136:139], v[196:199], 0
	v_mfma_f32_16x16x32_bf16 v[88:91], v[140:143], v[202:205], v[88:91]
	v_mfma_f32_16x16x32_bf16 v[72:75], v[136:139], v[206:209], 0
	v_mfma_f32_16x16x32_bf16 v[72:75], v[140:143], v[220:223], v[72:75]
	s_setprio 0
	s_setprio 1
	v_mfma_f32_16x16x32_bf16 v[116:119], v[144:147], v[160:163], 0
	v_mfma_f32_16x16x32_bf16 v[116:119], v[148:151], v[164:167], v[116:119]
	v_mfma_f32_16x16x32_bf16 v[100:103], v[144:147], v[188:191], 0
	v_mfma_f32_16x16x32_bf16 v[100:103], v[148:151], v[192:195], v[100:103]
	v_mfma_f32_16x16x32_bf16 v[84:87], v[144:147], v[196:199], 0
	v_mfma_f32_16x16x32_bf16 v[84:87], v[148:151], v[202:205], v[84:87]
	v_mfma_f32_16x16x32_bf16 v[68:71], v[144:147], v[206:209], 0
	v_mfma_f32_16x16x32_bf16 v[68:71], v[148:151], v[220:223], v[68:71]
	v_mfma_f32_16x16x32_bf16 v[112:115], v[152:155], v[160:163], 0
	v_mfma_f32_16x16x32_bf16 v[112:115], v[156:159], v[164:167], v[112:115]
	v_mfma_f32_16x16x32_bf16 v[96:99], v[152:155], v[188:191], 0
	v_mfma_f32_16x16x32_bf16 v[96:99], v[156:159], v[192:195], v[96:99]
	v_mfma_f32_16x16x32_bf16 v[80:83], v[152:155], v[196:199], 0
	v_mfma_f32_16x16x32_bf16 v[80:83], v[156:159], v[202:205], v[80:83]
	v_mfma_f32_16x16x32_bf16 v[64:67], v[152:155], v[206:209], 0
	v_mfma_f32_16x16x32_bf16 v[64:67], v[156:159], v[220:223], v[64:67]
	s_barrier
	s_setprio 0
	s_add_i32 m0, s39, 0xc000
	s_nop 0
	global_load_lds_dwordx4 v180, s[40:41]
	s_add_i32 m0, s39, 0xe000
	s_nop 0
	global_load_lds_dwordx4 v182, s[40:41]
	s_add_i32 s66, s50, s34
	v_lshl_add_u64 v[228:229], s[14:15], 0, v[170:171]
	s_mov_b32 m0, s66
	ds_read_b128 v[160:163], v217 offset:16384
	ds_read_b128 v[164:167], v217 offset:17408
	ds_read_b128 v[188:191], v217 offset:18432
	ds_read_b128 v[192:195], v217 offset:19456
	ds_read_b128 v[196:199], v217 offset:20480
	ds_read_b128 v[202:205], v217 offset:21504
	ds_read_b128 v[206:209], v217 offset:22528
	ds_read_b128 v[220:223], v217 offset:23552
	global_load_lds_dwordx4 v[228:229], off
	s_add_i32 m0, s66, 0x2000
	s_add_u32 s66, s14, 0x80000
	v_lshl_add_u64 v[232:233], s[14:15], 0, v[174:175]
	s_addc_u32 s67, s15, 0
	s_add_i32 s68, s51, s34
	global_load_lds_dwordx4 v[232:233], off
	s_mov_b32 m0, s68
	v_lshl_add_u64 v[236:237], s[26:27], 0, v[172:173]
	global_load_lds_dwordx4 v170, s[66:67]
	s_add_i32 m0, s68, 0x2000
	s_nop 0
	global_load_lds_dwordx4 v174, s[66:67]
	v_lshl_add_u64 v[234:235], s[26:27], 0, v[168:169]
	s_mov_b32 m0, s39
	s_nop 0
	global_load_lds_dwordx4 v[234:235], off
	s_mov_b32 m0, s42
	s_nop 0
	global_load_lds_dwordx4 v[236:237], off
	s_waitcnt vmcnt(8)
	s_waitcnt lgkmcnt(0)
	s_setprio 1
	s_barrier
	v_mfma_f32_16x16x32_bf16 v[60:63], v[128:131], v[160:163], 0
	v_mfma_f32_16x16x32_bf16 v[60:63], v[132:135], v[164:167], v[60:63]
	v_mfma_f32_16x16x32_bf16 v[44:47], v[128:131], v[188:191], 0
	v_mfma_f32_16x16x32_bf16 v[44:47], v[132:135], v[192:195], v[44:47]
	v_mfma_f32_16x16x32_bf16 v[28:31], v[128:131], v[196:199], 0
	v_mfma_f32_16x16x32_bf16 v[28:31], v[132:135], v[202:205], v[28:31]
	v_mfma_f32_16x16x32_bf16 v[12:15], v[128:131], v[206:209], 0
	v_mfma_f32_16x16x32_bf16 v[12:15], v[132:135], v[220:223], v[12:15]
	v_mfma_f32_16x16x32_bf16 v[56:59], v[136:139], v[160:163], 0
	v_mfma_f32_16x16x32_bf16 v[56:59], v[140:143], v[164:167], v[56:59]
	v_mfma_f32_16x16x32_bf16 v[40:43], v[136:139], v[188:191], 0
	v_mfma_f32_16x16x32_bf16 v[40:43], v[140:143], v[192:195], v[40:43]
	v_mfma_f32_16x16x32_bf16 v[24:27], v[136:139], v[196:199], 0
	v_mfma_f32_16x16x32_bf16 v[24:27], v[140:143], v[202:205], v[24:27]
	v_mfma_f32_16x16x32_bf16 v[8:11], v[136:139], v[206:209], 0
	v_mfma_f32_16x16x32_bf16 v[8:11], v[140:143], v[220:223], v[8:11]
	s_setprio 0
	s_setprio 1
	v_mfma_f32_16x16x32_bf16 v[52:55], v[144:147], v[160:163], 0
	v_mfma_f32_16x16x32_bf16 v[52:55], v[148:151], v[164:167], v[52:55]
	v_mfma_f32_16x16x32_bf16 v[36:39], v[144:147], v[188:191], 0
	v_mfma_f32_16x16x32_bf16 v[36:39], v[148:151], v[192:195], v[36:39]
	v_mfma_f32_16x16x32_bf16 v[20:23], v[144:147], v[196:199], 0
	v_mfma_f32_16x16x32_bf16 v[20:23], v[148:151], v[202:205], v[20:23]
	v_mfma_f32_16x16x32_bf16 v[4:7], v[144:147], v[206:209], 0
	v_mfma_f32_16x16x32_bf16 v[4:7], v[148:151], v[220:223], v[4:7]
	v_mfma_f32_16x16x32_bf16 v[48:51], v[152:155], v[160:163], 0
	v_mfma_f32_16x16x32_bf16 v[48:51], v[156:159], v[164:167], v[48:51]
	v_mfma_f32_16x16x32_bf16 v[32:35], v[152:155], v[188:191], 0
	v_mfma_f32_16x16x32_bf16 v[32:35], v[156:159], v[192:195], v[32:35]
	v_mfma_f32_16x16x32_bf16 v[16:19], v[152:155], v[196:199], 0
	v_mfma_f32_16x16x32_bf16 v[16:19], v[156:159], v[202:205], v[16:19]
	v_mfma_f32_16x16x32_bf16 v[0:3], v[152:155], v[206:209], 0
	v_mfma_f32_16x16x32_bf16 v[0:3], v[156:159], v[220:223], v[0:3]
	s_barrier
; #define PG8_STAGE(bufoff, gbase, voff) do { _Pragma("unroll") for (int _i = 0; _i < 2; ++_i) \
;         __builtin_amdgcn_global_load_lds((const unsigned*)((const char*)(gbase) + (voff)[_i]), (PG8_LAS unsigned*)(lds + (bufoff) + ldsw + _i * 8192), 16, 0, 0); } while (0)
; #define PG8_LDA(dst, b, h) do { _Pragma("unroll") for (int m = 0; m < 4; ++m) _Pragma("unroll") for (int k = 0; k < 2; ++k) dst[m][k] = *(const PG8_LAS bf16x8*)(lds + PG8_SA(b, h) + aoff + m * 2048 + k * 1024); } while (0)
; #define PG8_LDB(dst, b, h) do { _Pragma("unroll") for (int n = 0; n < 2; ++n) _Pragma("unroll") for (int k = 0; k < 2; ++k) dst[n][k] = *(const PG8_LAS bf16x8*)(lds + PG8_SB(b, h) + boff + n * 2048 + k * 1024); } while (0)
; #define PG8_MMA(ai, bj, At, Bt) do { __builtin_amdgcn_s_setprio(1); _Pragma("unroll") for (int m = 0; m < 4; ++m) _Pragma("unroll") for (int n = 0; n < 2; ++n) _Pragma("unroll") for (int k = 0; k < 2; ++k) \
;         acc[ai][bj][m][n] = __builtin_amdgcn_mfma_f32_16x16x32_bf16(Bt[n][k], At[m][k], acc[ai][bj][m][n], 0, 0, 0); __builtin_amdgcn_s_setprio(0); } while (0)
; #define PG8_BAR __builtin_amdgcn_s_barrier()
; template <class Epi, class Sched, bool ALIGN_EPI = false, bool SP2 = false, bool DUAL = false>
; __device__ __forceinline__ void gemm_phase(PG8_LAS unsigned char* lds, const Gemm g, const Sched& S, const Epi& E) {
;     ...
;             PG8_LDB(B0, 0, 0); PG8_LDB(B1, 0, 1); PG8_SCHED; PG8_LDA(At, 0, 0); PG8_STAGE(PG8_SA(1, 1), a1 + hstep, voffA);
;             PG8_WAIT_V(8); PG8_WAIT_L(0); PG8_BAR; PG8_MMA(0, 0, At, B0); PG8_MMA(0, 1, At, B1); PG8_BAR; PG8_SCHED;
;             PG8_LDA(At, 0, 1); PG8_STAGE(PG8_SB(0, 0), b2, voffB); PG8_STAGE(PG8_SB(0, 1), b2 + hstep, voffB); PG8_STAGE(PG8_SA(0, 0), a2, voffA);
;             PG8_WAIT_V(8); PG8_WAIT_L(0); PG8_BAR; PG8_MMA(1, 0, At, B0); PG8_MMA(1, 1, At, B1); PG8_BAR; PG8_SCHED;
;             PG8_LDB(B0, 1, 0); PG8_LDB(B1, 1, 1); PG8_SCHED; PG8_LDA(At, 1, 0); PG8_STAGE(PG8_SA(0, 1), a2 + hstep, voffA);
;             PG8_WAIT_V(8); PG8_WAIT_L(0); PG8_BAR; PG8_MMA(0, 0, At, B0); PG8_MMA(0, 1, At, B1); PG8_BAR; PG8_SCHED;
;             PG8_LDA(At, 1, 1); PG8_STAGE(PG8_SB(1, 0), b3, voffB); PG8_STAGE(PG8_SB(1, 1), b3 + hstep, voffB); PG8_STAGE(PG8_SA(1, 0), a3, voffA);
;             PG8_WAIT_V(8); PG8_WAIT_L(0); PG8_BAR; PG8_MMA(1, 0, At, B0); PG8_MMA(1, 1, At, B1); PG8_BAR; PG8_SCHED;
	s_setprio 0
	s_add_i32 s66, 0, 0x18000
	s_add_i32 s67, 0, 0x1c000
	v_add_u32_e32 v140, s66, v213
	v_add_u32_e32 v156, s67, v213
	ds_read_b128 v[128:131], v140
	ds_read_b128 v[132:135], v140 offset:1024
	ds_read_b128 v[136:139], v140 offset:2048
	ds_read_b128 v[140:143], v140 offset:3072
	ds_read_b128 v[144:147], v156
	ds_read_b128 v[148:151], v156 offset:1024
	ds_read_b128 v[152:155], v156 offset:2048
	ds_read_b128 v[156:159], v156 offset:3072
	s_add_u32 s26, s26, 0x80000
	s_addc_u32 s27, s27, 0
	s_mov_b32 m0, s43
	ds_read_b128 v[160:163], v217 offset:32768
	ds_read_b128 v[164:167], v217 offset:33792
	ds_read_b128 v[188:191], v217 offset:34816
	ds_read_b128 v[192:195], v217 offset:35840
	ds_read_b128 v[196:199], v217 offset:36864
	ds_read_b128 v[202:205], v217 offset:37888
	ds_read_b128 v[206:209], v217 offset:38912
	ds_read_b128 v[220:223], v217 offset:39936
	global_load_lds_dwordx4 v168, s[26:27]
	s_mov_b32 m0, s44
	s_nop 0
	global_load_lds_dwordx4 v172, s[26:27]
	s_waitcnt vmcnt(8)
	s_waitcnt lgkmcnt(0)
	s_setprio 1
	s_barrier
	v_mfma_f32_16x16x32_bf16 v[124:127], v[128:131], v[160:163], v[124:127]
	v_mfma_f32_16x16x32_bf16 v[124:127], v[132:135], v[164:167], v[124:127]
	v_mfma_f32_16x16x32_bf16 v[108:111], v[128:131], v[188:191], v[108:111]
	v_mfma_f32_16x16x32_bf16 v[108:111], v[132:135], v[192:195], v[108:111]
	v_mfma_f32_16x16x32_bf16 v[92:95], v[128:131], v[196:199], v[92:95]
	v_mfma_f32_16x16x32_bf16 v[92:95], v[132:135], v[202:205], v[92:95]
	v_mfma_f32_16x16x32_bf16 v[76:79], v[128:131], v[206:209], v[76:79]
	v_mfma_f32_16x16x32_bf16 v[76:79], v[132:135], v[220:223], v[76:79]
	v_mfma_f32_16x16x32_bf16 v[120:123], v[136:139], v[160:163], v[120:123]
	v_mfma_f32_16x16x32_bf16 v[120:123], v[140:143], v[164:167], v[120:123]
	v_mfma_f32_16x16x32_bf16 v[104:107], v[136:139], v[188:191], v[104:107]
	v_mfma_f32_16x16x32_bf16 v[104:107], v[140:143], v[192:195], v[104:107]
	v_mfma_f32_16x16x32_bf16 v[88:91], v[136:139], v[196:199], v[88:91]
	v_mfma_f32_16x16x32_bf16 v[88:91], v[140:143], v[202:205], v[88:91]
	v_mfma_f32_16x16x32_bf16 v[72:75], v[136:139], v[206:209], v[72:75]
	v_mfma_f32_16x16x32_bf16 v[72:75], v[140:143], v[220:223], v[72:75]
	s_setprio 0
	s_setprio 1
	v_mfma_f32_16x16x32_bf16 v[116:119], v[144:147], v[160:163], v[116:119]
	v_mfma_f32_16x16x32_bf16 v[116:119], v[148:151], v[164:167], v[116:119]
	v_mfma_f32_16x16x32_bf16 v[100:103], v[144:147], v[188:191], v[100:103]
	v_mfma_f32_16x16x32_bf16 v[100:103], v[148:151], v[192:195], v[100:103]
	v_mfma_f32_16x16x32_bf16 v[84:87], v[144:147], v[196:199], v[84:87]
	v_mfma_f32_16x16x32_bf16 v[84:87], v[148:151], v[202:205], v[84:87]
	v_mfma_f32_16x16x32_bf16 v[68:71], v[144:147], v[206:209], v[68:71]
	v_mfma_f32_16x16x32_bf16 v[68:71], v[148:151], v[220:223], v[68:71]
	v_mfma_f32_16x16x32_bf16 v[112:115], v[152:155], v[160:163], v[112:115]
	v_mfma_f32_16x16x32_bf16 v[112:115], v[156:159], v[164:167], v[112:115]
	v_mfma_f32_16x16x32_bf16 v[96:99], v[152:155], v[188:191], v[96:99]
	v_mfma_f32_16x16x32_bf16 v[96:99], v[156:159], v[192:195], v[96:99]
	v_mfma_f32_16x16x32_bf16 v[80:83], v[152:155], v[196:199], v[80:83]
	v_mfma_f32_16x16x32_bf16 v[80:83], v[156:159], v[202:205], v[80:83]
	v_mfma_f32_16x16x32_bf16 v[64:67], v[152:155], v[206:209], v[64:67]
	v_mfma_f32_16x16x32_bf16 v[64:67], v[156:159], v[220:223], v[64:67]
	s_barrier
	s_setprio 0
	s_add_i32 s26, s66, s34
	v_lshl_add_u64 v[228:229], v[228:229], 0, s[12:13]
	s_mov_b32 m0, s26
	ds_read_b128 v[160:163], v217 offset:49152
	ds_read_b128 v[164:167], v217 offset:50176
	ds_read_b128 v[188:191], v217 offset:51200
	ds_read_b128 v[192:195], v217 offset:52224
	ds_read_b128 v[196:199], v217 offset:53248
	ds_read_b128 v[202:205], v217 offset:54272
	ds_read_b128 v[206:209], v217 offset:55296
	ds_read_b128 v[220:223], v217 offset:56320
	global_load_lds_dwordx4 v[228:229], off
	s_add_i32 m0, s26, 0x2000
	s_add_u32 s14, s14, 0x80080
	v_lshl_add_u64 v[228:229], v[232:233], 0, s[12:13]
	s_addc_u32 s15, s15, 0
	s_add_i32 s26, s67, s34
	global_load_lds_dwordx4 v[228:229], off
	s_mov_b32 m0, s26
	s_nop 0
	global_load_lds_dwordx4 v170, s[14:15]
	s_add_i32 m0, s26, 0x2000
	s_nop 0
	global_load_lds_dwordx4 v174, s[14:15]
	v_lshl_add_u64 v[228:229], v[234:235], 0, s[12:13]
	s_mov_b32 m0, s47
	s_nop 0
	global_load_lds_dwordx4 v[228:229], off
	v_lshl_add_u64 v[228:229], v[236:237], 0, s[12:13]
	s_mov_b32 m0, s48
	s_nop 0
	global_load_lds_dwordx4 v[228:229], off
	s_waitcnt vmcnt(8)
	s_waitcnt lgkmcnt(0)
	s_setprio 1
	s_barrier
	v_mfma_f32_16x16x32_bf16 v[60:63], v[128:131], v[160:163], v[60:63]
	v_mfma_f32_16x16x32_bf16 v[60:63], v[132:135], v[164:167], v[60:63]
	v_mfma_f32_16x16x32_bf16 v[44:47], v[128:131], v[188:191], v[44:47]
	v_mfma_f32_16x16x32_bf16 v[44:47], v[132:135], v[192:195], v[44:47]
	v_mfma_f32_16x16x32_bf16 v[28:31], v[128:131], v[196:199], v[28:31]
	v_mfma_f32_16x16x32_bf16 v[28:31], v[132:135], v[202:205], v[28:31]
	v_mfma_f32_16x16x32_bf16 v[12:15], v[128:131], v[206:209], v[12:15]
	v_mfma_f32_16x16x32_bf16 v[12:15], v[132:135], v[220:223], v[12:15]
	v_mfma_f32_16x16x32_bf16 v[56:59], v[136:139], v[160:163], v[56:59]
	v_mfma_f32_16x16x32_bf16 v[56:59], v[140:143], v[164:167], v[56:59]
	v_mfma_f32_16x16x32_bf16 v[40:43], v[136:139], v[188:191], v[40:43]
	v_mfma_f32_16x16x32_bf16 v[40:43], v[140:143], v[192:195], v[40:43]
	v_mfma_f32_16x16x32_bf16 v[24:27], v[136:139], v[196:199], v[24:27]
	v_mfma_f32_16x16x32_bf16 v[24:27], v[140:143], v[202:205], v[24:27]
	v_mfma_f32_16x16x32_bf16 v[8:11], v[136:139], v[206:209], v[8:11]
	v_mfma_f32_16x16x32_bf16 v[8:11], v[140:143], v[220:223], v[8:11]
	s_setprio 0
	s_setprio 1
	v_mfma_f32_16x16x32_bf16 v[52:55], v[144:147], v[160:163], v[52:55]
	v_mfma_f32_16x16x32_bf16 v[52:55], v[148:151], v[164:167], v[52:55]
	v_mfma_f32_16x16x32_bf16 v[36:39], v[144:147], v[188:191], v[36:39]
	v_mfma_f32_16x16x32_bf16 v[36:39], v[148:151], v[192:195], v[36:39]
	v_mfma_f32_16x16x32_bf16 v[20:23], v[144:147], v[196:199], v[20:23]
	v_mfma_f32_16x16x32_bf16 v[20:23], v[148:151], v[202:205], v[20:23]
	v_mfma_f32_16x16x32_bf16 v[4:7], v[144:147], v[206:209], v[4:7]
	v_mfma_f32_16x16x32_bf16 v[4:7], v[148:151], v[220:223], v[4:7]
	v_mfma_f32_16x16x32_bf16 v[48:51], v[152:155], v[160:163], v[48:51]
	v_mfma_f32_16x16x32_bf16 v[48:51], v[156:159], v[164:167], v[48:51]
	v_mfma_f32_16x16x32_bf16 v[32:35], v[152:155], v[188:191], v[32:35]
	v_mfma_f32_16x16x32_bf16 v[32:35], v[156:159], v[192:195], v[32:35]
	v_mfma_f32_16x16x32_bf16 v[16:19], v[152:155], v[196:199], v[16:19]
	v_mfma_f32_16x16x32_bf16 v[16:19], v[156:159], v[202:205], v[16:19]
	v_mfma_f32_16x16x32_bf16 v[0:3], v[152:155], v[206:209], v[0:3]
	v_mfma_f32_16x16x32_bf16 v[0:3], v[156:159], v[220:223], v[0:3]
	s_barrier
	s_setprio 0
	s_add_i32 s65, s65, 2
	s_add_u32 s40, s40, 0x100
	s_addc_u32 s41, s41, 0
	s_add_u32 s63, s63, 0x100
	s_addc_u32 s64, s64, 0
; #define PG8_STAGE(bufoff, gbase, voff) do { _Pragma("unroll") for (int _i = 0; _i < 2; ++_i) \
;         __builtin_amdgcn_global_load_lds((const unsigned*)((const char*)(gbase) + (voff)[_i]), (PG8_LAS unsigned*)(lds + (bufoff) + ldsw + _i * 8192), 16, 0, 0); } while (0)
; #define PG8_LDA(dst, b, h) do { _Pragma("unroll") for (int m = 0; m < 4; ++m) _Pragma("unroll") for (int k = 0; k < 2; ++k) dst[m][k] = *(const PG8_LAS bf16x8*)(lds + PG8_SA(b, h) + aoff + m * 2048 + k * 1024); } while (0)
; #define PG8_LDB(dst, b, h) do { _Pragma("unroll") for (int n = 0; n < 2; ++n) _Pragma("unroll") for (int k = 0; k < 2; ++k) dst[n][k] = *(const PG8_LAS bf16x8*)(lds + PG8_SB(b, h) + boff + n * 2048 + k * 1024); } while (0)
; #define PG8_WAIT_V(n) asm volatile("s_waitcnt vmcnt(" #n ")" ::: "memory")
; #define PG8_WAIT_L(n) asm volatile("s_waitcnt lgkmcnt(" #n ")" ::: "memory")
; #define PG8_BAR __builtin_amdgcn_s_barrier()
; #define PG8_SCHED __builtin_amdgcn_sched_barrier(0)
; template <class Epi, class Sched, bool ALIGN_EPI = false, bool SP2 = false, bool DUAL = false>
; __device__ __forceinline__ void gemm_phase(PG8_LAS unsigned char* lds, const Gemm g, const Sched& S, const Epi& E) {
;     ...
;         for (int t = 0; t < nt; t += 2) {
;             const bool last = (t == nt - 2);
;             const char* a1 = cA + (size_t)(t + 1) * kstep;
;             const char* a2 = last ? nA : cA + (size_t)(t + 2) * kstep; const char* b2 = last ? nB : cB + (size_t)(t + 2) * kstep;
;             const char* a3 = a2 + kstep; const char* b3 = b2 + kstep;
;             if (last && has_next) S.a_ready(nxt);
;             if constexpr (SP2) {
;             PG8_LDB(B0, 0, 0); PG8_LDB(B1, 0, 1); PG8_SCHED; PG8_LDA(At, 0, 0); PG8_STAGE(PG8_SA(1, 1), a1 + hstep, voffA);
;             PG8_WAIT_V(8); PG8_WAIT_L(0); PG8_BAR; PG8_MMA(0, 0, At, B0); PG8_MMA(0, 1, At, B1); PG8_BAR; PG8_SCHED;
;             PG8_LDA(At, 0, 1); PG8_STAGE(PG8_SB(0, 0), b2, voffB); PG8_STAGE(PG8_SB(0, 1), b2 + hstep, voffB); PG8_STAGE(PG8_SA(0, 0), a2, voffA);
;             PG8_WAIT_V(8); PG8_WAIT_L(0); PG8_BAR; PG8_MMA(1, 0, At, B0); PG8_MMA(1, 1, At, B1); PG8_BAR; PG8_SCHED;
;             PG8_LDB(B0, 1, 0); PG8_LDB(B1, 1, 1); PG8_SCHED; PG8_LDA(At, 1, 0); PG8_STAGE(PG8_SA(0, 1), a2 + hstep, voffA);
;             PG8_WAIT_V(8); PG8_WAIT_L(0); PG8_BAR; PG8_MMA(0, 0, At, B0); PG8_MMA(0, 1, At, B1); PG8_BAR; PG8_SCHED;
.LBB0_992:
	ds_read_b128 v[128:131], v215
	ds_read_b128 v[132:135], v215 offset:1024
	ds_read_b128 v[136:139], v215 offset:2048
	ds_read_b128 v[140:143], v215 offset:3072
	ds_read_b128 v[144:147], v216
	ds_read_b128 v[148:151], v216 offset:1024
	ds_read_b128 v[152:155], v216 offset:2048
	ds_read_b128 v[156:159], v216 offset:3072
	s_add_u32 s14, s40, 0xfff80080
	s_addc_u32 s15, s41, -1
	s_cmp_eq_u32 s65, 28
	s_cselect_b32 s27, s25, s15
	s_cselect_b32 s26, s28, s14
	s_cselect_b32 s15, s23, s64
	s_cselect_b32 s14, s29, s63
	s_add_i32 m0, s39, 0xc000
	ds_read_b128 v[160:163], v217
	ds_read_b128 v[164:167], v217 offset:1024
	ds_read_b128 v[188:191], v217 offset:2048
	ds_read_b128 v[192:195], v217 offset:3072
	ds_read_b128 v[196:199], v217 offset:4096
	ds_read_b128 v[202:205], v217 offset:5120
	ds_read_b128 v[206:209], v217 offset:6144
	ds_read_b128 v[220:223], v217 offset:7168
	global_load_lds_dwordx4 v180, s[40:41]
	s_add_i32 m0, s39, 0xe000
	s_nop 0
	global_load_lds_dwordx4 v182, s[40:41]
	s_waitcnt vmcnt(8)
	s_waitcnt lgkmcnt(0)
	s_setprio 1
	s_barrier
	v_mfma_f32_16x16x32_bf16 v[124:127], v[128:131], v[160:163], v[124:127]
	v_mfma_f32_16x16x32_bf16 v[124:127], v[132:135], v[164:167], v[124:127]
	v_mfma_f32_16x16x32_bf16 v[108:111], v[128:131], v[188:191], v[108:111]
	v_mfma_f32_16x16x32_bf16 v[108:111], v[132:135], v[192:195], v[108:111]
	v_mfma_f32_16x16x32_bf16 v[92:95], v[128:131], v[196:199], v[92:95]
	v_mfma_f32_16x16x32_bf16 v[92:95], v[132:135], v[202:205], v[92:95]
	v_mfma_f32_16x16x32_bf16 v[76:79], v[128:131], v[206:209], v[76:79]
	v_mfma_f32_16x16x32_bf16 v[76:79], v[132:135], v[220:223], v[76:79]
	v_mfma_f32_16x16x32_bf16 v[120:123], v[136:139], v[160:163], v[120:123]
	v_mfma_f32_16x16x32_bf16 v[120:123], v[140:143], v[164:167], v[120:123]
	v_mfma_f32_16x16x32_bf16 v[104:107], v[136:139], v[188:191], v[104:107]
	v_mfma_f32_16x16x32_bf16 v[104:107], v[140:143], v[192:195], v[104:107]
	v_mfma_f32_16x16x32_bf16 v[88:91], v[136:139], v[196:199], v[88:91]
	v_mfma_f32_16x16x32_bf16 v[88:91], v[140:143], v[202:205], v[88:91]
	v_mfma_f32_16x16x32_bf16 v[72:75], v[136:139], v[206:209], v[72:75]
	v_mfma_f32_16x16x32_bf16 v[72:75], v[140:143], v[220:223], v[72:75]
	s_setprio 0
	s_setprio 1
	v_mfma_f32_16x16x32_bf16 v[116:119], v[144:147], v[160:163], v[116:119]
	v_mfma_f32_16x16x32_bf16 v[116:119], v[148:151], v[164:167], v[116:119]
	v_mfma_f32_16x16x32_bf16 v[100:103], v[144:147], v[188:191], v[100:103]
	v_mfma_f32_16x16x32_bf16 v[100:103], v[148:151], v[192:195], v[100:103]
	v_mfma_f32_16x16x32_bf16 v[84:87], v[144:147], v[196:199], v[84:87]
	v_mfma_f32_16x16x32_bf16 v[84:87], v[148:151], v[202:205], v[84:87]
	v_mfma_f32_16x16x32_bf16 v[68:71], v[144:147], v[206:209], v[68:71]
	v_mfma_f32_16x16x32_bf16 v[68:71], v[148:151], v[220:223], v[68:71]
	v_mfma_f32_16x16x32_bf16 v[112:115], v[152:155], v[160:163], v[112:115]
	v_mfma_f32_16x16x32_bf16 v[112:115], v[156:159], v[164:167], v[112:115]
	v_mfma_f32_16x16x32_bf16 v[96:99], v[152:155], v[188:191], v[96:99]
	v_mfma_f32_16x16x32_bf16 v[96:99], v[156:159], v[192:195], v[96:99]
	v_mfma_f32_16x16x32_bf16 v[80:83], v[152:155], v[196:199], v[80:83]
	v_mfma_f32_16x16x32_bf16 v[80:83], v[156:159], v[202:205], v[80:83]
	v_mfma_f32_16x16x32_bf16 v[64:67], v[152:155], v[206:209], v[64:67]
	v_mfma_f32_16x16x32_bf16 v[64:67], v[156:159], v[220:223], v[64:67]
	s_barrier
	s_setprio 0
	s_add_i32 s66, s50, s34
	v_lshl_add_u64 v[228:229], s[14:15], 0, v[170:171]
	s_mov_b32 m0, s66
	ds_read_b128 v[160:163], v217 offset:16384
	ds_read_b128 v[164:167], v217 offset:17408
	ds_read_b128 v[188:191], v217 offset:18432
	ds_read_b128 v[192:195], v217 offset:19456
	ds_read_b128 v[196:199], v217 offset:20480
	ds_read_b128 v[202:205], v217 offset:21504
	ds_read_b128 v[206:209], v217 offset:22528
	ds_read_b128 v[220:223], v217 offset:23552
	global_load_lds_dwordx4 v[228:229], off
	s_add_i32 m0, s66, 0x2000
	s_add_u32 s66, s14, 0x80000
	v_lshl_add_u64 v[232:233], s[14:15], 0, v[174:175]
	s_addc_u32 s67, s15, 0
	s_add_i32 s68, s51, s34
	global_load_lds_dwordx4 v[232:233], off
	s_mov_b32 m0, s68
	v_lshl_add_u64 v[236:237], s[26:27], 0, v[172:173]
	global_load_lds_dwordx4 v170, s[66:67]
	s_add_i32 m0, s68, 0x2000
	s_nop 0
	global_load_lds_dwordx4 v174, s[66:67]
	v_lshl_add_u64 v[234:235], s[26:27], 0, v[168:169]
	s_mov_b32 m0, s39
	s_nop 0
	global_load_lds_dwordx4 v[234:235], off
	s_mov_b32 m0, s42
	s_nop 0
	global_load_lds_dwordx4 v[236:237], off
	s_waitcnt vmcnt(8)
	s_waitcnt lgkmcnt(0)
	s_setprio 1
	s_barrier
	v_mfma_f32_16x16x32_bf16 v[60:63], v[128:131], v[160:163], v[60:63]
	v_mfma_f32_16x16x32_bf16 v[60:63], v[132:135], v[164:167], v[60:63]
	v_mfma_f32_16x16x32_bf16 v[44:47], v[128:131], v[188:191], v[44:47]
	v_mfma_f32_16x16x32_bf16 v[44:47], v[132:135], v[192:195], v[44:47]
	v_mfma_f32_16x16x32_bf16 v[28:31], v[128:131], v[196:199], v[28:31]
	v_mfma_f32_16x16x32_bf16 v[28:31], v[132:135], v[202:205], v[28:31]
	v_mfma_f32_16x16x32_bf16 v[12:15], v[128:131], v[206:209], v[12:15]
	v_mfma_f32_16x16x32_bf16 v[12:15], v[132:135], v[220:223], v[12:15]
	v_mfma_f32_16x16x32_bf16 v[56:59], v[136:139], v[160:163], v[56:59]
	v_mfma_f32_16x16x32_bf16 v[56:59], v[140:143], v[164:167], v[56:59]
	v_mfma_f32_16x16x32_bf16 v[40:43], v[136:139], v[188:191], v[40:43]
	v_mfma_f32_16x16x32_bf16 v[40:43], v[140:143], v[192:195], v[40:43]
	v_mfma_f32_16x16x32_bf16 v[24:27], v[136:139], v[196:199], v[24:27]
	v_mfma_f32_16x16x32_bf16 v[24:27], v[140:143], v[202:205], v[24:27]
	v_mfma_f32_16x16x32_bf16 v[8:11], v[136:139], v[206:209], v[8:11]
	v_mfma_f32_16x16x32_bf16 v[8:11], v[140:143], v[220:223], v[8:11]
	s_setprio 0
	s_setprio 1
	v_mfma_f32_16x16x32_bf16 v[52:55], v[144:147], v[160:163], v[52:55]
	v_mfma_f32_16x16x32_bf16 v[52:55], v[148:151], v[164:167], v[52:55]
	v_mfma_f32_16x16x32_bf16 v[36:39], v[144:147], v[188:191], v[36:39]
	v_mfma_f32_16x16x32_bf16 v[36:39], v[148:151], v[192:195], v[36:39]
	v_mfma_f32_16x16x32_bf16 v[20:23], v[144:147], v[196:199], v[20:23]
	v_mfma_f32_16x16x32_bf16 v[20:23], v[148:151], v[202:205], v[20:23]
	v_mfma_f32_16x16x32_bf16 v[4:7], v[144:147], v[206:209], v[4:7]
	v_mfma_f32_16x16x32_bf16 v[4:7], v[148:151], v[220:223], v[4:7]
	v_mfma_f32_16x16x32_bf16 v[48:51], v[152:155], v[160:163], v[48:51]
	v_mfma_f32_16x16x32_bf16 v[48:51], v[156:159], v[164:167], v[48:51]
	v_mfma_f32_16x16x32_bf16 v[32:35], v[152:155], v[188:191], v[32:35]
	v_mfma_f32_16x16x32_bf16 v[32:35], v[156:159], v[192:195], v[32:35]
	v_mfma_f32_16x16x32_bf16 v[16:19], v[152:155], v[196:199], v[16:19]
	v_mfma_f32_16x16x32_bf16 v[16:19], v[156:159], v[202:205], v[16:19]
	v_mfma_f32_16x16x32_bf16 v[0:3], v[152:155], v[206:209], v[0:3]
	v_mfma_f32_16x16x32_bf16 v[0:3], v[156:159], v[220:223], v[0:3]
	s_barrier
; #define PG8_STAGE(bufoff, gbase, voff) do { _Pragma("unroll") for (int _i = 0; _i < 2; ++_i) \
;         __builtin_amdgcn_global_load_lds((const unsigned*)((const char*)(gbase) + (voff)[_i]), (PG8_LAS unsigned*)(lds + (bufoff) + ldsw + _i * 8192), 16, 0, 0); } while (0)
; #define PG8_LDA(dst, b, h) do { _Pragma("unroll") for (int m = 0; m < 4; ++m) _Pragma("unroll") for (int k = 0; k < 2; ++k) dst[m][k] = *(const PG8_LAS bf16x8*)(lds + PG8_SA(b, h) + aoff + m * 2048 + k * 1024); } while (0)
; #define PG8_LDB(dst, b, h) do { _Pragma("unroll") for (int n = 0; n < 2; ++n) _Pragma("unroll") for (int k = 0; k < 2; ++k) dst[n][k] = *(const PG8_LAS bf16x8*)(lds + PG8_SB(b, h) + boff + n * 2048 + k * 1024); } while (0)
; #define PG8_MMA(ai, bj, At, Bt) do { __builtin_amdgcn_s_setprio(1); _Pragma("unroll") for (int m = 0; m < 4; ++m) _Pragma("unroll") for (int n = 0; n < 2; ++n) _Pragma("unroll") for (int k = 0; k < 2; ++k) \
;         acc[ai][bj][m][n] = __builtin_amdgcn_mfma_f32_16x16x32_bf16(Bt[n][k], At[m][k], acc[ai][bj][m][n], 0, 0, 0); __builtin_amdgcn_s_setprio(0); } while (0)
; #define PG8_WAIT_V(n) asm volatile("s_waitcnt vmcnt(" #n ")" ::: "memory")
; #define PG8_WAIT_L(n) asm volatile("s_waitcnt lgkmcnt(" #n ")" ::: "memory")
; #define PG8_BAR __builtin_amdgcn_s_barrier()
; #define PG8_SCHED __builtin_amdgcn_sched_barrier(0)
; template <class Epi, class Sched, bool ALIGN_EPI = false, bool SP2 = false, bool DUAL = false>
; __device__ __forceinline__ void gemm_phase(PG8_LAS unsigned char* lds, const Gemm g, const Sched& S, const Epi& E) {
;     ...
;             PG8_LDB(B0, 1, 0); PG8_LDB(B1, 1, 1); PG8_SCHED; PG8_LDA(At, 1, 0); PG8_STAGE(PG8_SA(0, 1), a2 + hstep, voffA);
;             PG8_WAIT_V(8); PG8_WAIT_L(0); PG8_BAR; PG8_MMA(0, 0, At, B0); PG8_MMA(0, 1, At, B1); PG8_BAR; PG8_SCHED;
;             PG8_LDA(At, 1, 1); PG8_STAGE(PG8_SB(1, 0), b3, voffB); PG8_STAGE(PG8_SB(1, 1), b3 + hstep, voffB); PG8_STAGE(PG8_SA(1, 0), a3, voffA);
;             PG8_WAIT_V(8); PG8_WAIT_L(0); PG8_BAR; PG8_MMA(1, 0, At, B0); PG8_MMA(1, 1, At, B1); PG8_BAR; PG8_SCHED;
	s_setprio 0
	s_add_i32 s66, 0, 0x18000
	s_add_i32 s67, 0, 0x1c000
	v_add_u32_e32 v140, s66, v213
	v_add_u32_e32 v156, s67, v213
	ds_read_b128 v[128:131], v140
	ds_read_b128 v[132:135], v140 offset:1024
	ds_read_b128 v[136:139], v140 offset:2048
	ds_read_b128 v[140:143], v140 offset:3072
	ds_read_b128 v[144:147], v156
	ds_read_b128 v[148:151], v156 offset:1024
	ds_read_b128 v[152:155], v156 offset:2048
	ds_read_b128 v[156:159], v156 offset:3072
	s_add_u32 s26, s26, 0x80000
	s_addc_u32 s27, s27, 0
	s_mov_b32 m0, s43
	ds_read_b128 v[160:163], v217 offset:32768
	ds_read_b128 v[164:167], v217 offset:33792
	ds_read_b128 v[188:191], v217 offset:34816
	ds_read_b128 v[192:195], v217 offset:35840
	ds_read_b128 v[196:199], v217 offset:36864
	ds_read_b128 v[202:205], v217 offset:37888
	ds_read_b128 v[206:209], v217 offset:38912
	ds_read_b128 v[220:223], v217 offset:39936
	global_load_lds_dwordx4 v168, s[26:27]
	s_mov_b32 m0, s44
	s_nop 0
	global_load_lds_dwordx4 v172, s[26:27]
	s_waitcnt vmcnt(8)
	s_waitcnt lgkmcnt(0)
	s_setprio 1
	s_barrier
	v_mfma_f32_16x16x32_bf16 v[124:127], v[128:131], v[160:163], v[124:127]
	v_mfma_f32_16x16x32_bf16 v[124:127], v[132:135], v[164:167], v[124:127]
	v_mfma_f32_16x16x32_bf16 v[108:111], v[128:131], v[188:191], v[108:111]
	v_mfma_f32_16x16x32_bf16 v[108:111], v[132:135], v[192:195], v[108:111]
	v_mfma_f32_16x16x32_bf16 v[92:95], v[128:131], v[196:199], v[92:95]
	v_mfma_f32_16x16x32_bf16 v[92:95], v[132:135], v[202:205], v[92:95]
	v_mfma_f32_16x16x32_bf16 v[76:79], v[128:131], v[206:209], v[76:79]
	v_mfma_f32_16x16x32_bf16 v[76:79], v[132:135], v[220:223], v[76:79]
	v_mfma_f32_16x16x32_bf16 v[120:123], v[136:139], v[160:163], v[120:123]
	v_mfma_f32_16x16x32_bf16 v[120:123], v[140:143], v[164:167], v[120:123]
	v_mfma_f32_16x16x32_bf16 v[104:107], v[136:139], v[188:191], v[104:107]
	v_mfma_f32_16x16x32_bf16 v[104:107], v[140:143], v[192:195], v[104:107]
	v_mfma_f32_16x16x32_bf16 v[88:91], v[136:139], v[196:199], v[88:91]
	v_mfma_f32_16x16x32_bf16 v[88:91], v[140:143], v[202:205], v[88:91]
	v_mfma_f32_16x16x32_bf16 v[72:75], v[136:139], v[206:209], v[72:75]
	v_mfma_f32_16x16x32_bf16 v[72:75], v[140:143], v[220:223], v[72:75]
	s_setprio 0
	s_setprio 1
	v_mfma_f32_16x16x32_bf16 v[116:119], v[144:147], v[160:163], v[116:119]
	v_mfma_f32_16x16x32_bf16 v[116:119], v[148:151], v[164:167], v[116:119]
	v_mfma_f32_16x16x32_bf16 v[100:103], v[144:147], v[188:191], v[100:103]
	v_mfma_f32_16x16x32_bf16 v[100:103], v[148:151], v[192:195], v[100:103]
	v_mfma_f32_16x16x32_bf16 v[84:87], v[144:147], v[196:199], v[84:87]
	v_mfma_f32_16x16x32_bf16 v[84:87], v[148:151], v[202:205], v[84:87]
	v_mfma_f32_16x16x32_bf16 v[68:71], v[144:147], v[206:209], v[68:71]
	v_mfma_f32_16x16x32_bf16 v[68:71], v[148:151], v[220:223], v[68:71]
	v_mfma_f32_16x16x32_bf16 v[112:115], v[152:155], v[160:163], v[112:115]
	v_mfma_f32_16x16x32_bf16 v[112:115], v[156:159], v[164:167], v[112:115]
	v_mfma_f32_16x16x32_bf16 v[96:99], v[152:155], v[188:191], v[96:99]
	v_mfma_f32_16x16x32_bf16 v[96:99], v[156:159], v[192:195], v[96:99]
	v_mfma_f32_16x16x32_bf16 v[80:83], v[152:155], v[196:199], v[80:83]
	v_mfma_f32_16x16x32_bf16 v[80:83], v[156:159], v[202:205], v[80:83]
	v_mfma_f32_16x16x32_bf16 v[64:67], v[152:155], v[206:209], v[64:67]
	v_mfma_f32_16x16x32_bf16 v[64:67], v[156:159], v[220:223], v[64:67]
	s_barrier
	s_setprio 0
	s_add_i32 s26, s66, s34
	v_lshl_add_u64 v[228:229], v[228:229], 0, s[12:13]
	s_mov_b32 m0, s26
	ds_read_b128 v[160:163], v217 offset:49152
	ds_read_b128 v[164:167], v217 offset:50176
	ds_read_b128 v[188:191], v217 offset:51200
	ds_read_b128 v[192:195], v217 offset:52224
	ds_read_b128 v[196:199], v217 offset:53248
	ds_read_b128 v[202:205], v217 offset:54272
	ds_read_b128 v[206:209], v217 offset:55296
	ds_read_b128 v[220:223], v217 offset:56320
	global_load_lds_dwordx4 v[228:229], off
	s_add_i32 m0, s26, 0x2000
	s_add_u32 s14, s14, 0x80080
	v_lshl_add_u64 v[228:229], v[232:233], 0, s[12:13]
	s_addc_u32 s15, s15, 0
	s_add_i32 s26, s67, s34
	global_load_lds_dwordx4 v[228:229], off
	s_mov_b32 m0, s26
	s_nop 0
	global_load_lds_dwordx4 v170, s[14:15]
	s_add_i32 m0, s26, 0x2000
	s_nop 0
	global_load_lds_dwordx4 v174, s[14:15]
	v_lshl_add_u64 v[228:229], v[234:235], 0, s[12:13]
	s_mov_b32 m0, s47
	s_nop 0
	global_load_lds_dwordx4 v[228:229], off
	v_lshl_add_u64 v[228:229], v[236:237], 0, s[12:13]
	s_mov_b32 m0, s48
	s_nop 0
	global_load_lds_dwordx4 v[228:229], off
	s_waitcnt vmcnt(8)
	s_waitcnt lgkmcnt(0)
	s_setprio 1
	s_barrier
; #define PG8_STAGE(bufoff, gbase, voff) do { _Pragma("unroll") for (int _i = 0; _i < 2; ++_i) \
;         __builtin_amdgcn_global_load_lds((const unsigned*)((const char*)(gbase) + (voff)[_i]), (PG8_LAS unsigned*)(lds + (bufoff) + ldsw + _i * 8192), 16, 0, 0); } while (0)
; #define PG8_LDA(dst, b, h) do { _Pragma("unroll") for (int m = 0; m < 4; ++m) _Pragma("unroll") for (int k = 0; k < 2; ++k) dst[m][k] = *(const PG8_LAS bf16x8*)(lds + PG8_SA(b, h) + aoff + m * 2048 + k * 1024); } while (0)
; #define PG8_MMA(ai, bj, At, Bt) do { __builtin_amdgcn_s_setprio(1); _Pragma("unroll") for (int m = 0; m < 4; ++m) _Pragma("unroll") for (int n = 0; n < 2; ++n) _Pragma("unroll") for (int k = 0; k < 2; ++k) \
;         acc[ai][bj][m][n] = __builtin_amdgcn_mfma_f32_16x16x32_bf16(Bt[n][k], At[m][k], acc[ai][bj][m][n], 0, 0, 0); __builtin_amdgcn_s_setprio(0); } while (0)
; #define PG8_WAIT_V(n) asm volatile("s_waitcnt vmcnt(" #n ")" ::: "memory")
; #define PG8_WAIT_L(n) asm volatile("s_waitcnt lgkmcnt(" #n ")" ::: "memory")
; #define PG8_BAR __builtin_amdgcn_s_barrier()
; #define PG8_SCHED __builtin_amdgcn_sched_barrier(0)
; template <class Epi, class Sched, bool ALIGN_EPI = false, bool SP2 = false, bool DUAL = false>
; __device__ __forceinline__ void gemm_phase(PG8_LAS unsigned char* lds, const Gemm g, const Sched& S, const Epi& E) {
;     ...
;             PG8_WAIT_V(8); PG8_WAIT_L(0); PG8_BAR; PG8_MMA(0, 0, At, B0); PG8_MMA(0, 1, At, B1); PG8_BAR; PG8_SCHED;
;             PG8_LDA(At, 1, 1); PG8_STAGE(PG8_SB(1, 0), b3, voffB); PG8_STAGE(PG8_SB(1, 1), b3 + hstep, voffB); PG8_STAGE(PG8_SA(1, 0), a3, voffA);
;             PG8_WAIT_V(8); PG8_WAIT_L(0); PG8_BAR; PG8_MMA(1, 0, At, B0); PG8_MMA(1, 1, At, B1); PG8_BAR; PG8_SCHED;
;     __device__ __forceinline__ void operator()(const f32x4 (&acc)[2][2][4][2], const Unit& u, int wr, int wc, int fr, int fq) const {
;         const int rowb = u.pm * BM + wr * 64 + fr, col = u.pn * HALF + wc * 32 + fq * 8;
;         f32x4 p[2][4][2];
; #pragma unroll
;         for (int ai = 0; ai < 2; ++ai)
; #pragma unroll
;             for (int m = 0; m < 4; ++m) { const float* sp = ss2 + (size_t)(rowb + ai * HALF + m * 16) * 32 + fq * 8; p[ai][m][0] = *(const f32x4*)sp; p[ai][m][1] = *(const f32x4*)(sp + 4); }
	v_mfma_f32_16x16x32_bf16 v[60:63], v[128:131], v[160:163], v[60:63]
	v_mfma_f32_16x16x32_bf16 v[60:63], v[132:135], v[164:167], v[60:63]
	v_mfma_f32_16x16x32_bf16 v[44:47], v[128:131], v[188:191], v[44:47]
	v_mfma_f32_16x16x32_bf16 v[44:47], v[132:135], v[192:195], v[44:47]
	v_mfma_f32_16x16x32_bf16 v[28:31], v[128:131], v[196:199], v[28:31]
	v_mfma_f32_16x16x32_bf16 v[28:31], v[132:135], v[202:205], v[28:31]
	v_mfma_f32_16x16x32_bf16 v[12:15], v[128:131], v[206:209], v[12:15]
	v_mfma_f32_16x16x32_bf16 v[12:15], v[132:135], v[220:223], v[12:15]
	v_mfma_f32_16x16x32_bf16 v[56:59], v[136:139], v[160:163], v[56:59]
	v_mfma_f32_16x16x32_bf16 v[56:59], v[140:143], v[164:167], v[56:59]
	v_mfma_f32_16x16x32_bf16 v[40:43], v[136:139], v[188:191], v[40:43]
	v_mfma_f32_16x16x32_bf16 v[40:43], v[140:143], v[192:195], v[40:43]
	v_mfma_f32_16x16x32_bf16 v[24:27], v[136:139], v[196:199], v[24:27]
	v_mfma_f32_16x16x32_bf16 v[24:27], v[140:143], v[202:205], v[24:27]
	v_mfma_f32_16x16x32_bf16 v[8:11], v[136:139], v[206:209], v[8:11]
	v_mfma_f32_16x16x32_bf16 v[8:11], v[140:143], v[220:223], v[8:11]
	s_setprio 0
	s_setprio 1
	v_mfma_f32_16x16x32_bf16 v[52:55], v[144:147], v[160:163], v[52:55]
	v_mfma_f32_16x16x32_bf16 v[52:55], v[148:151], v[164:167], v[52:55]
	v_mfma_f32_16x16x32_bf16 v[36:39], v[144:147], v[188:191], v[36:39]
	v_mfma_f32_16x16x32_bf16 v[36:39], v[148:151], v[192:195], v[36:39]
	v_mfma_f32_16x16x32_bf16 v[20:23], v[144:147], v[196:199], v[20:23]
	v_mfma_f32_16x16x32_bf16 v[20:23], v[148:151], v[202:205], v[20:23]
	v_mfma_f32_16x16x32_bf16 v[4:7], v[144:147], v[206:209], v[4:7]
	v_mfma_f32_16x16x32_bf16 v[4:7], v[148:151], v[220:223], v[4:7]
	v_mfma_f32_16x16x32_bf16 v[48:51], v[152:155], v[160:163], v[48:51]
	v_mfma_f32_16x16x32_bf16 v[48:51], v[156:159], v[164:167], v[48:51]
	v_mfma_f32_16x16x32_bf16 v[32:35], v[152:155], v[188:191], v[32:35]
	v_mfma_f32_16x16x32_bf16 v[32:35], v[156:159], v[192:195], v[32:35]
	v_mfma_f32_16x16x32_bf16 v[16:19], v[152:155], v[196:199], v[16:19]
	v_mfma_f32_16x16x32_bf16 v[16:19], v[156:159], v[202:205], v[16:19]
	v_mfma_f32_16x16x32_bf16 v[0:3], v[152:155], v[206:209], v[0:3]
	v_mfma_f32_16x16x32_bf16 v[0:3], v[156:159], v[220:223], v[0:3]
	s_barrier
	s_setprio 0
	s_add_i32 s65, s65, 2
	s_add_u32 s40, s40, 0x100
	s_addc_u32 s41, s41, 0
	s_add_u32 s63, s63, 0x100
	s_addc_u32 s64, s64, 0
	s_cmp_gt_u32 s65, 29
	s_cbranch_scc0 .LBB0_992
	v_lshl_add_u32 v144, s38, 8, v212
	v_ashrrev_i32_e32 v145, 31, v144
	v_or_b32_e32 v206, 16, v144
	v_lshlrev_b64 v[128:129], 7, v[144:145]
	v_ashrrev_i32_e32 v207, 31, v206
	v_lshl_add_u64 v[132:133], v[178:179], 0, v[128:129]
	v_lshlrev_b64 v[136:137], 7, v[206:207]
	global_load_dwordx4 v[128:131], v[132:133], off
	s_nop 0
	global_load_dwordx4 v[132:135], v[132:133], off offset:16
	v_lshl_add_u64 v[140:141], v[178:179], 0, v[136:137]
	global_load_dwordx4 v[136:139], v[140:141], off
	s_nop 0
	global_load_dwordx4 v[140:143], v[140:141], off offset:16
	v_readlane_b32 s64, v254, 20
	v_readlane_b32 s70, v254, 26
	v_readlane_b32 s71, v254, 27
	v_readlane_b32 s72, v254, 28
	v_readlane_b32 s73, v254, 29
	v_readlane_b32 s74, v254, 30
	v_readlane_b32 s75, v254, 31
	v_readlane_b32 s76, v254, 32
	v_readlane_b32 s77, v254, 33
	s_and_b64 vcc, exec, s[16:17]
	s_mov_b64 s[70:71], s[74:75]
	s_mov_b64 s[72:73], s[76:77]
	v_readlane_b32 s65, v254, 21
	v_readlane_b32 s66, v254, 22
	v_readlane_b32 s67, v254, 23
	v_readlane_b32 s68, v254, 24
	v_readlane_b32 s69, v254, 25
	v_readlane_b32 s78, v254, 34
	v_readlane_b32 s79, v254, 35
	s_cbranch_vccz .LBB0_995
	s_barrier

;     __device__ bool next(int i, Unit& u) const { if (!base.next(i >> 1, u)) return false; u.sub = i & 1; return true; }
; #define PG8_STAGE(bufoff, gbase, voff) do { _Pragma("unroll") for (int _i = 0; _i < 2; ++_i) \
;         __builtin_amdgcn_global_load_lds((const unsigned*)((const char*)(gbase) + (voff)[_i]), (PG8_LAS unsigned*)(lds + (bufoff) + ldsw + _i * 8192), 16, 0, 0); } while (0)
; #define PG8_LDA(dst, b, h) do { _Pragma("unroll") for (int m = 0; m < 4; ++m) _Pragma("unroll") for (int k = 0; k < 2; ++k) dst[m][k] = *(const PG8_LAS bf16x8*)(lds + PG8_SA(b, h) + aoff + m * 2048 + k * 1024); } while (0)
; #define PG8_LDB(dst, b, h) do { _Pragma("unroll") for (int n = 0; n < 2; ++n) _Pragma("unroll") for (int k = 0; k < 2; ++k) dst[n][k] = *(const PG8_LAS bf16x8*)(lds + PG8_SB(b, h) + boff + n * 2048 + k * 1024); } while (0)
; #define PG8_WAIT_V(n) asm volatile("s_waitcnt vmcnt(" #n ")" ::: "memory")
; template <class Epi, class Sched, bool ALIGN_EPI = false, bool SP2 = false, bool DUAL = false>
; __device__ __forceinline__ void gemm_phase(PG8_LAS unsigned char* lds, const Gemm g, const Sched& S, const Epi& E) {
;     ...
;         const bool has_next = S.next(ui + 1, nxt);
;         const char* nA = has_next ? (const char*)((DUAL && nxt.sub) ? g.A2 : g.A) + (size_t)nxt.pm * tstep : cA; const char* nB = has_next ? (const char*)((DUAL && nxt.sub) ? g.Bt2 : g.Bt) + (size_t)nxt.pn * tstep : cB;
;         for (int t = 0; t < nt; t += 2) {
;             const bool last = (t == nt - 2);
;             const char* a1 = cA + (size_t)(t + 1) * kstep;
;             const char* a2 = last ? nA : cA + (size_t)(t + 2) * kstep; const char* b2 = last ? nB : cB + (size_t)(t + 2) * kstep;
;             const char* a3 = a2 + kstep; const char* b3 = b2 + kstep;
;             if (last && has_next) S.a_ready(nxt);
;             if constexpr (SP2) {
;             PG8_LDB(B0, 0, 0); PG8_LDB(B1, 0, 1); PG8_SCHED; PG8_LDA(At, 0, 0); PG8_STAGE(PG8_SA(1, 1), a1 + hstep, voffA);
;             PG8_WAIT_V(8); PG8_WAIT_L(0); PG8_BAR; PG8_MMA(0, 0, At, B0); PG8_MMA(0, 1, At, B1); PG8_BAR; PG8_SCHED;
;             PG8_LDA(At, 0, 1); PG8_STAGE(PG8_SB(0, 0), b2, voffB); PG8_STAGE(PG8_SB(0, 1), b2 + hstep, voffB); PG8_STAGE(PG8_SA(0, 0), a2, voffA);
;             PG8_WAIT_V(8); PG8_WAIT_L(0); PG8_BAR; PG8_MMA(1, 0, At, B0); PG8_MMA(1, 1, At, B1); PG8_BAR; PG8_SCHED;
.LBB0_1192:
	s_add_u32 s24, s24, 0x160080
	s_addc_u32 s25, s25, 0
	s_add_u32 s46, s14, 0x100
	s_addc_u32 s47, s15, 0
	s_mov_b32 s48, -2
	s_add_u32 s14, s24, 0xffea0080
	s_addc_u32 s15, s25, -1
	s_cmpk_eq_i32 s48, 0x54
	s_cselect_b32 s27, s5, s15
	s_cselect_b32 s26, s4, s14
	s_cselect_b32 s15, s23, s47
	s_cselect_b32 s14, s22, s46
	s_waitcnt vmcnt(8)
	s_waitcnt lgkmcnt(0)
	s_setprio 1
	s_barrier
	v_mfma_f32_16x16x32_bf16 v[124:127], v[128:131], v[160:163], 0
	v_mfma_f32_16x16x32_bf16 v[124:127], v[132:135], v[182:185], v[124:127]
	v_mfma_f32_16x16x32_bf16 v[112:115], v[128:131], v[186:189], 0
	v_mfma_f32_16x16x32_bf16 v[112:115], v[132:135], v[190:193], v[112:115]
	v_mfma_f32_16x16x32_bf16 v[96:99], v[128:131], v[204:207], 0
	v_mfma_f32_16x16x32_bf16 v[96:99], v[132:135], v[208:211], v[96:99]
	v_mfma_f32_16x16x32_bf16 v[80:83], v[128:131], v[212:215], 0
	v_mfma_f32_16x16x32_bf16 v[80:83], v[132:135], v[216:219], v[80:83]
	v_mfma_f32_16x16x32_bf16 v[120:123], v[136:139], v[160:163], 0
	v_mfma_f32_16x16x32_bf16 v[120:123], v[140:143], v[182:185], v[120:123]
	v_mfma_f32_16x16x32_bf16 v[104:107], v[136:139], v[186:189], 0
	v_mfma_f32_16x16x32_bf16 v[104:107], v[140:143], v[190:193], v[104:107]
	v_mfma_f32_16x16x32_bf16 v[88:91], v[136:139], v[204:207], 0
	v_mfma_f32_16x16x32_bf16 v[88:91], v[140:143], v[208:211], v[88:91]
	v_mfma_f32_16x16x32_bf16 v[72:75], v[136:139], v[212:215], 0
	v_mfma_f32_16x16x32_bf16 v[72:75], v[140:143], v[216:219], v[72:75]
	s_setprio 0
	s_setprio 1
	v_mfma_f32_16x16x32_bf16 v[116:119], v[144:147], v[160:163], 0
	v_mfma_f32_16x16x32_bf16 v[116:119], v[148:151], v[182:185], v[116:119]
	v_mfma_f32_16x16x32_bf16 v[100:103], v[144:147], v[186:189], 0
	v_mfma_f32_16x16x32_bf16 v[100:103], v[148:151], v[190:193], v[100:103]
	v_mfma_f32_16x16x32_bf16 v[84:87], v[144:147], v[204:207], 0
	v_mfma_f32_16x16x32_bf16 v[84:87], v[148:151], v[208:211], v[84:87]
	v_mfma_f32_16x16x32_bf16 v[68:71], v[144:147], v[212:215], 0
	v_mfma_f32_16x16x32_bf16 v[68:71], v[148:151], v[216:219], v[68:71]
	v_mfma_f32_16x16x32_bf16 v[108:111], v[152:155], v[160:163], 0
	v_mfma_f32_16x16x32_bf16 v[108:111], v[156:159], v[182:185], v[108:111]
	v_mfma_f32_16x16x32_bf16 v[92:95], v[152:155], v[186:189], 0
	v_mfma_f32_16x16x32_bf16 v[92:95], v[156:159], v[190:193], v[92:95]
	v_mfma_f32_16x16x32_bf16 v[76:79], v[152:155], v[204:207], 0
	v_mfma_f32_16x16x32_bf16 v[76:79], v[156:159], v[208:211], v[76:79]
	v_mfma_f32_16x16x32_bf16 v[64:67], v[152:155], v[212:215], 0
	v_mfma_f32_16x16x32_bf16 v[64:67], v[156:159], v[216:219], v[64:67]
	s_barrier
	s_setprio 0
	s_add_i32 m0, s31, 0xc000
	s_nop 0
	global_load_lds_dwordx4 v172, s[24:25]
	s_add_i32 m0, s31, 0xe000
	s_nop 0
	global_load_lds_dwordx4 v174, s[24:25]
	s_add_i32 s49, s40, s30
	v_lshl_add_u64 v[220:221], s[14:15], 0, v[166:167]
	s_mov_b32 m0, s49
	ds_read_b128 v[160:163], v203 offset:16384
	ds_read_b128 v[182:185], v203 offset:17408
	ds_read_b128 v[186:189], v203 offset:18432
	ds_read_b128 v[190:193], v203 offset:19456
	ds_read_b128 v[204:207], v203 offset:20480
	ds_read_b128 v[208:211], v203 offset:21504
	ds_read_b128 v[212:215], v203 offset:22528
	ds_read_b128 v[216:219], v203 offset:23552
	global_load_lds_dwordx4 v[220:221], off
	s_add_i32 m0, s49, 0x2000
	s_add_u32 s50, s14, 0x160000
	v_lshl_add_u64 v[222:223], s[14:15], 0, v[170:171]
	s_addc_u32 s51, s15, 0
	s_add_i32 s49, s41, s30
	global_load_lds_dwordx4 v[222:223], off
	s_mov_b32 m0, s49
	v_lshl_add_u64 v[226:227], s[26:27], 0, v[168:169]
	global_load_lds_dwordx4 v166, s[50:51]
	s_add_i32 m0, s49, 0x2000
	s_nop 0
	global_load_lds_dwordx4 v170, s[50:51]
	v_lshl_add_u64 v[224:225], s[26:27], 0, v[164:165]
	s_mov_b32 m0, s31
	s_nop 0
	global_load_lds_dwordx4 v[224:225], off
	s_mov_b32 m0, s33
	s_nop 0
	global_load_lds_dwordx4 v[226:227], off
	s_waitcnt vmcnt(8)
	s_waitcnt lgkmcnt(0)
	s_setprio 1
	s_barrier
	v_mfma_f32_16x16x32_bf16 v[60:63], v[128:131], v[160:163], 0
	v_mfma_f32_16x16x32_bf16 v[60:63], v[132:135], v[182:185], v[60:63]
	v_mfma_f32_16x16x32_bf16 v[48:51], v[128:131], v[186:189], 0
	v_mfma_f32_16x16x32_bf16 v[48:51], v[132:135], v[190:193], v[48:51]
	v_mfma_f32_16x16x32_bf16 v[32:35], v[128:131], v[204:207], 0
	v_mfma_f32_16x16x32_bf16 v[32:35], v[132:135], v[208:211], v[32:35]
	v_mfma_f32_16x16x32_bf16 v[16:19], v[128:131], v[212:215], 0
	v_mfma_f32_16x16x32_bf16 v[16:19], v[132:135], v[216:219], v[16:19]
	v_mfma_f32_16x16x32_bf16 v[56:59], v[136:139], v[160:163], 0
	v_mfma_f32_16x16x32_bf16 v[56:59], v[140:143], v[182:185], v[56:59]
	v_mfma_f32_16x16x32_bf16 v[40:43], v[136:139], v[186:189], 0
	v_mfma_f32_16x16x32_bf16 v[40:43], v[140:143], v[190:193], v[40:43]
	v_mfma_f32_16x16x32_bf16 v[24:27], v[136:139], v[204:207], 0
	v_mfma_f32_16x16x32_bf16 v[24:27], v[140:143], v[208:211], v[24:27]
	v_mfma_f32_16x16x32_bf16 v[8:11], v[136:139], v[212:215], 0
	v_mfma_f32_16x16x32_bf16 v[8:11], v[140:143], v[216:219], v[8:11]
	s_setprio 0
	s_setprio 1
	v_mfma_f32_16x16x32_bf16 v[52:55], v[144:147], v[160:163], 0
	v_mfma_f32_16x16x32_bf16 v[52:55], v[148:151], v[182:185], v[52:55]
	v_mfma_f32_16x16x32_bf16 v[36:39], v[144:147], v[186:189], 0
	v_mfma_f32_16x16x32_bf16 v[36:39], v[148:151], v[190:193], v[36:39]
	v_mfma_f32_16x16x32_bf16 v[20:23], v[144:147], v[204:207], 0
	v_mfma_f32_16x16x32_bf16 v[20:23], v[148:151], v[208:211], v[20:23]
	v_mfma_f32_16x16x32_bf16 v[4:7], v[144:147], v[212:215], 0
	v_mfma_f32_16x16x32_bf16 v[4:7], v[148:151], v[216:219], v[4:7]
	v_mfma_f32_16x16x32_bf16 v[44:47], v[152:155], v[160:163], 0
	v_mfma_f32_16x16x32_bf16 v[44:47], v[156:159], v[182:185], v[44:47]
	v_mfma_f32_16x16x32_bf16 v[28:31], v[152:155], v[186:189], 0
	v_mfma_f32_16x16x32_bf16 v[28:31], v[156:159], v[190:193], v[28:31]
	v_mfma_f32_16x16x32_bf16 v[12:15], v[152:155], v[204:207], 0
	v_mfma_f32_16x16x32_bf16 v[12:15], v[156:159], v[208:211], v[12:15]
	v_mfma_f32_16x16x32_bf16 v[0:3], v[152:155], v[212:215], 0
	v_mfma_f32_16x16x32_bf16 v[0:3], v[156:159], v[216:219], v[0:3]
	s_barrier
; #define PG8_STAGE(bufoff, gbase, voff) do { _Pragma("unroll") for (int _i = 0; _i < 2; ++_i) \
;         __builtin_amdgcn_global_load_lds((const unsigned*)((const char*)(gbase) + (voff)[_i]), (PG8_LAS unsigned*)(lds + (bufoff) + ldsw + _i * 8192), 16, 0, 0); } while (0)
; #define PG8_LDA(dst, b, h) do { _Pragma("unroll") for (int m = 0; m < 4; ++m) _Pragma("unroll") for (int k = 0; k < 2; ++k) dst[m][k] = *(const PG8_LAS bf16x8*)(lds + PG8_SA(b, h) + aoff + m * 2048 + k * 1024); } while (0)
; #define PG8_LDB(dst, b, h) do { _Pragma("unroll") for (int n = 0; n < 2; ++n) _Pragma("unroll") for (int k = 0; k < 2; ++k) dst[n][k] = *(const PG8_LAS bf16x8*)(lds + PG8_SB(b, h) + boff + n * 2048 + k * 1024); } while (0)
; #define PG8_MMA(ai, bj, At, Bt) do { __builtin_amdgcn_s_setprio(1); _Pragma("unroll") for (int m = 0; m < 4; ++m) _Pragma("unroll") for (int n = 0; n < 2; ++n) _Pragma("unroll") for (int k = 0; k < 2; ++k) \
;         acc[ai][bj][m][n] = __builtin_amdgcn_mfma_f32_16x16x32_bf16(Bt[n][k], At[m][k], acc[ai][bj][m][n], 0, 0, 0); __builtin_amdgcn_s_setprio(0); } while (0)
; #define PG8_WAIT_V(n) asm volatile("s_waitcnt vmcnt(" #n ")" ::: "memory")
; #define PG8_WAIT_L(n) asm volatile("s_waitcnt lgkmcnt(" #n ")" ::: "memory")
; #define PG8_BAR __builtin_amdgcn_s_barrier()
; #define PG8_SCHED __builtin_amdgcn_sched_barrier(0)
; template <class Epi, class Sched, bool ALIGN_EPI = false, bool SP2 = false, bool DUAL = false>
; __device__ __forceinline__ void gemm_phase(PG8_LAS unsigned char* lds, const Gemm g, const Sched& S, const Epi& E) {
;     ...
;             PG8_WAIT_V(8); PG8_WAIT_L(0); PG8_BAR; PG8_MMA(1, 0, At, B0); PG8_MMA(1, 1, At, B1); PG8_BAR; PG8_SCHED;
;             PG8_LDB(B0, 1, 0); PG8_LDB(B1, 1, 1); PG8_SCHED; PG8_LDA(At, 1, 0); PG8_STAGE(PG8_SA(0, 1), a2 + hstep, voffA);
;             PG8_WAIT_V(8); PG8_WAIT_L(0); PG8_BAR; PG8_MMA(0, 0, At, B0); PG8_MMA(0, 1, At, B1); PG8_BAR; PG8_SCHED;
;             PG8_LDA(At, 1, 1); PG8_STAGE(PG8_SB(1, 0), b3, voffB); PG8_STAGE(PG8_SB(1, 1), b3 + hstep, voffB); PG8_STAGE(PG8_SA(1, 0), a3, voffA);
;             PG8_WAIT_V(8); PG8_WAIT_L(0); PG8_BAR; PG8_MMA(1, 0, At, B0); PG8_MMA(1, 1, At, B1); PG8_BAR; PG8_SCHED;
	s_setprio 0
	s_add_i32 s49, 0, 0x18000
	s_add_i32 s50, 0, 0x1c000
	v_add_u32_e32 v140, s49, v198
	v_add_u32_e32 v156, s50, v198
	ds_read_b128 v[128:131], v140
	ds_read_b128 v[132:135], v140 offset:1024
	ds_read_b128 v[136:139], v140 offset:2048
	ds_read_b128 v[140:143], v140 offset:3072
	ds_read_b128 v[144:147], v156
	ds_read_b128 v[148:151], v156 offset:1024
	ds_read_b128 v[152:155], v156 offset:2048
	ds_read_b128 v[156:159], v156 offset:3072
	s_add_u32 s26, s26, 0x160000
	s_addc_u32 s27, s27, 0
	s_mov_b32 m0, s34
	ds_read_b128 v[160:163], v203 offset:32768
	ds_read_b128 v[182:185], v203 offset:33792
	ds_read_b128 v[186:189], v203 offset:34816
	ds_read_b128 v[190:193], v203 offset:35840
	ds_read_b128 v[204:207], v203 offset:36864
	ds_read_b128 v[208:211], v203 offset:37888
	ds_read_b128 v[212:215], v203 offset:38912
	ds_read_b128 v[216:219], v203 offset:39936
	global_load_lds_dwordx4 v164, s[26:27]
	s_mov_b32 m0, s35
	s_nop 0
	global_load_lds_dwordx4 v168, s[26:27]
	s_waitcnt vmcnt(8)
	s_waitcnt lgkmcnt(0)
	s_setprio 1
	s_barrier
	v_mfma_f32_16x16x32_bf16 v[124:127], v[128:131], v[160:163], v[124:127]
	v_mfma_f32_16x16x32_bf16 v[124:127], v[132:135], v[182:185], v[124:127]
	v_mfma_f32_16x16x32_bf16 v[112:115], v[128:131], v[186:189], v[112:115]
	v_mfma_f32_16x16x32_bf16 v[112:115], v[132:135], v[190:193], v[112:115]
	v_mfma_f32_16x16x32_bf16 v[96:99], v[128:131], v[204:207], v[96:99]
	v_mfma_f32_16x16x32_bf16 v[96:99], v[132:135], v[208:211], v[96:99]
	v_mfma_f32_16x16x32_bf16 v[80:83], v[128:131], v[212:215], v[80:83]
	v_mfma_f32_16x16x32_bf16 v[80:83], v[132:135], v[216:219], v[80:83]
	v_mfma_f32_16x16x32_bf16 v[120:123], v[136:139], v[160:163], v[120:123]
	v_mfma_f32_16x16x32_bf16 v[120:123], v[140:143], v[182:185], v[120:123]
	v_mfma_f32_16x16x32_bf16 v[104:107], v[136:139], v[186:189], v[104:107]
	v_mfma_f32_16x16x32_bf16 v[104:107], v[140:143], v[190:193], v[104:107]
	v_mfma_f32_16x16x32_bf16 v[88:91], v[136:139], v[204:207], v[88:91]
	v_mfma_f32_16x16x32_bf16 v[88:91], v[140:143], v[208:211], v[88:91]
	v_mfma_f32_16x16x32_bf16 v[72:75], v[136:139], v[212:215], v[72:75]
	v_mfma_f32_16x16x32_bf16 v[72:75], v[140:143], v[216:219], v[72:75]
	s_setprio 0
	s_setprio 1
	v_mfma_f32_16x16x32_bf16 v[116:119], v[144:147], v[160:163], v[116:119]
	v_mfma_f32_16x16x32_bf16 v[116:119], v[148:151], v[182:185], v[116:119]
	v_mfma_f32_16x16x32_bf16 v[100:103], v[144:147], v[186:189], v[100:103]
	v_mfma_f32_16x16x32_bf16 v[100:103], v[148:151], v[190:193], v[100:103]
	v_mfma_f32_16x16x32_bf16 v[84:87], v[144:147], v[204:207], v[84:87]
	v_mfma_f32_16x16x32_bf16 v[84:87], v[148:151], v[208:211], v[84:87]
	v_mfma_f32_16x16x32_bf16 v[68:71], v[144:147], v[212:215], v[68:71]
	v_mfma_f32_16x16x32_bf16 v[68:71], v[148:151], v[216:219], v[68:71]
	v_mfma_f32_16x16x32_bf16 v[108:111], v[152:155], v[160:163], v[108:111]
	v_mfma_f32_16x16x32_bf16 v[108:111], v[156:159], v[182:185], v[108:111]
	v_mfma_f32_16x16x32_bf16 v[92:95], v[152:155], v[186:189], v[92:95]
	v_mfma_f32_16x16x32_bf16 v[92:95], v[156:159], v[190:193], v[92:95]
	v_mfma_f32_16x16x32_bf16 v[76:79], v[152:155], v[204:207], v[76:79]
	v_mfma_f32_16x16x32_bf16 v[76:79], v[156:159], v[208:211], v[76:79]
	v_mfma_f32_16x16x32_bf16 v[64:67], v[152:155], v[212:215], v[64:67]
	v_mfma_f32_16x16x32_bf16 v[64:67], v[156:159], v[216:219], v[64:67]
	s_barrier
	s_setprio 0
	s_add_i32 s26, s49, s30
	v_lshl_add_u64 v[220:221], v[220:221], 0, s[18:19]
	s_mov_b32 m0, s26
	ds_read_b128 v[160:163], v203 offset:49152
	ds_read_b128 v[182:185], v203 offset:50176
	ds_read_b128 v[186:189], v203 offset:51200
	ds_read_b128 v[190:193], v203 offset:52224
	ds_read_b128 v[204:207], v203 offset:53248
	ds_read_b128 v[208:211], v203 offset:54272
	ds_read_b128 v[212:215], v203 offset:55296
	ds_read_b128 v[216:219], v203 offset:56320
	global_load_lds_dwordx4 v[220:221], off
	s_add_i32 m0, s26, 0x2000
	s_add_u32 s14, s14, 0x160080
	v_lshl_add_u64 v[220:221], v[222:223], 0, s[18:19]
	s_addc_u32 s15, s15, 0
	s_add_i32 s26, s50, s30
	global_load_lds_dwordx4 v[220:221], off
	s_mov_b32 m0, s26
	s_nop 0
	global_load_lds_dwordx4 v166, s[14:15]
	s_add_i32 m0, s26, 0x2000
	s_nop 0
	global_load_lds_dwordx4 v170, s[14:15]
	v_lshl_add_u64 v[220:221], v[224:225], 0, s[18:19]
	s_mov_b32 m0, s37
	s_nop 0
	global_load_lds_dwordx4 v[220:221], off
	v_lshl_add_u64 v[220:221], v[226:227], 0, s[18:19]
	s_mov_b32 m0, s38
	s_nop 0
	global_load_lds_dwordx4 v[220:221], off
	s_waitcnt vmcnt(8)
	s_waitcnt lgkmcnt(0)
	s_setprio 1
	s_barrier
	v_mfma_f32_16x16x32_bf16 v[60:63], v[128:131], v[160:163], v[60:63]
	v_mfma_f32_16x16x32_bf16 v[60:63], v[132:135], v[182:185], v[60:63]
	v_mfma_f32_16x16x32_bf16 v[48:51], v[128:131], v[186:189], v[48:51]
	v_mfma_f32_16x16x32_bf16 v[48:51], v[132:135], v[190:193], v[48:51]
	v_mfma_f32_16x16x32_bf16 v[32:35], v[128:131], v[204:207], v[32:35]
	v_mfma_f32_16x16x32_bf16 v[32:35], v[132:135], v[208:211], v[32:35]
	v_mfma_f32_16x16x32_bf16 v[16:19], v[128:131], v[212:215], v[16:19]
	v_mfma_f32_16x16x32_bf16 v[16:19], v[132:135], v[216:219], v[16:19]
	v_mfma_f32_16x16x32_bf16 v[56:59], v[136:139], v[160:163], v[56:59]
	v_mfma_f32_16x16x32_bf16 v[56:59], v[140:143], v[182:185], v[56:59]
	v_mfma_f32_16x16x32_bf16 v[40:43], v[136:139], v[186:189], v[40:43]
	v_mfma_f32_16x16x32_bf16 v[40:43], v[140:143], v[190:193], v[40:43]
	v_mfma_f32_16x16x32_bf16 v[24:27], v[136:139], v[204:207], v[24:27]
	v_mfma_f32_16x16x32_bf16 v[24:27], v[140:143], v[208:211], v[24:27]
	v_mfma_f32_16x16x32_bf16 v[8:11], v[136:139], v[212:215], v[8:11]
	v_mfma_f32_16x16x32_bf16 v[8:11], v[140:143], v[216:219], v[8:11]
	s_setprio 0
	s_setprio 1
	v_mfma_f32_16x16x32_bf16 v[52:55], v[144:147], v[160:163], v[52:55]
	v_mfma_f32_16x16x32_bf16 v[52:55], v[148:151], v[182:185], v[52:55]
	v_mfma_f32_16x16x32_bf16 v[36:39], v[144:147], v[186:189], v[36:39]
	v_mfma_f32_16x16x32_bf16 v[36:39], v[148:151], v[190:193], v[36:39]
	v_mfma_f32_16x16x32_bf16 v[20:23], v[144:147], v[204:207], v[20:23]
	v_mfma_f32_16x16x32_bf16 v[20:23], v[148:151], v[208:211], v[20:23]
	v_mfma_f32_16x16x32_bf16 v[4:7], v[144:147], v[212:215], v[4:7]
	v_mfma_f32_16x16x32_bf16 v[4:7], v[148:151], v[216:219], v[4:7]
	v_mfma_f32_16x16x32_bf16 v[44:47], v[152:155], v[160:163], v[44:47]
	v_mfma_f32_16x16x32_bf16 v[44:47], v[156:159], v[182:185], v[44:47]
	v_mfma_f32_16x16x32_bf16 v[28:31], v[152:155], v[186:189], v[28:31]
	v_mfma_f32_16x16x32_bf16 v[28:31], v[156:159], v[190:193], v[28:31]
	v_mfma_f32_16x16x32_bf16 v[12:15], v[152:155], v[204:207], v[12:15]
	v_mfma_f32_16x16x32_bf16 v[12:15], v[156:159], v[208:211], v[12:15]
	v_mfma_f32_16x16x32_bf16 v[0:3], v[152:155], v[212:215], v[0:3]
	v_mfma_f32_16x16x32_bf16 v[0:3], v[156:159], v[216:219], v[0:3]
	s_barrier
	s_setprio 0
	s_add_i32 s48, s48, 2
	s_add_u32 s24, s24, 0x100
	s_addc_u32 s25, s25, 0
	s_add_u32 s46, s46, 0x100
	s_addc_u32 s47, s47, 0
; #define PG8_STAGE(bufoff, gbase, voff) do { _Pragma("unroll") for (int _i = 0; _i < 2; ++_i) \
;         __builtin_amdgcn_global_load_lds((const unsigned*)((const char*)(gbase) + (voff)[_i]), (PG8_LAS unsigned*)(lds + (bufoff) + ldsw + _i * 8192), 16, 0, 0); } while (0)
; #define PG8_LDA(dst, b, h) do { _Pragma("unroll") for (int m = 0; m < 4; ++m) _Pragma("unroll") for (int k = 0; k < 2; ++k) dst[m][k] = *(const PG8_LAS bf16x8*)(lds + PG8_SA(b, h) + aoff + m * 2048 + k * 1024); } while (0)
; #define PG8_LDB(dst, b, h) do { _Pragma("unroll") for (int n = 0; n < 2; ++n) _Pragma("unroll") for (int k = 0; k < 2; ++k) dst[n][k] = *(const PG8_LAS bf16x8*)(lds + PG8_SB(b, h) + boff + n * 2048 + k * 1024); } while (0)
; #define PG8_MMA(ai, bj, At, Bt) do { __builtin_amdgcn_s_setprio(1); _Pragma("unroll") for (int m = 0; m < 4; ++m) _Pragma("unroll") for (int n = 0; n < 2; ++n) _Pragma("unroll") for (int k = 0; k < 2; ++k) \
;         acc[ai][bj][m][n] = __builtin_amdgcn_mfma_f32_16x16x32_bf16(Bt[n][k], At[m][k], acc[ai][bj][m][n], 0, 0, 0); __builtin_amdgcn_s_setprio(0); } while (0)
; #define PG8_WAIT_V(n) asm volatile("s_waitcnt vmcnt(" #n ")" ::: "memory")
; #define PG8_BAR __builtin_amdgcn_s_barrier()
; template <class Epi, class Sched, bool ALIGN_EPI = false, bool SP2 = false, bool DUAL = false>
; __device__ __forceinline__ void gemm_phase(PG8_LAS unsigned char* lds, const Gemm g, const Sched& S, const Epi& E) {
;     ...
;         for (int t = 0; t < nt; t += 2) {
;             const bool last = (t == nt - 2);
;             const char* a1 = cA + (size_t)(t + 1) * kstep;
;             const char* a2 = last ? nA : cA + (size_t)(t + 2) * kstep; const char* b2 = last ? nB : cB + (size_t)(t + 2) * kstep;
;             const char* a3 = a2 + kstep; const char* b3 = b2 + kstep;
;             if (last && has_next) S.a_ready(nxt);
;             if constexpr (SP2) {
;             PG8_LDB(B0, 0, 0); PG8_LDB(B1, 0, 1); PG8_SCHED; PG8_LDA(At, 0, 0); PG8_STAGE(PG8_SA(1, 1), a1 + hstep, voffA);
;             PG8_WAIT_V(8); PG8_WAIT_L(0); PG8_BAR; PG8_MMA(0, 0, At, B0); PG8_MMA(0, 1, At, B1); PG8_BAR; PG8_SCHED;
;             PG8_LDA(At, 0, 1); PG8_STAGE(PG8_SB(0, 0), b2, voffB); PG8_STAGE(PG8_SB(0, 1), b2 + hstep, voffB); PG8_STAGE(PG8_SA(0, 0), a2, voffA);
;             PG8_WAIT_V(8); PG8_WAIT_L(0); PG8_BAR; PG8_MMA(1, 0, At, B0); PG8_MMA(1, 1, At, B1); PG8_BAR; PG8_SCHED;
.LBB0_1193:
	ds_read_b128 v[128:131], v201
	ds_read_b128 v[132:135], v201 offset:1024
	ds_read_b128 v[136:139], v201 offset:2048
	ds_read_b128 v[140:143], v201 offset:3072
	ds_read_b128 v[144:147], v202
	ds_read_b128 v[148:151], v202 offset:1024
	ds_read_b128 v[152:155], v202 offset:2048
	ds_read_b128 v[156:159], v202 offset:3072
	s_add_u32 s14, s24, 0xffea0080
	s_addc_u32 s15, s25, -1
	s_cmpk_eq_i32 s48, 0x54
	s_cselect_b32 s27, s5, s15
	s_cselect_b32 s26, s4, s14
	s_cselect_b32 s15, s23, s47
	s_cselect_b32 s14, s22, s46
	s_add_i32 m0, s31, 0xc000
	ds_read_b128 v[160:163], v203
	ds_read_b128 v[182:185], v203 offset:1024
	ds_read_b128 v[186:189], v203 offset:2048
	ds_read_b128 v[190:193], v203 offset:3072
	ds_read_b128 v[204:207], v203 offset:4096
	ds_read_b128 v[208:211], v203 offset:5120
	ds_read_b128 v[212:215], v203 offset:6144
	ds_read_b128 v[216:219], v203 offset:7168
	global_load_lds_dwordx4 v172, s[24:25]
	s_add_i32 m0, s31, 0xe000
	s_nop 0
	global_load_lds_dwordx4 v174, s[24:25]
	s_waitcnt vmcnt(8)
	s_waitcnt lgkmcnt(0)
	s_setprio 1
	s_barrier
	v_mfma_f32_16x16x32_bf16 v[124:127], v[128:131], v[160:163], v[124:127]
	v_mfma_f32_16x16x32_bf16 v[124:127], v[132:135], v[182:185], v[124:127]
	v_mfma_f32_16x16x32_bf16 v[112:115], v[128:131], v[186:189], v[112:115]
	v_mfma_f32_16x16x32_bf16 v[112:115], v[132:135], v[190:193], v[112:115]
	v_mfma_f32_16x16x32_bf16 v[96:99], v[128:131], v[204:207], v[96:99]
	v_mfma_f32_16x16x32_bf16 v[96:99], v[132:135], v[208:211], v[96:99]
	v_mfma_f32_16x16x32_bf16 v[80:83], v[128:131], v[212:215], v[80:83]
	v_mfma_f32_16x16x32_bf16 v[80:83], v[132:135], v[216:219], v[80:83]
	v_mfma_f32_16x16x32_bf16 v[120:123], v[136:139], v[160:163], v[120:123]
	v_mfma_f32_16x16x32_bf16 v[120:123], v[140:143], v[182:185], v[120:123]
	v_mfma_f32_16x16x32_bf16 v[104:107], v[136:139], v[186:189], v[104:107]
	v_mfma_f32_16x16x32_bf16 v[104:107], v[140:143], v[190:193], v[104:107]
	v_mfma_f32_16x16x32_bf16 v[88:91], v[136:139], v[204:207], v[88:91]
	v_mfma_f32_16x16x32_bf16 v[88:91], v[140:143], v[208:211], v[88:91]
	v_mfma_f32_16x16x32_bf16 v[72:75], v[136:139], v[212:215], v[72:75]
	v_mfma_f32_16x16x32_bf16 v[72:75], v[140:143], v[216:219], v[72:75]
	s_setprio 0
	s_setprio 1
	v_mfma_f32_16x16x32_bf16 v[116:119], v[144:147], v[160:163], v[116:119]
	v_mfma_f32_16x16x32_bf16 v[116:119], v[148:151], v[182:185], v[116:119]
	v_mfma_f32_16x16x32_bf16 v[100:103], v[144:147], v[186:189], v[100:103]
	v_mfma_f32_16x16x32_bf16 v[100:103], v[148:151], v[190:193], v[100:103]
	v_mfma_f32_16x16x32_bf16 v[84:87], v[144:147], v[204:207], v[84:87]
	v_mfma_f32_16x16x32_bf16 v[84:87], v[148:151], v[208:211], v[84:87]
	v_mfma_f32_16x16x32_bf16 v[68:71], v[144:147], v[212:215], v[68:71]
	v_mfma_f32_16x16x32_bf16 v[68:71], v[148:151], v[216:219], v[68:71]
	v_mfma_f32_16x16x32_bf16 v[108:111], v[152:155], v[160:163], v[108:111]
	v_mfma_f32_16x16x32_bf16 v[108:111], v[156:159], v[182:185], v[108:111]
	v_mfma_f32_16x16x32_bf16 v[92:95], v[152:155], v[186:189], v[92:95]
	v_mfma_f32_16x16x32_bf16 v[92:95], v[156:159], v[190:193], v[92:95]
	v_mfma_f32_16x16x32_bf16 v[76:79], v[152:155], v[204:207], v[76:79]
	v_mfma_f32_16x16x32_bf16 v[76:79], v[156:159], v[208:211], v[76:79]
	v_mfma_f32_16x16x32_bf16 v[64:67], v[152:155], v[212:215], v[64:67]
	v_mfma_f32_16x16x32_bf16 v[64:67], v[156:159], v[216:219], v[64:67]
	s_barrier
	s_setprio 0
	s_add_i32 s49, s40, s30
	v_lshl_add_u64 v[220:221], s[14:15], 0, v[166:167]
	s_mov_b32 m0, s49
	ds_read_b128 v[160:163], v203 offset:16384
	ds_read_b128 v[182:185], v203 offset:17408
	ds_read_b128 v[186:189], v203 offset:18432
	ds_read_b128 v[190:193], v203 offset:19456
	ds_read_b128 v[204:207], v203 offset:20480
	ds_read_b128 v[208:211], v203 offset:21504
	ds_read_b128 v[212:215], v203 offset:22528
	ds_read_b128 v[216:219], v203 offset:23552
	global_load_lds_dwordx4 v[220:221], off
	s_add_i32 m0, s49, 0x2000
	s_add_u32 s50, s14, 0x160000
	v_lshl_add_u64 v[222:223], s[14:15], 0, v[170:171]
	s_addc_u32 s51, s15, 0
	s_add_i32 s49, s41, s30
	global_load_lds_dwordx4 v[222:223], off
	s_mov_b32 m0, s49
	v_lshl_add_u64 v[226:227], s[26:27], 0, v[168:169]
	global_load_lds_dwordx4 v166, s[50:51]
	s_add_i32 m0, s49, 0x2000
	s_nop 0
	global_load_lds_dwordx4 v170, s[50:51]
	v_lshl_add_u64 v[224:225], s[26:27], 0, v[164:165]
	s_mov_b32 m0, s31
	s_nop 0
	global_load_lds_dwordx4 v[224:225], off
	s_mov_b32 m0, s33
	s_nop 0
	global_load_lds_dwordx4 v[226:227], off
	s_waitcnt vmcnt(8)
	s_waitcnt lgkmcnt(0)
	s_setprio 1
	s_barrier
	v_mfma_f32_16x16x32_bf16 v[60:63], v[128:131], v[160:163], v[60:63]
	v_mfma_f32_16x16x32_bf16 v[60:63], v[132:135], v[182:185], v[60:63]
	v_mfma_f32_16x16x32_bf16 v[48:51], v[128:131], v[186:189], v[48:51]
	v_mfma_f32_16x16x32_bf16 v[48:51], v[132:135], v[190:193], v[48:51]
	v_mfma_f32_16x16x32_bf16 v[32:35], v[128:131], v[204:207], v[32:35]
	v_mfma_f32_16x16x32_bf16 v[32:35], v[132:135], v[208:211], v[32:35]
	v_mfma_f32_16x16x32_bf16 v[16:19], v[128:131], v[212:215], v[16:19]
	v_mfma_f32_16x16x32_bf16 v[16:19], v[132:135], v[216:219], v[16:19]
	v_mfma_f32_16x16x32_bf16 v[56:59], v[136:139], v[160:163], v[56:59]
	v_mfma_f32_16x16x32_bf16 v[56:59], v[140:143], v[182:185], v[56:59]
	v_mfma_f32_16x16x32_bf16 v[40:43], v[136:139], v[186:189], v[40:43]
	v_mfma_f32_16x16x32_bf16 v[40:43], v[140:143], v[190:193], v[40:43]
	v_mfma_f32_16x16x32_bf16 v[24:27], v[136:139], v[204:207], v[24:27]
	v_mfma_f32_16x16x32_bf16 v[24:27], v[140:143], v[208:211], v[24:27]
	v_mfma_f32_16x16x32_bf16 v[8:11], v[136:139], v[212:215], v[8:11]
	v_mfma_f32_16x16x32_bf16 v[8:11], v[140:143], v[216:219], v[8:11]
	s_setprio 0
	s_setprio 1
	v_mfma_f32_16x16x32_bf16 v[52:55], v[144:147], v[160:163], v[52:55]
	v_mfma_f32_16x16x32_bf16 v[52:55], v[148:151], v[182:185], v[52:55]
	v_mfma_f32_16x16x32_bf16 v[36:39], v[144:147], v[186:189], v[36:39]
	v_mfma_f32_16x16x32_bf16 v[36:39], v[148:151], v[190:193], v[36:39]
	v_mfma_f32_16x16x32_bf16 v[20:23], v[144:147], v[204:207], v[20:23]
	v_mfma_f32_16x16x32_bf16 v[20:23], v[148:151], v[208:211], v[20:23]
	v_mfma_f32_16x16x32_bf16 v[4:7], v[144:147], v[212:215], v[4:7]
	v_mfma_f32_16x16x32_bf16 v[4:7], v[148:151], v[216:219], v[4:7]
	v_mfma_f32_16x16x32_bf16 v[44:47], v[152:155], v[160:163], v[44:47]
	v_mfma_f32_16x16x32_bf16 v[44:47], v[156:159], v[182:185], v[44:47]
	v_mfma_f32_16x16x32_bf16 v[28:31], v[152:155], v[186:189], v[28:31]
	v_mfma_f32_16x16x32_bf16 v[28:31], v[156:159], v[190:193], v[28:31]
	v_mfma_f32_16x16x32_bf16 v[12:15], v[152:155], v[204:207], v[12:15]
	v_mfma_f32_16x16x32_bf16 v[12:15], v[156:159], v[208:211], v[12:15]
	v_mfma_f32_16x16x32_bf16 v[0:3], v[152:155], v[212:215], v[0:3]
	v_mfma_f32_16x16x32_bf16 v[0:3], v[156:159], v[216:219], v[0:3]
	s_barrier
; #define PG8_STAGE(bufoff, gbase, voff) do { _Pragma("unroll") for (int _i = 0; _i < 2; ++_i) \
;         __builtin_amdgcn_global_load_lds((const unsigned*)((const char*)(gbase) + (voff)[_i]), (PG8_LAS unsigned*)(lds + (bufoff) + ldsw + _i * 8192), 16, 0, 0); } while (0)
; #define PG8_LDA(dst, b, h) do { _Pragma("unroll") for (int m = 0; m < 4; ++m) _Pragma("unroll") for (int k = 0; k < 2; ++k) dst[m][k] = *(const PG8_LAS bf16x8*)(lds + PG8_SA(b, h) + aoff + m * 2048 + k * 1024); } while (0)
; #define PG8_LDB(dst, b, h) do { _Pragma("unroll") for (int n = 0; n < 2; ++n) _Pragma("unroll") for (int k = 0; k < 2; ++k) dst[n][k] = *(const PG8_LAS bf16x8*)(lds + PG8_SB(b, h) + boff + n * 2048 + k * 1024); } while (0)
; #define PG8_MMA(ai, bj, At, Bt) do { __builtin_amdgcn_s_setprio(1); _Pragma("unroll") for (int m = 0; m < 4; ++m) _Pragma("unroll") for (int n = 0; n < 2; ++n) _Pragma("unroll") for (int k = 0; k < 2; ++k) \
;         acc[ai][bj][m][n] = __builtin_amdgcn_mfma_f32_16x16x32_bf16(Bt[n][k], At[m][k], acc[ai][bj][m][n], 0, 0, 0); __builtin_amdgcn_s_setprio(0); } while (0)
; #define PG8_WAIT_V(n) asm volatile("s_waitcnt vmcnt(" #n ")" ::: "memory")
; #define PG8_WAIT_L(n) asm volatile("s_waitcnt lgkmcnt(" #n ")" ::: "memory")
; #define PG8_BAR __builtin_amdgcn_s_barrier()
; #define PG8_SCHED __builtin_amdgcn_sched_barrier(0)
; template <class Epi, class Sched, bool ALIGN_EPI = false, bool SP2 = false, bool DUAL = false>
; __device__ __forceinline__ void gemm_phase(PG8_LAS unsigned char* lds, const Gemm g, const Sched& S, const Epi& E) {
;     ...
;             PG8_LDB(B0, 1, 0); PG8_LDB(B1, 1, 1); PG8_SCHED; PG8_LDA(At, 1, 0); PG8_STAGE(PG8_SA(0, 1), a2 + hstep, voffA);
;             PG8_WAIT_V(8); PG8_WAIT_L(0); PG8_BAR; PG8_MMA(0, 0, At, B0); PG8_MMA(0, 1, At, B1); PG8_BAR; PG8_SCHED;
;             PG8_LDA(At, 1, 1); PG8_STAGE(PG8_SB(1, 0), b3, voffB); PG8_STAGE(PG8_SB(1, 1), b3 + hstep, voffB); PG8_STAGE(PG8_SA(1, 0), a3, voffA);
;             PG8_WAIT_V(8); PG8_WAIT_L(0); PG8_BAR; PG8_MMA(1, 0, At, B0); PG8_MMA(1, 1, At, B1); PG8_BAR; PG8_SCHED;
;     ...
;         if constexpr (ALIGN_EPI) { if (wr == 0) PG8_BAR; }
	s_setprio 0
	s_add_i32 s49, 0, 0x18000
	s_add_i32 s50, 0, 0x1c000
	v_add_u32_e32 v140, s49, v198
	v_add_u32_e32 v156, s50, v198
	ds_read_b128 v[128:131], v140
	ds_read_b128 v[132:135], v140 offset:1024
	ds_read_b128 v[136:139], v140 offset:2048
	ds_read_b128 v[140:143], v140 offset:3072
	ds_read_b128 v[144:147], v156
	ds_read_b128 v[148:151], v156 offset:1024
	ds_read_b128 v[152:155], v156 offset:2048
	ds_read_b128 v[156:159], v156 offset:3072
	s_add_u32 s26, s26, 0x160000
	s_addc_u32 s27, s27, 0
	s_mov_b32 m0, s34
	ds_read_b128 v[160:163], v203 offset:32768
	ds_read_b128 v[182:185], v203 offset:33792
	ds_read_b128 v[186:189], v203 offset:34816
	ds_read_b128 v[190:193], v203 offset:35840
	ds_read_b128 v[204:207], v203 offset:36864
	ds_read_b128 v[208:211], v203 offset:37888
	ds_read_b128 v[212:215], v203 offset:38912
	ds_read_b128 v[216:219], v203 offset:39936
	global_load_lds_dwordx4 v164, s[26:27]
	s_mov_b32 m0, s35
	s_nop 0
	global_load_lds_dwordx4 v168, s[26:27]
	s_waitcnt vmcnt(8)
	s_waitcnt lgkmcnt(0)
	s_setprio 1
	s_barrier
	v_mfma_f32_16x16x32_bf16 v[124:127], v[128:131], v[160:163], v[124:127]
	v_mfma_f32_16x16x32_bf16 v[124:127], v[132:135], v[182:185], v[124:127]
	v_mfma_f32_16x16x32_bf16 v[112:115], v[128:131], v[186:189], v[112:115]
	v_mfma_f32_16x16x32_bf16 v[112:115], v[132:135], v[190:193], v[112:115]
	v_mfma_f32_16x16x32_bf16 v[96:99], v[128:131], v[204:207], v[96:99]
	v_mfma_f32_16x16x32_bf16 v[96:99], v[132:135], v[208:211], v[96:99]
	v_mfma_f32_16x16x32_bf16 v[80:83], v[128:131], v[212:215], v[80:83]
	v_mfma_f32_16x16x32_bf16 v[80:83], v[132:135], v[216:219], v[80:83]
	v_mfma_f32_16x16x32_bf16 v[120:123], v[136:139], v[160:163], v[120:123]
	v_mfma_f32_16x16x32_bf16 v[120:123], v[140:143], v[182:185], v[120:123]
	v_mfma_f32_16x16x32_bf16 v[104:107], v[136:139], v[186:189], v[104:107]
	v_mfma_f32_16x16x32_bf16 v[104:107], v[140:143], v[190:193], v[104:107]
	v_mfma_f32_16x16x32_bf16 v[88:91], v[136:139], v[204:207], v[88:91]
	v_mfma_f32_16x16x32_bf16 v[88:91], v[140:143], v[208:211], v[88:91]
	v_mfma_f32_16x16x32_bf16 v[72:75], v[136:139], v[212:215], v[72:75]
	v_mfma_f32_16x16x32_bf16 v[72:75], v[140:143], v[216:219], v[72:75]
	s_setprio 0
	s_setprio 1
	v_mfma_f32_16x16x32_bf16 v[116:119], v[144:147], v[160:163], v[116:119]
	v_mfma_f32_16x16x32_bf16 v[116:119], v[148:151], v[182:185], v[116:119]
	v_mfma_f32_16x16x32_bf16 v[100:103], v[144:147], v[186:189], v[100:103]
	v_mfma_f32_16x16x32_bf16 v[100:103], v[148:151], v[190:193], v[100:103]
	v_mfma_f32_16x16x32_bf16 v[84:87], v[144:147], v[204:207], v[84:87]
	v_mfma_f32_16x16x32_bf16 v[84:87], v[148:151], v[208:211], v[84:87]
	v_mfma_f32_16x16x32_bf16 v[68:71], v[144:147], v[212:215], v[68:71]
	v_mfma_f32_16x16x32_bf16 v[68:71], v[148:151], v[216:219], v[68:71]
	v_mfma_f32_16x16x32_bf16 v[108:111], v[152:155], v[160:163], v[108:111]
	v_mfma_f32_16x16x32_bf16 v[108:111], v[156:159], v[182:185], v[108:111]
	v_mfma_f32_16x16x32_bf16 v[92:95], v[152:155], v[186:189], v[92:95]
	v_mfma_f32_16x16x32_bf16 v[92:95], v[156:159], v[190:193], v[92:95]
	v_mfma_f32_16x16x32_bf16 v[76:79], v[152:155], v[204:207], v[76:79]
	v_mfma_f32_16x16x32_bf16 v[76:79], v[156:159], v[208:211], v[76:79]
	v_mfma_f32_16x16x32_bf16 v[64:67], v[152:155], v[212:215], v[64:67]
	v_mfma_f32_16x16x32_bf16 v[64:67], v[156:159], v[216:219], v[64:67]
	s_barrier
	s_setprio 0
	s_add_i32 s26, s49, s30
	v_lshl_add_u64 v[220:221], v[220:221], 0, s[18:19]
	s_mov_b32 m0, s26
	ds_read_b128 v[160:163], v203 offset:49152
	ds_read_b128 v[182:185], v203 offset:50176
	ds_read_b128 v[186:189], v203 offset:51200
	ds_read_b128 v[190:193], v203 offset:52224
	ds_read_b128 v[204:207], v203 offset:53248
	ds_read_b128 v[208:211], v203 offset:54272
	ds_read_b128 v[212:215], v203 offset:55296
	ds_read_b128 v[216:219], v203 offset:56320
	global_load_lds_dwordx4 v[220:221], off
	s_add_i32 m0, s26, 0x2000
	s_add_u32 s14, s14, 0x160080
	v_lshl_add_u64 v[220:221], v[222:223], 0, s[18:19]
	s_addc_u32 s15, s15, 0
	s_add_i32 s26, s50, s30
	global_load_lds_dwordx4 v[220:221], off
	s_mov_b32 m0, s26
	s_nop 0
	global_load_lds_dwordx4 v166, s[14:15]
	s_add_i32 m0, s26, 0x2000
	s_nop 0
	global_load_lds_dwordx4 v170, s[14:15]
	v_lshl_add_u64 v[220:221], v[224:225], 0, s[18:19]
	s_mov_b32 m0, s37
	s_nop 0
	global_load_lds_dwordx4 v[220:221], off
	v_lshl_add_u64 v[220:221], v[226:227], 0, s[18:19]
	s_mov_b32 m0, s38
	s_nop 0
	global_load_lds_dwordx4 v[220:221], off
	s_waitcnt vmcnt(8)
	s_waitcnt lgkmcnt(0)
	s_setprio 1
	s_barrier
	v_mfma_f32_16x16x32_bf16 v[60:63], v[128:131], v[160:163], v[60:63]
	v_mfma_f32_16x16x32_bf16 v[60:63], v[132:135], v[182:185], v[60:63]
	v_mfma_f32_16x16x32_bf16 v[48:51], v[128:131], v[186:189], v[48:51]
	v_mfma_f32_16x16x32_bf16 v[48:51], v[132:135], v[190:193], v[48:51]
	v_mfma_f32_16x16x32_bf16 v[32:35], v[128:131], v[204:207], v[32:35]
	v_mfma_f32_16x16x32_bf16 v[32:35], v[132:135], v[208:211], v[32:35]
	v_mfma_f32_16x16x32_bf16 v[16:19], v[128:131], v[212:215], v[16:19]
	v_mfma_f32_16x16x32_bf16 v[16:19], v[132:135], v[216:219], v[16:19]
	v_mfma_f32_16x16x32_bf16 v[56:59], v[136:139], v[160:163], v[56:59]
	v_mfma_f32_16x16x32_bf16 v[56:59], v[140:143], v[182:185], v[56:59]
	v_mfma_f32_16x16x32_bf16 v[40:43], v[136:139], v[186:189], v[40:43]
	v_mfma_f32_16x16x32_bf16 v[40:43], v[140:143], v[190:193], v[40:43]
	v_mfma_f32_16x16x32_bf16 v[24:27], v[136:139], v[204:207], v[24:27]
	v_mfma_f32_16x16x32_bf16 v[24:27], v[140:143], v[208:211], v[24:27]
	v_mfma_f32_16x16x32_bf16 v[8:11], v[136:139], v[212:215], v[8:11]
	v_mfma_f32_16x16x32_bf16 v[8:11], v[140:143], v[216:219], v[8:11]
	s_setprio 0
	s_setprio 1
	v_mfma_f32_16x16x32_bf16 v[52:55], v[144:147], v[160:163], v[52:55]
	v_mfma_f32_16x16x32_bf16 v[52:55], v[148:151], v[182:185], v[52:55]
	v_mfma_f32_16x16x32_bf16 v[36:39], v[144:147], v[186:189], v[36:39]
	v_mfma_f32_16x16x32_bf16 v[36:39], v[148:151], v[190:193], v[36:39]
	v_mfma_f32_16x16x32_bf16 v[20:23], v[144:147], v[204:207], v[20:23]
	v_mfma_f32_16x16x32_bf16 v[20:23], v[148:151], v[208:211], v[20:23]
	v_mfma_f32_16x16x32_bf16 v[4:7], v[144:147], v[212:215], v[4:7]
	v_mfma_f32_16x16x32_bf16 v[4:7], v[148:151], v[216:219], v[4:7]
	v_mfma_f32_16x16x32_bf16 v[44:47], v[152:155], v[160:163], v[44:47]
	v_mfma_f32_16x16x32_bf16 v[44:47], v[156:159], v[182:185], v[44:47]
	v_mfma_f32_16x16x32_bf16 v[28:31], v[152:155], v[186:189], v[28:31]
	v_mfma_f32_16x16x32_bf16 v[28:31], v[156:159], v[190:193], v[28:31]
	v_mfma_f32_16x16x32_bf16 v[12:15], v[152:155], v[204:207], v[12:15]
	v_mfma_f32_16x16x32_bf16 v[12:15], v[156:159], v[208:211], v[12:15]
	v_mfma_f32_16x16x32_bf16 v[0:3], v[152:155], v[212:215], v[0:3]
	v_mfma_f32_16x16x32_bf16 v[0:3], v[156:159], v[216:219], v[0:3]
	s_barrier
	s_setprio 0
	s_add_i32 s48, s48, 2
	s_add_u32 s24, s24, 0x100
	s_addc_u32 s25, s25, 0
	s_add_u32 s46, s46, 0x100
	s_addc_u32 s47, s47, 0
	s_cmpk_gt_u32 s48, 0x55
	s_cbranch_scc0 .LBB0_1193
	s_and_b64 vcc, exec, s[20:21]
	s_cbranch_vccz .LBB0_1196
	s_barrier
